# gates epilogue: n=0 / n=1 halves of log_a and b rows leave as one global_store_dwordx4 (16 stores per lane and tile instead of 32)
# speedup vs baseline: 1.0140x; 1.0016x over previous
; #define PG8_STAGE(bufoff, gbase, voff) do { _Pragma("unroll") for (int _i = 0; _i < 2; ++_i) \
;         __builtin_amdgcn_global_load_lds((const unsigned*)((const char*)(gbase) + (voff)[_i]), (LAS unsigned*)(lds + (bufoff) + ldsw + _i * 8192), 16, 0, 0); } while (0)
; #define PG8_LDA(dst, b, h) do { _Pragma("unroll") for (int m = 0; m < 4; ++m) _Pragma("unroll") for (int k = 0; k < 2; ++k) dst[m][k] = *(const LAS bf16x8*)(lds + PG8_SA(b, h) + aoff + m * 2048 + k * 1024); } while (0)
; #define PG8_LDB(dst, b, h) do { _Pragma("unroll") for (int n = 0; n < 2; ++n) _Pragma("unroll") for (int k = 0; k < 2; ++k) dst[n][k] = *(const LAS bf16x8*)(lds + PG8_SB(b, h) + boff + n * 2048 + k * 1024); } while (0)
; #define PG8_WAIT_V(n) asm volatile("s_waitcnt vmcnt(" #n ")" ::: "memory")
; #define PG8_WAIT_L(n) asm volatile("s_waitcnt lgkmcnt(" #n ")" ::: "memory")
; #define PG8_BAR __builtin_amdgcn_s_barrier()
; #define PG8_SCHED __builtin_amdgcn_sched_barrier(0)
; template <class Epi>
; __device__ __forceinline__ void gemm_phase(LAS unsigned char* lds, const Gemm g, const StaticOrder& S, const Epi& E) {
;     ...
;         const bool has_next = S.next(ui + 1, nxt);
;         const char* nA = has_next ? (const char*)g.A + (size_t)nxt.pm * tstepA + (size_t)(nxt.pn >> g.a_shift) * g.a_step : cA; const char* nB = has_next ? (const char*)g.Bt + (size_t)nxt.pn * tstepB : cB;
;         for (int t = 0; t < nt; t += 2) {
;             const bool last = (t == nt - 2);
;             const char* a1 = cA + (size_t)(t + 1) * kstep;
;             const char* a2 = last ? nA : cA + (size_t)(t + 2) * kstep; const char* b2 = last ? nB : cB + (size_t)(t + 2) * kstep;
;             const char* a3 = a2 + kstep; const char* b3 = b2 + kstep;
;             PG8_LDB(B0, 0, 0); PG8_SCHED; PG8_LDA(At, 0, 0); PG8_STAGE(PG8_SA(1, 1), a1 + hstepA, voffA);
;             PG8_WAIT_L(8); PG8_BAR; PG8_WAIT_L(0); PG8_MMA(0, 0, At, B0); PG8_BAR; PG8_SCHED;
;             PG8_LDB(B1, 0, 1); PG8_STAGE(PG8_SB(0, 0), b2, voffB);
;             PG8_BAR; PG8_WAIT_L(0); PG8_MMA(0, 1, At, B1); PG8_BAR;
;             PG8_LDA(At, 0, 1); PG8_STAGE(PG8_SA(0, 0), a2, voffA);
;             PG8_BAR; PG8_WAIT_L(0); PG8_MMA(1, 0, At, B0); PG8_BAR; PG8_SCHED;
;             PG8_STAGE(PG8_SB(0, 1), b2 + hstepB, voffB);
;             PG8_WAIT_V(6); PG8_BAR; PG8_MMA(1, 1, At, B1); PG8_BAR;
.LBB0_1094:
	s_ashr_i32 s41, s40, 31
	s_lshl_b64 s[42:43], s[40:41], 19
	s_add_u32 s39, s18, s42
	s_addc_u32 s41, s19, s43
	s_ashr_i32 s42, s38, 1
	s_ashr_i32 s43, s42, 31
	s_lshl_b64 s[42:43], s[42:43], 9
	s_add_u32 s42, s39, s42
	v_cmp_lt_i64_e32 vcc, s[36:37], v[176:177]
	s_addc_u32 s43, s41, s43
	ds_read_b128 v[0:3], v207
	ds_read_b128 v[4:7], v207 offset:1024
	ds_read_b128 v[8:11], v207 offset:2048
	ds_read_b128 v[12:15], v207 offset:3072
	s_and_b64 s[44:45], vcc, exec
	s_cselect_b32 s49, s43, s15
	s_cselect_b32 s48, s42, s14
	s_ashr_i32 s39, s38, 31
	s_lshl_b64 s[44:45], s[38:39], 17
	s_add_u32 s44, s5, s44
	s_addc_u32 s45, s6, s45
	s_and_b64 s[46:47], vcc, exec
	s_cselect_b32 s47, s45, s17
	s_cselect_b32 s46, s44, s16
	s_add_u32 s82, s14, 0x40080
	s_addc_u32 s83, s15, 0
	s_add_i32 s85, s8, 0xc000
	v_lshl_add_u64 v[48:49], s[82:83], 0, v[168:169]
	s_mov_b32 m0, s85
	s_add_i32 s39, s8, 0xe000
	ds_read_b128 v[16:19], v208
	ds_read_b128 v[20:23], v208 offset:1024
	ds_read_b128 v[24:27], v208 offset:2048
	ds_read_b128 v[28:31], v208 offset:3072
	ds_read_b128 v[32:35], v208 offset:4096
	ds_read_b128 v[36:39], v208 offset:5120
	ds_read_b128 v[40:43], v208 offset:6144
	ds_read_b128 v[44:47], v208 offset:7168
	global_load_lds_dwordx4 v[48:49], off
	v_lshl_add_u64 v[48:49], s[82:83], 0, v[172:173]
	s_mov_b32 m0, s39
	s_nop 0
	global_load_lds_dwordx4 v[48:49], off
	s_waitcnt lgkmcnt(8)
	s_barrier
	s_waitcnt lgkmcnt(0)
	s_setprio 1
	s_waitcnt lgkmcnt(0)
	v_mfma_f32_16x16x32_bf16 v[48:51], v[0:3], v[16:19], 0
	v_mfma_f32_16x16x32_bf16 v[52:55], v[8:11], v[16:19], 0
	v_mfma_f32_16x16x32_bf16 v[56:59], v[0:3], v[24:27], 0
	v_mfma_f32_16x16x32_bf16 v[60:63], v[8:11], v[24:27], 0
	v_mfma_f32_16x16x32_bf16 v[64:67], v[0:3], v[32:35], 0
	v_mfma_f32_16x16x32_bf16 v[68:71], v[8:11], v[32:35], 0
	v_mfma_f32_16x16x32_bf16 v[72:75], v[0:3], v[40:43], 0
	v_mfma_f32_16x16x32_bf16 v[76:79], v[8:11], v[40:43], 0
	v_mfma_f32_16x16x32_bf16 v[48:51], v[4:7], v[20:23], v[48:51]
	v_mfma_f32_16x16x32_bf16 v[52:55], v[12:15], v[20:23], v[52:55]
	v_mfma_f32_16x16x32_bf16 v[56:59], v[4:7], v[28:31], v[56:59]
	v_mfma_f32_16x16x32_bf16 v[60:63], v[12:15], v[28:31], v[60:63]
	v_mfma_f32_16x16x32_bf16 v[64:67], v[4:7], v[36:39], v[64:67]
	v_mfma_f32_16x16x32_bf16 v[68:71], v[12:15], v[36:39], v[68:71]
	v_mfma_f32_16x16x32_bf16 v[72:75], v[4:7], v[44:47], v[72:75]
	v_mfma_f32_16x16x32_bf16 v[76:79], v[12:15], v[44:47], v[76:79]
	s_setprio 0
	s_barrier
	v_lshl_add_u64 v[212:213], s[16:17], 0, v[170:171]
	s_add_i32 s82, s75, s7
	v_lshl_add_u64 v[96:97], v[212:213], 0, s[28:29]
	s_mov_b32 m0, s82
	v_lshl_add_u64 v[214:215], s[16:17], 0, v[174:175]
	s_add_i32 s41, s82, 0x2000
	ds_read_b128 v[80:83], v209
	ds_read_b128 v[84:87], v209 offset:1024
	ds_read_b128 v[88:91], v209 offset:2048
	ds_read_b128 v[92:95], v209 offset:3072
	global_load_lds_dwordx4 v[96:97], off
	v_lshl_add_u64 v[96:97], v[214:215], 0, s[28:29]
	s_mov_b32 m0, s41
	s_nop 0
	global_load_lds_dwordx4 v[96:97], off
	s_barrier
	s_waitcnt lgkmcnt(0)
	s_setprio 1
	s_waitcnt lgkmcnt(0)
	v_mfma_f32_16x16x32_bf16 v[96:99], v[80:83], v[16:19], 0
	v_mfma_f32_16x16x32_bf16 v[16:19], v[88:91], v[16:19], 0
	v_mfma_f32_16x16x32_bf16 v[96:99], v[84:87], v[20:23], v[96:99]
	v_mfma_f32_16x16x32_bf16 v[16:19], v[92:95], v[20:23], v[16:19]
	v_mfma_f32_16x16x32_bf16 v[20:23], v[80:83], v[24:27], 0
	v_mfma_f32_16x16x32_bf16 v[24:27], v[88:91], v[24:27], 0
	v_mfma_f32_16x16x32_bf16 v[20:23], v[84:87], v[28:31], v[20:23]
	v_mfma_f32_16x16x32_bf16 v[24:27], v[92:95], v[28:31], v[24:27]
	v_mfma_f32_16x16x32_bf16 v[28:31], v[80:83], v[32:35], 0
	v_mfma_f32_16x16x32_bf16 v[32:35], v[88:91], v[32:35], 0
	v_mfma_f32_16x16x32_bf16 v[28:31], v[84:87], v[36:39], v[28:31]
	v_mfma_f32_16x16x32_bf16 v[32:35], v[92:95], v[36:39], v[32:35]
	v_mfma_f32_16x16x32_bf16 v[36:39], v[80:83], v[40:43], 0
	v_mfma_f32_16x16x32_bf16 v[40:43], v[88:91], v[40:43], 0
	v_mfma_f32_16x16x32_bf16 v[36:39], v[84:87], v[44:47], v[36:39]
	v_mfma_f32_16x16x32_bf16 v[40:43], v[92:95], v[44:47], v[40:43]
	s_setprio 0
	v_lshl_add_u64 v[216:217], s[14:15], 0, v[168:169]
	s_mov_b32 m0, s8
	v_lshl_add_u64 v[128:129], v[216:217], 0, s[28:29]
	v_lshl_add_u64 v[220:221], s[14:15], 0, v[172:173]
	s_barrier
	ds_read_b128 v[44:47], v208 offset:16384
	ds_read_b128 v[100:103], v208 offset:17408
	ds_read_b128 v[104:107], v208 offset:18432
	ds_read_b128 v[108:111], v208 offset:19456
	ds_read_b128 v[112:115], v208 offset:20480
	ds_read_b128 v[116:119], v208 offset:21504
	ds_read_b128 v[120:123], v208 offset:22528
	ds_read_b128 v[124:127], v208 offset:23552
	global_load_lds_dwordx4 v[128:129], off
	v_lshl_add_u64 v[128:129], v[220:221], 0, s[28:29]
	s_mov_b32 m0, s9
	s_nop 0
	global_load_lds_dwordx4 v[128:129], off
	s_barrier
	s_waitcnt lgkmcnt(0)
	s_setprio 1
	s_waitcnt lgkmcnt(0)
	v_mfma_f32_16x16x32_bf16 v[128:131], v[0:3], v[44:47], 0
	v_mfma_f32_16x16x32_bf16 v[136:139], v[0:3], v[104:107], 0
	v_mfma_f32_16x16x32_bf16 v[144:147], v[0:3], v[112:115], 0
	v_mfma_f32_16x16x32_bf16 v[0:3], v[0:3], v[120:123], 0
	v_mfma_f32_16x16x32_bf16 v[128:131], v[4:7], v[100:103], v[128:131]
	v_mfma_f32_16x16x32_bf16 v[132:135], v[8:11], v[44:47], 0
	v_mfma_f32_16x16x32_bf16 v[136:139], v[4:7], v[108:111], v[136:139]
	v_mfma_f32_16x16x32_bf16 v[140:143], v[8:11], v[104:107], 0
	v_mfma_f32_16x16x32_bf16 v[144:147], v[4:7], v[116:119], v[144:147]
	v_mfma_f32_16x16x32_bf16 v[148:151], v[8:11], v[112:115], 0
	v_mfma_f32_16x16x32_bf16 v[0:3], v[4:7], v[124:127], v[0:3]
	v_mfma_f32_16x16x32_bf16 v[4:7], v[8:11], v[120:123], 0
	v_mfma_f32_16x16x32_bf16 v[132:135], v[12:15], v[100:103], v[132:135]
	v_mfma_f32_16x16x32_bf16 v[140:143], v[12:15], v[108:111], v[140:143]
	v_mfma_f32_16x16x32_bf16 v[148:151], v[12:15], v[116:119], v[148:151]
	v_mfma_f32_16x16x32_bf16 v[4:7], v[12:15], v[124:127], v[4:7]
	s_setprio 0
	s_barrier
; #define PG8_STAGE(bufoff, gbase, voff) do { _Pragma("unroll") for (int _i = 0; _i < 2; ++_i) \
;         __builtin_amdgcn_global_load_lds((const unsigned*)((const char*)(gbase) + (voff)[_i]), (LAS unsigned*)(lds + (bufoff) + ldsw + _i * 8192), 16, 0, 0); } while (0)
; #define PG8_LDA(dst, b, h) do { _Pragma("unroll") for (int m = 0; m < 4; ++m) _Pragma("unroll") for (int k = 0; k < 2; ++k) dst[m][k] = *(const LAS bf16x8*)(lds + PG8_SA(b, h) + aoff + m * 2048 + k * 1024); } while (0)
; #define PG8_LDB(dst, b, h) do { _Pragma("unroll") for (int n = 0; n < 2; ++n) _Pragma("unroll") for (int k = 0; k < 2; ++k) dst[n][k] = *(const LAS bf16x8*)(lds + PG8_SB(b, h) + boff + n * 2048 + k * 1024); } while (0)
; #define PG8_MMA(ai, bj, At, Bt) do { __builtin_amdgcn_s_setprio(1); _Pragma("unroll") for (int m = 0; m < 4; ++m) _Pragma("unroll") for (int n = 0; n < 2; ++n) _Pragma("unroll") for (int k = 0; k < 2; ++k) \
;         acc[ai][bj][m][n] = __builtin_amdgcn_mfma_f32_16x16x32_bf16(Bt[n][k], At[m][k], acc[ai][bj][m][n], 0, 0, 0); __builtin_amdgcn_s_setprio(0); } while (0)
; #define PG8_WAIT_V(n) asm volatile("s_waitcnt vmcnt(" #n ")" ::: "memory")
; #define PG8_WAIT_L(n) asm volatile("s_waitcnt lgkmcnt(" #n ")" ::: "memory")
; #define PG8_BAR __builtin_amdgcn_s_barrier()
; #define PG8_SCHED __builtin_amdgcn_sched_barrier(0)
; template <class Epi>
; __device__ __forceinline__ void gemm_phase(LAS unsigned char* lds, const Gemm g, const StaticOrder& S, const Epi& E) {
;     ...
;             PG8_STAGE(PG8_SB(0, 1), b2 + hstepB, voffB);
;             PG8_WAIT_V(6); PG8_BAR; PG8_MMA(1, 1, At, B1); PG8_BAR;
;             PG8_LDB(B0, 1, 0); PG8_SCHED; PG8_LDA(At, 1, 0); PG8_STAGE(PG8_SA(0, 1), a2 + hstepA, voffA);
;             PG8_WAIT_L(8); PG8_BAR; PG8_WAIT_L(0); PG8_MMA(0, 0, At, B0); PG8_BAR; PG8_SCHED;
;             PG8_LDB(B1, 1, 1); PG8_STAGE(PG8_SB(1, 0), b3, voffB);
;             PG8_BAR; PG8_WAIT_L(0); PG8_MMA(0, 1, At, B1); PG8_BAR;
;             PG8_LDA(At, 1, 1); PG8_STAGE(PG8_SA(1, 0), a3, voffA);
	s_add_u32 s86, s16, 0x10100
	s_addc_u32 s87, s17, 0
	s_add_i32 s83, s76, s7
	v_lshl_add_u64 v[8:9], s[86:87], 0, v[170:171]
	s_mov_b32 m0, s83
	s_add_i32 s81, s83, 0x2000
	global_load_lds_dwordx4 v[8:9], off
	v_lshl_add_u64 v[8:9], s[86:87], 0, v[174:175]
	s_mov_b32 m0, s81
	s_nop 0
	global_load_lds_dwordx4 v[8:9], off
	s_waitcnt vmcnt(6)
	s_barrier
	s_setprio 1
	v_mfma_f32_16x16x32_bf16 v[8:11], v[80:83], v[44:47], 0
	v_mfma_f32_16x16x32_bf16 v[12:15], v[88:91], v[44:47], 0
	v_mfma_f32_16x16x32_bf16 v[8:11], v[84:87], v[100:103], v[8:11]
	v_mfma_f32_16x16x32_bf16 v[12:15], v[92:95], v[100:103], v[12:15]
	v_mfma_f32_16x16x32_bf16 v[44:47], v[80:83], v[104:107], 0
	v_mfma_f32_16x16x32_bf16 v[100:103], v[88:91], v[104:107], 0
	v_mfma_f32_16x16x32_bf16 v[104:107], v[80:83], v[112:115], 0
	v_mfma_f32_16x16x32_bf16 v[80:83], v[80:83], v[120:123], 0
	v_mfma_f32_16x16x32_bf16 v[44:47], v[84:87], v[108:111], v[44:47]
	v_mfma_f32_16x16x32_bf16 v[100:103], v[92:95], v[108:111], v[100:103]
	v_mfma_f32_16x16x32_bf16 v[104:107], v[84:87], v[116:119], v[104:107]
	v_mfma_f32_16x16x32_bf16 v[108:111], v[88:91], v[112:115], 0
	v_mfma_f32_16x16x32_bf16 v[80:83], v[84:87], v[124:127], v[80:83]
	v_mfma_f32_16x16x32_bf16 v[84:87], v[88:91], v[120:123], 0
	v_mfma_f32_16x16x32_bf16 v[108:111], v[92:95], v[116:119], v[108:111]
	v_mfma_f32_16x16x32_bf16 v[84:87], v[92:95], v[124:127], v[84:87]
	s_setprio 0
	s_add_i32 s84, 0, 0x18000
	v_add_u32_e32 v218, s84, v205
	s_barrier
	ds_read_b128 v[88:91], v218
	ds_read_b128 v[92:95], v218 offset:1024
	ds_read_b128 v[112:115], v218 offset:2048
	ds_read_b128 v[116:119], v218 offset:3072
	s_add_u32 s86, s14, 0x40100
	s_addc_u32 s87, s15, 0
	s_mov_b32 m0, s35
	v_lshl_add_u64 v[188:189], s[86:87], 0, v[168:169]
	ds_read_b128 v[120:123], v208 offset:32768
	ds_read_b128 v[124:127], v208 offset:33792
	ds_read_b128 v[152:155], v208 offset:34816
	ds_read_b128 v[156:159], v208 offset:35840
	ds_read_b128 v[160:163], v208 offset:36864
	ds_read_b128 v[164:167], v208 offset:37888
	ds_read_b128 v[180:183], v208 offset:38912
	ds_read_b128 v[184:187], v208 offset:39936
	global_load_lds_dwordx4 v[188:189], off
	v_lshl_add_u64 v[188:189], s[86:87], 0, v[172:173]
	s_mov_b32 m0, s63
	s_nop 0
	global_load_lds_dwordx4 v[188:189], off
	s_waitcnt lgkmcnt(8)
	s_barrier
	s_waitcnt lgkmcnt(0)
	s_setprio 1
	s_waitcnt lgkmcnt(0)
	v_mfma_f32_16x16x32_bf16 v[48:51], v[88:91], v[120:123], v[48:51]
	v_mfma_f32_16x16x32_bf16 v[52:55], v[112:115], v[120:123], v[52:55]
	v_mfma_f32_16x16x32_bf16 v[56:59], v[88:91], v[152:155], v[56:59]
	v_mfma_f32_16x16x32_bf16 v[60:63], v[112:115], v[152:155], v[60:63]
	v_mfma_f32_16x16x32_bf16 v[64:67], v[88:91], v[160:163], v[64:67]
	v_mfma_f32_16x16x32_bf16 v[68:71], v[112:115], v[160:163], v[68:71]
	v_mfma_f32_16x16x32_bf16 v[72:75], v[88:91], v[180:183], v[72:75]
	v_mfma_f32_16x16x32_bf16 v[76:79], v[112:115], v[180:183], v[76:79]
	v_mfma_f32_16x16x32_bf16 v[48:51], v[92:95], v[124:127], v[48:51]
	v_mfma_f32_16x16x32_bf16 v[52:55], v[116:119], v[124:127], v[52:55]
	v_mfma_f32_16x16x32_bf16 v[56:59], v[92:95], v[156:159], v[56:59]
	v_mfma_f32_16x16x32_bf16 v[60:63], v[116:119], v[156:159], v[60:63]
	v_mfma_f32_16x16x32_bf16 v[64:67], v[92:95], v[164:167], v[64:67]
	v_mfma_f32_16x16x32_bf16 v[68:71], v[116:119], v[164:167], v[68:71]
	v_mfma_f32_16x16x32_bf16 v[72:75], v[92:95], v[184:187], v[72:75]
	v_mfma_f32_16x16x32_bf16 v[76:79], v[116:119], v[184:187], v[76:79]
	s_setprio 0
	s_barrier
	s_add_i32 s87, 0, 0x1c000
	s_add_i32 s86, s84, s7
	v_add_u32_e32 v235, s87, v205
	v_lshl_add_u64 v[212:213], v[212:213], 0, s[30:31]
	s_mov_b32 m0, s86
	s_add_i32 s84, s86, 0x2000
	ds_read_b128 v[188:191], v235
	ds_read_b128 v[192:195], v235 offset:1024
	ds_read_b128 v[196:199], v235 offset:2048
	ds_read_b128 v[200:203], v235 offset:3072
	global_load_lds_dwordx4 v[212:213], off
	v_lshl_add_u64 v[212:213], v[214:215], 0, s[30:31]
	s_mov_b32 m0, s84
	s_nop 0
	global_load_lds_dwordx4 v[212:213], off
	s_barrier
	s_waitcnt lgkmcnt(0)
	s_setprio 1
	s_waitcnt lgkmcnt(0)
	v_mfma_f32_16x16x32_bf16 v[96:99], v[188:191], v[120:123], v[96:99]
	v_mfma_f32_16x16x32_bf16 v[16:19], v[196:199], v[120:123], v[16:19]
	v_mfma_f32_16x16x32_bf16 v[20:23], v[188:191], v[152:155], v[20:23]
	v_mfma_f32_16x16x32_bf16 v[24:27], v[196:199], v[152:155], v[24:27]
	v_mfma_f32_16x16x32_bf16 v[28:31], v[188:191], v[160:163], v[28:31]
	v_mfma_f32_16x16x32_bf16 v[32:35], v[196:199], v[160:163], v[32:35]
	v_mfma_f32_16x16x32_bf16 v[36:39], v[188:191], v[180:183], v[36:39]
	v_mfma_f32_16x16x32_bf16 v[40:43], v[196:199], v[180:183], v[40:43]
	v_mfma_f32_16x16x32_bf16 v[96:99], v[192:195], v[124:127], v[96:99]
	v_mfma_f32_16x16x32_bf16 v[16:19], v[200:203], v[124:127], v[16:19]
	v_mfma_f32_16x16x32_bf16 v[20:23], v[192:195], v[156:159], v[20:23]
	v_mfma_f32_16x16x32_bf16 v[24:27], v[200:203], v[156:159], v[24:27]
	v_mfma_f32_16x16x32_bf16 v[28:31], v[192:195], v[164:167], v[28:31]
	v_mfma_f32_16x16x32_bf16 v[32:35], v[200:203], v[164:167], v[32:35]
	v_mfma_f32_16x16x32_bf16 v[36:39], v[192:195], v[184:187], v[36:39]
	v_mfma_f32_16x16x32_bf16 v[40:43], v[200:203], v[184:187], v[40:43]
	s_setprio 0
	s_mov_b32 m0, s72
	v_lshl_add_u64 v[212:213], v[216:217], 0, s[30:31]
	s_barrier
	ds_read_b128 v[120:123], v208 offset:49152
	ds_read_b128 v[124:127], v208 offset:50176
	ds_read_b128 v[152:155], v208 offset:51200
	ds_read_b128 v[156:159], v208 offset:52224
	ds_read_b128 v[160:163], v208 offset:53248
	ds_read_b128 v[164:167], v208 offset:54272
	ds_read_b128 v[180:183], v208 offset:55296
	ds_read_b128 v[184:187], v208 offset:56320
	global_load_lds_dwordx4 v[212:213], off
	v_lshl_add_u64 v[212:213], v[220:221], 0, s[30:31]
	s_mov_b32 m0, s73
	s_nop 0
	global_load_lds_dwordx4 v[212:213], off
	s_barrier
; #define PG8_STAGE(bufoff, gbase, voff) do { _Pragma("unroll") for (int _i = 0; _i < 2; ++_i) \
;         __builtin_amdgcn_global_load_lds((const unsigned*)((const char*)(gbase) + (voff)[_i]), (LAS unsigned*)(lds + (bufoff) + ldsw + _i * 8192), 16, 0, 0); } while (0)
; #define PG8_LDA(dst, b, h) do { _Pragma("unroll") for (int m = 0; m < 4; ++m) _Pragma("unroll") for (int k = 0; k < 2; ++k) dst[m][k] = *(const LAS bf16x8*)(lds + PG8_SA(b, h) + aoff + m * 2048 + k * 1024); } while (0)
; #define PG8_LDB(dst, b, h) do { _Pragma("unroll") for (int n = 0; n < 2; ++n) _Pragma("unroll") for (int k = 0; k < 2; ++k) dst[n][k] = *(const LAS bf16x8*)(lds + PG8_SB(b, h) + boff + n * 2048 + k * 1024); } while (0)
; #define PG8_MMA(ai, bj, At, Bt) do { __builtin_amdgcn_s_setprio(1); _Pragma("unroll") for (int m = 0; m < 4; ++m) _Pragma("unroll") for (int n = 0; n < 2; ++n) _Pragma("unroll") for (int k = 0; k < 2; ++k) \
;         acc[ai][bj][m][n] = __builtin_amdgcn_mfma_f32_16x16x32_bf16(Bt[n][k], At[m][k], acc[ai][bj][m][n], 0, 0, 0); __builtin_amdgcn_s_setprio(0); } while (0)
; #define PG8_WAIT_V(n) asm volatile("s_waitcnt vmcnt(" #n ")" ::: "memory")
; #define PG8_WAIT_L(n) asm volatile("s_waitcnt lgkmcnt(" #n ")" ::: "memory")
; #define PG8_BAR __builtin_amdgcn_s_barrier()
; #define PG8_SCHED __builtin_amdgcn_sched_barrier(0)
; template <class Epi>
; __device__ __forceinline__ void gemm_phase(LAS unsigned char* lds, const Gemm g, const StaticOrder& S, const Epi& E) {
;     ...
;             PG8_LDB(B0, 0, 0); PG8_SCHED; PG8_LDA(At, 0, 0); PG8_STAGE(PG8_SA(1, 1), a1 + hstepA, voffA);
;             PG8_WAIT_L(8); PG8_BAR; PG8_WAIT_L(0); PG8_MMA(0, 0, At, B0); PG8_BAR; PG8_SCHED;
;             PG8_LDB(B1, 0, 1); PG8_STAGE(PG8_SB(0, 0), b2, voffB);
;             PG8_BAR; PG8_WAIT_L(0); PG8_MMA(0, 1, At, B1); PG8_BAR;
;             PG8_LDA(At, 0, 1); PG8_STAGE(PG8_SA(0, 0), a2, voffA);
;     ...
;             PG8_BAR; PG8_WAIT_L(0); PG8_MMA(1, 0, At, B0); PG8_BAR; PG8_SCHED;
;             PG8_STAGE(PG8_SB(1, 1), b3 + hstepB, voffB);
;             PG8_WAIT_V(6); PG8_BAR; PG8_MMA(1, 1, At, B1); PG8_BAR;
	s_waitcnt lgkmcnt(0)
	s_setprio 1
	s_waitcnt lgkmcnt(0)
	v_mfma_f32_16x16x32_bf16 v[128:131], v[88:91], v[120:123], v[128:131]
	v_mfma_f32_16x16x32_bf16 v[132:135], v[112:115], v[120:123], v[132:135]
	v_mfma_f32_16x16x32_bf16 v[136:139], v[88:91], v[152:155], v[136:139]
	v_mfma_f32_16x16x32_bf16 v[140:143], v[112:115], v[152:155], v[140:143]
	v_mfma_f32_16x16x32_bf16 v[144:147], v[88:91], v[160:163], v[144:147]
	v_mfma_f32_16x16x32_bf16 v[148:151], v[112:115], v[160:163], v[148:151]
	v_mfma_f32_16x16x32_bf16 v[0:3], v[88:91], v[180:183], v[0:3]
	v_mfma_f32_16x16x32_bf16 v[4:7], v[112:115], v[180:183], v[4:7]
	v_mfma_f32_16x16x32_bf16 v[128:131], v[92:95], v[124:127], v[128:131]
	v_mfma_f32_16x16x32_bf16 v[132:135], v[116:119], v[124:127], v[132:135]
	v_mfma_f32_16x16x32_bf16 v[136:139], v[92:95], v[156:159], v[136:139]
	v_mfma_f32_16x16x32_bf16 v[140:143], v[116:119], v[156:159], v[140:143]
	v_mfma_f32_16x16x32_bf16 v[144:147], v[92:95], v[164:167], v[144:147]
	v_mfma_f32_16x16x32_bf16 v[148:151], v[116:119], v[164:167], v[148:151]
	v_mfma_f32_16x16x32_bf16 v[0:3], v[92:95], v[184:187], v[0:3]
	v_mfma_f32_16x16x32_bf16 v[4:7], v[116:119], v[184:187], v[4:7]
	s_setprio 0
	s_barrier
	s_add_u32 s88, s16, 0x10180
	s_addc_u32 s89, s17, 0
	s_add_i32 s17, s87, s7
	v_lshl_add_u64 v[88:89], s[88:89], 0, v[170:171]
	s_mov_b32 m0, s17
	s_add_i32 s16, s17, 0x2000
	global_load_lds_dwordx4 v[88:89], off
	v_lshl_add_u64 v[88:89], s[88:89], 0, v[174:175]
	s_mov_b32 m0, s16
	s_nop 0
	global_load_lds_dwordx4 v[88:89], off
	s_waitcnt vmcnt(6)
	s_barrier
	s_setprio 1
	v_mfma_f32_16x16x32_bf16 v[8:11], v[188:191], v[120:123], v[8:11]
	v_mfma_f32_16x16x32_bf16 v[12:15], v[196:199], v[120:123], v[12:15]
	v_mfma_f32_16x16x32_bf16 v[44:47], v[188:191], v[152:155], v[44:47]
	v_mfma_f32_16x16x32_bf16 v[88:91], v[196:199], v[152:155], v[100:103]
	v_mfma_f32_16x16x32_bf16 v[92:95], v[188:191], v[160:163], v[104:107]
	v_mfma_f32_16x16x32_bf16 v[100:103], v[196:199], v[160:163], v[108:111]
	v_mfma_f32_16x16x32_bf16 v[80:83], v[188:191], v[180:183], v[80:83]
	v_mfma_f32_16x16x32_bf16 v[84:87], v[196:199], v[180:183], v[84:87]
	v_mfma_f32_16x16x32_bf16 v[8:11], v[192:195], v[124:127], v[8:11]
	v_mfma_f32_16x16x32_bf16 v[12:15], v[200:203], v[124:127], v[12:15]
	v_mfma_f32_16x16x32_bf16 v[44:47], v[192:195], v[156:159], v[44:47]
	v_mfma_f32_16x16x32_bf16 v[88:91], v[200:203], v[156:159], v[88:91]
	v_mfma_f32_16x16x32_bf16 v[92:95], v[192:195], v[164:167], v[92:95]
	v_mfma_f32_16x16x32_bf16 v[100:103], v[200:203], v[164:167], v[100:103]
	v_mfma_f32_16x16x32_bf16 v[80:83], v[192:195], v[184:187], v[80:83]
	v_mfma_f32_16x16x32_bf16 v[84:87], v[200:203], v[184:187], v[84:87]
	s_setprio 0
	s_barrier
	ds_read_b128 v[104:107], v207
	ds_read_b128 v[108:111], v207 offset:1024
	ds_read_b128 v[112:115], v207 offset:2048
	ds_read_b128 v[116:119], v207 offset:3072
	s_add_u32 s14, s14, 0x40180
	s_addc_u32 s15, s15, 0
	s_mov_b32 m0, s85
	v_lshl_add_u64 v[188:189], s[14:15], 0, v[168:169]
	ds_read_b128 v[120:123], v208
	ds_read_b128 v[124:127], v208 offset:1024
	ds_read_b128 v[152:155], v208 offset:2048
	ds_read_b128 v[156:159], v208 offset:3072
	ds_read_b128 v[160:163], v208 offset:4096
	ds_read_b128 v[164:167], v208 offset:5120
	ds_read_b128 v[180:183], v208 offset:6144
	ds_read_b128 v[184:187], v208 offset:7168
	global_load_lds_dwordx4 v[188:189], off
	v_lshl_add_u64 v[188:189], s[14:15], 0, v[172:173]
	s_mov_b32 m0, s39
	s_nop 0
	global_load_lds_dwordx4 v[188:189], off
	s_waitcnt lgkmcnt(8)
	s_barrier
	s_waitcnt lgkmcnt(0)
	s_setprio 1
	s_waitcnt lgkmcnt(0)
	v_mfma_f32_16x16x32_bf16 v[72:75], v[104:107], v[180:183], v[72:75]
	v_mfma_f32_16x16x32_bf16 v[48:51], v[104:107], v[120:123], v[48:51]
	v_mfma_f32_16x16x32_bf16 v[52:55], v[112:115], v[120:123], v[52:55]
	v_mfma_f32_16x16x32_bf16 v[56:59], v[104:107], v[152:155], v[56:59]
	v_mfma_f32_16x16x32_bf16 v[60:63], v[112:115], v[152:155], v[60:63]
	v_mfma_f32_16x16x32_bf16 v[64:67], v[104:107], v[160:163], v[64:67]
	v_mfma_f32_16x16x32_bf16 v[68:71], v[112:115], v[160:163], v[68:71]
	v_mfma_f32_16x16x32_bf16 v[188:191], v[108:111], v[184:187], v[72:75]
	v_mfma_f32_16x16x32_bf16 v[72:75], v[112:115], v[180:183], v[76:79]
	v_mfma_f32_16x16x32_bf16 v[48:51], v[108:111], v[124:127], v[48:51]
	v_mfma_f32_16x16x32_bf16 v[52:55], v[116:119], v[124:127], v[52:55]
	v_mfma_f32_16x16x32_bf16 v[56:59], v[108:111], v[156:159], v[56:59]
	v_mfma_f32_16x16x32_bf16 v[60:63], v[116:119], v[156:159], v[60:63]
	v_mfma_f32_16x16x32_bf16 v[64:67], v[108:111], v[164:167], v[64:67]
	v_mfma_f32_16x16x32_bf16 v[68:71], v[116:119], v[164:167], v[68:71]
	v_mfma_f32_16x16x32_bf16 v[76:79], v[116:119], v[184:187], v[72:75]
	s_setprio 0
	s_barrier
	s_mov_b32 m0, s82
	v_lshl_add_u64 v[216:217], s[46:47], 0, v[170:171]
	ds_read_b128 v[72:75], v209
	ds_read_b128 v[192:195], v209 offset:1024
	ds_read_b128 v[196:199], v209 offset:2048
	ds_read_b128 v[200:203], v209 offset:3072
	global_load_lds_dwordx4 v[216:217], off
	v_lshl_add_u64 v[232:233], s[46:47], 0, v[174:175]
	s_mov_b32 m0, s41
	s_nop 0
	global_load_lds_dwordx4 v[232:233], off
	s_barrier
; #define PG8_STAGE(bufoff, gbase, voff) do { _Pragma("unroll") for (int _i = 0; _i < 2; ++_i) \
;         __builtin_amdgcn_global_load_lds((const unsigned*)((const char*)(gbase) + (voff)[_i]), (LAS unsigned*)(lds + (bufoff) + ldsw + _i * 8192), 16, 0, 0); } while (0)
; #define PG8_LDA(dst, b, h) do { _Pragma("unroll") for (int m = 0; m < 4; ++m) _Pragma("unroll") for (int k = 0; k < 2; ++k) dst[m][k] = *(const LAS bf16x8*)(lds + PG8_SA(b, h) + aoff + m * 2048 + k * 1024); } while (0)
; #define PG8_LDB(dst, b, h) do { _Pragma("unroll") for (int n = 0; n < 2; ++n) _Pragma("unroll") for (int k = 0; k < 2; ++k) dst[n][k] = *(const LAS bf16x8*)(lds + PG8_SB(b, h) + boff + n * 2048 + k * 1024); } while (0)
; #define PG8_WAIT_V(n) asm volatile("s_waitcnt vmcnt(" #n ")" ::: "memory")
; #define PG8_WAIT_L(n) asm volatile("s_waitcnt lgkmcnt(" #n ")" ::: "memory")
; #define PG8_BAR __builtin_amdgcn_s_barrier()
; #define PG8_SCHED __builtin_amdgcn_sched_barrier(0)
; template <class Epi>
; __device__ __forceinline__ void gemm_phase(LAS unsigned char* lds, const Gemm g, const StaticOrder& S, const Epi& E) {
;     ...
;             PG8_LDB(B0, 0, 0); PG8_SCHED; PG8_LDA(At, 0, 0); PG8_STAGE(PG8_SA(1, 1), a1 + hstepA, voffA);
;             PG8_WAIT_L(8); PG8_BAR; PG8_WAIT_L(0); PG8_MMA(0, 0, At, B0); PG8_BAR; PG8_SCHED;
;             PG8_LDB(B1, 0, 1); PG8_STAGE(PG8_SB(0, 0), b2, voffB);
;             PG8_BAR; PG8_WAIT_L(0); PG8_MMA(0, 1, At, B1); PG8_BAR;
;             PG8_LDA(At, 0, 1); PG8_STAGE(PG8_SA(0, 0), a2, voffA);
;             PG8_BAR; PG8_WAIT_L(0); PG8_MMA(1, 0, At, B0); PG8_BAR; PG8_SCHED;
;             PG8_STAGE(PG8_SB(0, 1), b2 + hstepB, voffB);
;             PG8_WAIT_V(6); PG8_BAR; PG8_MMA(1, 1, At, B1); PG8_BAR;
;             PG8_LDB(B0, 1, 0); PG8_SCHED; PG8_LDA(At, 1, 0); PG8_STAGE(PG8_SA(0, 1), a2 + hstepA, voffA);
;             PG8_WAIT_L(8); PG8_BAR; PG8_WAIT_L(0); PG8_MMA(0, 0, At, B0); PG8_BAR; PG8_SCHED;
;             PG8_LDB(B1, 1, 1); PG8_STAGE(PG8_SB(1, 0), b3, voffB);
;             PG8_BAR; PG8_WAIT_L(0); PG8_MMA(0, 1, At, B1); PG8_BAR;
;             PG8_LDA(At, 1, 1); PG8_STAGE(PG8_SA(1, 0), a3, voffA);
;             PG8_BAR; PG8_WAIT_L(0); PG8_MMA(1, 0, At, B0); PG8_BAR; PG8_SCHED;
;             PG8_STAGE(PG8_SB(1, 1), b3 + hstepB, voffB);
;             PG8_WAIT_V(6); PG8_BAR; PG8_MMA(1, 1, At, B1); PG8_BAR;
	s_waitcnt lgkmcnt(0)
	s_setprio 1
	s_waitcnt lgkmcnt(0)
	v_mfma_f32_16x16x32_bf16 v[96:99], v[72:75], v[120:123], v[96:99]
	v_mfma_f32_16x16x32_bf16 v[16:19], v[196:199], v[120:123], v[16:19]
	v_mfma_f32_16x16x32_bf16 v[20:23], v[72:75], v[152:155], v[20:23]
	v_mfma_f32_16x16x32_bf16 v[24:27], v[196:199], v[152:155], v[24:27]
	v_mfma_f32_16x16x32_bf16 v[28:31], v[72:75], v[160:163], v[28:31]
	v_mfma_f32_16x16x32_bf16 v[32:35], v[196:199], v[160:163], v[32:35]
	v_mfma_f32_16x16x32_bf16 v[36:39], v[72:75], v[180:183], v[36:39]
	v_mfma_f32_16x16x32_bf16 v[40:43], v[196:199], v[180:183], v[40:43]
	v_mfma_f32_16x16x32_bf16 v[96:99], v[192:195], v[124:127], v[96:99]
	v_mfma_f32_16x16x32_bf16 v[16:19], v[200:203], v[124:127], v[16:19]
	v_mfma_f32_16x16x32_bf16 v[20:23], v[192:195], v[156:159], v[20:23]
	v_mfma_f32_16x16x32_bf16 v[24:27], v[200:203], v[156:159], v[24:27]
	v_mfma_f32_16x16x32_bf16 v[28:31], v[192:195], v[164:167], v[28:31]
	v_mfma_f32_16x16x32_bf16 v[32:35], v[200:203], v[164:167], v[32:35]
	v_mfma_f32_16x16x32_bf16 v[36:39], v[192:195], v[184:187], v[36:39]
	v_mfma_f32_16x16x32_bf16 v[40:43], v[200:203], v[184:187], v[40:43]
	s_setprio 0
	s_mov_b32 m0, s8
	v_lshl_add_u64 v[248:249], s[48:49], 0, v[168:169]
	s_barrier
	ds_read_b128 v[120:123], v208 offset:16384
	ds_read_b128 v[124:127], v208 offset:17408
	ds_read_b128 v[152:155], v208 offset:18432
	ds_read_b128 v[156:159], v208 offset:19456
	ds_read_b128 v[160:163], v208 offset:20480
	ds_read_b128 v[164:167], v208 offset:21504
	ds_read_b128 v[180:183], v208 offset:22528
	ds_read_b128 v[184:187], v208 offset:23552
	global_load_lds_dwordx4 v[248:249], off
	v_lshl_add_u64 v[250:251], s[48:49], 0, v[172:173]
	s_mov_b32 m0, s9
	s_nop 0
	global_load_lds_dwordx4 v[250:251], off
	s_barrier
	s_waitcnt lgkmcnt(0)
	s_setprio 1
	s_waitcnt lgkmcnt(0)
	v_mfma_f32_16x16x32_bf16 v[136:139], v[104:107], v[152:155], v[136:139]
	v_mfma_f32_16x16x32_bf16 v[212:215], v[108:111], v[156:159], v[136:139]
	v_mfma_f32_16x16x32_bf16 v[136:139], v[112:115], v[152:155], v[140:143]
	v_mfma_f32_16x16x32_bf16 v[220:223], v[116:119], v[156:159], v[136:139]
	v_mfma_f32_16x16x32_bf16 v[136:139], v[104:107], v[160:163], v[144:147]
	v_mfma_f32_16x16x32_bf16 v[128:131], v[104:107], v[120:123], v[128:131]
	v_mfma_f32_16x16x32_bf16 v[132:135], v[112:115], v[120:123], v[132:135]
	v_mfma_f32_16x16x32_bf16 v[224:227], v[108:111], v[164:167], v[136:139]
	v_mfma_f32_16x16x32_bf16 v[136:139], v[112:115], v[160:163], v[148:151]
	v_mfma_f32_16x16x32_bf16 v[0:3], v[104:107], v[180:183], v[0:3]
	v_mfma_f32_16x16x32_bf16 v[4:7], v[112:115], v[180:183], v[4:7]
	v_mfma_f32_16x16x32_bf16 v[128:131], v[108:111], v[124:127], v[128:131]
	v_mfma_f32_16x16x32_bf16 v[132:135], v[116:119], v[124:127], v[132:135]
	v_mfma_f32_16x16x32_bf16 v[228:231], v[116:119], v[164:167], v[136:139]
	v_mfma_f32_16x16x32_bf16 v[0:3], v[108:111], v[184:187], v[0:3]
	v_mfma_f32_16x16x32_bf16 v[4:7], v[116:119], v[184:187], v[4:7]
	s_setprio 0
	s_barrier
	s_add_u32 s14, s46, 0x10000
	s_addc_u32 s15, s47, 0
	s_mov_b32 m0, s83
	v_lshl_add_u64 v[104:105], s[14:15], 0, v[170:171]
	global_load_lds_dwordx4 v[104:105], off
	v_lshl_add_u64 v[104:105], s[14:15], 0, v[174:175]
	s_mov_b32 m0, s81
	s_nop 0
	global_load_lds_dwordx4 v[104:105], off
	s_waitcnt vmcnt(6)
	s_barrier
	s_setprio 1
	v_mfma_f32_16x16x32_bf16 v[12:15], v[196:199], v[120:123], v[12:15]
	v_mfma_f32_16x16x32_bf16 v[104:107], v[200:203], v[124:127], v[12:15]
	v_mfma_f32_16x16x32_bf16 v[12:15], v[72:75], v[152:155], v[44:47]
	v_mfma_f32_16x16x32_bf16 v[44:47], v[192:195], v[156:159], v[12:15]
	v_mfma_f32_16x16x32_bf16 v[12:15], v[196:199], v[152:155], v[88:91]
	v_mfma_f32_16x16x32_bf16 v[108:111], v[200:203], v[156:159], v[12:15]
	v_mfma_f32_16x16x32_bf16 v[12:15], v[72:75], v[160:163], v[92:95]
	v_mfma_f32_16x16x32_bf16 v[92:95], v[192:195], v[164:167], v[12:15]
	v_mfma_f32_16x16x32_bf16 v[12:15], v[196:199], v[160:163], v[100:103]
	v_mfma_f32_16x16x32_bf16 v[100:103], v[200:203], v[164:167], v[12:15]
	v_mfma_f32_16x16x32_bf16 v[12:15], v[72:75], v[180:183], v[80:83]
	v_mfma_f32_16x16x32_bf16 v[8:11], v[72:75], v[120:123], v[8:11]
	v_mfma_f32_16x16x32_bf16 v[80:83], v[192:195], v[184:187], v[12:15]
	v_mfma_f32_16x16x32_bf16 v[12:15], v[196:199], v[180:183], v[84:87]
	v_mfma_f32_16x16x32_bf16 v[8:11], v[192:195], v[124:127], v[8:11]
	v_mfma_f32_16x16x32_bf16 v[180:183], v[200:203], v[184:187], v[12:15]
	s_setprio 0
	s_barrier
	ds_read_b128 v[116:119], v218
	ds_read_b128 v[124:127], v218 offset:1024
	ds_read_b128 v[184:187], v218 offset:2048
	ds_read_b128 v[192:195], v218 offset:3072
	s_add_u32 s14, s48, 0x40000
	s_addc_u32 s15, s49, 0
	s_mov_b32 m0, s35
	v_lshl_add_u64 v[72:73], s[14:15], 0, v[168:169]
	ds_read_b128 v[12:15], v208 offset:32768
	ds_read_b128 v[88:91], v208 offset:33792
	ds_read_b128 v[112:115], v208 offset:34816
	ds_read_b128 v[120:123], v208 offset:35840
	ds_read_b128 v[140:143], v208 offset:36864
	ds_read_b128 v[196:199], v208 offset:37888
	ds_read_b128 v[200:203], v208 offset:38912
	ds_read_b128 v[236:239], v208 offset:39936
	global_load_lds_dwordx4 v[72:73], off
	v_lshl_add_u64 v[72:73], s[14:15], 0, v[172:173]
	s_mov_b32 m0, s63
	s_nop 0
	global_load_lds_dwordx4 v[72:73], off
	s_waitcnt lgkmcnt(8)
	s_barrier
; #define PG8_STAGE(bufoff, gbase, voff) do { _Pragma("unroll") for (int _i = 0; _i < 2; ++_i) \
;         __builtin_amdgcn_global_load_lds((const unsigned*)((const char*)(gbase) + (voff)[_i]), (LAS unsigned*)(lds + (bufoff) + ldsw + _i * 8192), 16, 0, 0); } while (0)
; #define PG8_LDA(dst, b, h) do { _Pragma("unroll") for (int m = 0; m < 4; ++m) _Pragma("unroll") for (int k = 0; k < 2; ++k) dst[m][k] = *(const LAS bf16x8*)(lds + PG8_SA(b, h) + aoff + m * 2048 + k * 1024); } while (0)
; #define PG8_LDB(dst, b, h) do { _Pragma("unroll") for (int n = 0; n < 2; ++n) _Pragma("unroll") for (int k = 0; k < 2; ++k) dst[n][k] = *(const LAS bf16x8*)(lds + PG8_SB(b, h) + boff + n * 2048 + k * 1024); } while (0)
; #define PG8_MMA(ai, bj, At, Bt) do { __builtin_amdgcn_s_setprio(1); _Pragma("unroll") for (int m = 0; m < 4; ++m) _Pragma("unroll") for (int n = 0; n < 2; ++n) _Pragma("unroll") for (int k = 0; k < 2; ++k) \
;         acc[ai][bj][m][n] = __builtin_amdgcn_mfma_f32_16x16x32_bf16(Bt[n][k], At[m][k], acc[ai][bj][m][n], 0, 0, 0); __builtin_amdgcn_s_setprio(0); } while (0)
; #define PG8_WAIT_V(n) asm volatile("s_waitcnt vmcnt(" #n ")" ::: "memory")
; #define PG8_WAIT_L(n) asm volatile("s_waitcnt lgkmcnt(" #n ")" ::: "memory")
; #define PG8_BAR __builtin_amdgcn_s_barrier()
; #define PG8_SCHED __builtin_amdgcn_sched_barrier(0)
; template <class Epi>
; __device__ __forceinline__ void gemm_phase(LAS unsigned char* lds, const Gemm g, const StaticOrder& S, const Epi& E) {
;     ...
;             PG8_LDB(B0, 1, 0); PG8_SCHED; PG8_LDA(At, 1, 0); PG8_STAGE(PG8_SA(0, 1), a2 + hstepA, voffA);
;             PG8_WAIT_L(8); PG8_BAR; PG8_WAIT_L(0); PG8_MMA(0, 0, At, B0); PG8_BAR; PG8_SCHED;
;             PG8_LDB(B1, 1, 1); PG8_STAGE(PG8_SB(1, 0), b3, voffB);
;             PG8_BAR; PG8_WAIT_L(0); PG8_MMA(0, 1, At, B1); PG8_BAR;
;             PG8_LDA(At, 1, 1); PG8_STAGE(PG8_SA(1, 0), a3, voffA);
;             PG8_BAR; PG8_WAIT_L(0); PG8_MMA(1, 0, At, B0); PG8_BAR; PG8_SCHED;
;             PG8_STAGE(PG8_SB(1, 1), b3 + hstepB, voffB);
;             PG8_WAIT_V(6); PG8_BAR; PG8_MMA(1, 1, At, B1); PG8_BAR;
;     __device__ __forceinline__ void operator()(AccRef acc, const Unit& u, int wr, int wc, int fr, int fq) const {
;         const int row0 = u.pm * 256 + wr * 64 + fr, col0 = u.pn * 128 + wc * 32 + 8 * fq;
	s_waitcnt lgkmcnt(0)
	s_setprio 1
	s_waitcnt lgkmcnt(0)
	v_mfma_f32_16x16x32_bf16 v[48:51], v[116:119], v[12:15], v[48:51]
	v_mfma_f32_16x16x32_bf16 v[160:163], v[124:127], v[88:91], v[48:51]
	v_mfma_f32_16x16x32_bf16 v[48:51], v[184:187], v[12:15], v[52:55]
	v_mfma_f32_16x16x32_bf16 v[84:87], v[192:195], v[88:91], v[48:51]
	v_mfma_f32_16x16x32_bf16 v[48:51], v[116:119], v[112:115], v[56:59]
	v_mfma_f32_16x16x32_bf16 v[152:155], v[124:127], v[120:123], v[48:51]
	v_mfma_f32_16x16x32_bf16 v[48:51], v[184:187], v[112:115], v[60:63]
	v_mfma_f32_16x16x32_bf16 v[72:75], v[192:195], v[120:123], v[48:51]
	v_mfma_f32_16x16x32_bf16 v[48:51], v[116:119], v[140:143], v[64:67]
	v_mfma_f32_16x16x32_bf16 v[144:147], v[124:127], v[196:199], v[48:51]
	v_mfma_f32_16x16x32_bf16 v[48:51], v[184:187], v[140:143], v[68:71]
	v_mfma_f32_16x16x32_bf16 v[60:63], v[192:195], v[196:199], v[48:51]
	v_mfma_f32_16x16x32_bf16 v[48:51], v[116:119], v[200:203], v[188:191]
	v_mfma_f32_16x16x32_bf16 v[136:139], v[124:127], v[236:239], v[48:51]
	v_mfma_f32_16x16x32_bf16 v[48:51], v[184:187], v[200:203], v[76:79]
	v_mfma_f32_16x16x32_bf16 v[48:51], v[192:195], v[236:239], v[48:51]
	s_setprio 0
	s_barrier
	s_mov_b32 m0, s86
	v_lshl_add_u64 v[52:53], v[216:217], 0, s[24:25]
	ds_read_b128 v[56:59], v235
	ds_read_b128 v[68:71], v235 offset:1024
	ds_read_b128 v[188:191], v235 offset:2048
	ds_read_b128 v[240:243], v235 offset:3072
	global_load_lds_dwordx4 v[52:53], off
	v_lshl_add_u64 v[52:53], v[232:233], 0, s[24:25]
	s_mov_b32 m0, s84
	s_nop 0
	global_load_lds_dwordx4 v[52:53], off
	s_barrier
	s_waitcnt lgkmcnt(0)
	s_setprio 1
	s_waitcnt lgkmcnt(0)
	v_mfma_f32_16x16x32_bf16 v[52:55], v[56:59], v[12:15], v[96:99]
	v_mfma_f32_16x16x32_bf16 v[12:15], v[188:191], v[12:15], v[16:19]
	v_mfma_f32_16x16x32_bf16 v[164:167], v[68:71], v[88:91], v[52:55]
	v_mfma_f32_16x16x32_bf16 v[88:91], v[240:243], v[88:91], v[12:15]
	v_mfma_f32_16x16x32_bf16 v[12:15], v[56:59], v[112:115], v[20:23]
	v_mfma_f32_16x16x32_bf16 v[156:159], v[68:71], v[120:123], v[12:15]
	v_mfma_f32_16x16x32_bf16 v[12:15], v[188:191], v[112:115], v[24:27]
	v_mfma_f32_16x16x32_bf16 v[76:79], v[240:243], v[120:123], v[12:15]
	v_mfma_f32_16x16x32_bf16 v[12:15], v[56:59], v[140:143], v[28:31]
	v_mfma_f32_16x16x32_bf16 v[148:151], v[68:71], v[196:199], v[12:15]
	v_mfma_f32_16x16x32_bf16 v[12:15], v[188:191], v[140:143], v[32:35]
	v_mfma_f32_16x16x32_bf16 v[64:67], v[240:243], v[196:199], v[12:15]
	v_mfma_f32_16x16x32_bf16 v[12:15], v[56:59], v[200:203], v[36:39]
	v_mfma_f32_16x16x32_bf16 v[140:143], v[68:71], v[236:239], v[12:15]
	v_mfma_f32_16x16x32_bf16 v[12:15], v[188:191], v[200:203], v[40:43]
	v_mfma_f32_16x16x32_bf16 v[52:55], v[240:243], v[236:239], v[12:15]
	s_setprio 0
	s_mov_b32 m0, s72
	s_nop 4
	v_lshl_add_u64 v[12:13], v[248:249], 0, s[24:25]
	s_barrier
	ds_read_b128 v[16:19], v208 offset:49152
	ds_read_b128 v[20:23], v208 offset:50176
	ds_read_b128 v[28:31], v208 offset:51200
	ds_read_b128 v[32:35], v208 offset:52224
	ds_read_b128 v[196:199], v208 offset:53248
	ds_read_b128 v[200:203], v208 offset:54272
	ds_read_b128 v[236:239], v208 offset:55296
	ds_read_b128 v[244:247], v208 offset:56320
	global_load_lds_dwordx4 v[12:13], off
	v_lshl_add_u64 v[12:13], v[250:251], 0, s[24:25]
	s_mov_b32 m0, s73
	s_nop 0
	global_load_lds_dwordx4 v[12:13], off
	s_barrier
	s_waitcnt lgkmcnt(0)
	s_setprio 1
	s_waitcnt lgkmcnt(0)
	v_mfma_f32_16x16x32_bf16 v[12:15], v[116:119], v[16:19], v[128:131]
	v_mfma_f32_16x16x32_bf16 v[128:131], v[124:127], v[20:23], v[12:15]
	v_mfma_f32_16x16x32_bf16 v[12:15], v[184:187], v[16:19], v[132:135]
	v_mfma_f32_16x16x32_bf16 v[36:39], v[192:195], v[20:23], v[12:15]
	v_mfma_f32_16x16x32_bf16 v[12:15], v[116:119], v[28:31], v[212:215]
	v_mfma_f32_16x16x32_bf16 v[120:123], v[124:127], v[32:35], v[12:15]
	v_mfma_f32_16x16x32_bf16 v[12:15], v[184:187], v[28:31], v[220:223]
	v_mfma_f32_16x16x32_bf16 v[24:27], v[192:195], v[32:35], v[12:15]
	v_mfma_f32_16x16x32_bf16 v[12:15], v[116:119], v[196:199], v[224:227]
	v_mfma_f32_16x16x32_bf16 v[0:3], v[116:119], v[236:239], v[0:3]
	v_mfma_f32_16x16x32_bf16 v[112:115], v[124:127], v[200:203], v[12:15]
	v_mfma_f32_16x16x32_bf16 v[12:15], v[184:187], v[196:199], v[228:231]
	v_mfma_f32_16x16x32_bf16 v[96:99], v[124:127], v[244:247], v[0:3]
	v_mfma_f32_16x16x32_bf16 v[0:3], v[184:187], v[236:239], v[4:7]
	v_mfma_f32_16x16x32_bf16 v[12:15], v[192:195], v[200:203], v[12:15]
	v_mfma_f32_16x16x32_bf16 v[0:3], v[192:195], v[244:247], v[0:3]
	s_setprio 0
	s_barrier
	s_add_u32 s14, s46, 0x10080
	s_addc_u32 s15, s47, 0
	s_mov_b32 m0, s17
	v_lshl_add_u64 v[4:5], s[14:15], 0, v[170:171]
	global_load_lds_dwordx4 v[4:5], off
	v_lshl_add_u64 v[4:5], s[14:15], 0, v[174:175]
	s_mov_b32 m0, s16
	s_nop 0
	global_load_lds_dwordx4 v[4:5], off
	s_waitcnt vmcnt(6)
	s_barrier
	s_setprio 1
	v_mfma_f32_16x16x32_bf16 v[4:7], v[56:59], v[16:19], v[8:11]
	v_mfma_f32_16x16x32_bf16 v[132:135], v[68:71], v[20:23], v[4:7]
	v_mfma_f32_16x16x32_bf16 v[4:7], v[188:191], v[16:19], v[104:107]
	v_mfma_f32_16x16x32_bf16 v[40:43], v[240:243], v[20:23], v[4:7]
	v_mfma_f32_16x16x32_bf16 v[4:7], v[56:59], v[28:31], v[44:47]
	v_mfma_f32_16x16x32_bf16 v[124:127], v[68:71], v[32:35], v[4:7]
	v_mfma_f32_16x16x32_bf16 v[4:7], v[188:191], v[28:31], v[108:111]
	v_mfma_f32_16x16x32_bf16 v[28:31], v[240:243], v[32:35], v[4:7]
	v_mfma_f32_16x16x32_bf16 v[4:7], v[56:59], v[196:199], v[92:95]
	v_mfma_f32_16x16x32_bf16 v[116:119], v[68:71], v[200:203], v[4:7]
	v_mfma_f32_16x16x32_bf16 v[4:7], v[188:191], v[196:199], v[100:103]
	v_mfma_f32_16x16x32_bf16 v[16:19], v[240:243], v[200:203], v[4:7]
	v_mfma_f32_16x16x32_bf16 v[4:7], v[56:59], v[236:239], v[80:83]
	v_mfma_f32_16x16x32_bf16 v[100:103], v[68:71], v[244:247], v[4:7]
	v_mfma_f32_16x16x32_bf16 v[4:7], v[188:191], v[236:239], v[180:183]
	v_mfma_f32_16x16x32_bf16 v[4:7], v[240:243], v[244:247], v[4:7]
	s_setprio 0
	s_nop 0
	v_lshl_or_b32 v180, s13, 7, v206
	v_ashrrev_i32_e32 v181, 31, v180
	v_lshlrev_b64 v[8:9], 2, v[180:181]
	v_lshl_add_u64 v[184:185], s[22:23], 0, v[8:9]
	s_barrier
; __device__ __forceinline__ float bflo(unsigned w) { return __uint_as_float(w << 16); }
; __device__ __forceinline__ float bfhi(unsigned w) { return __uint_as_float(w & 0xffff0000u); }
; __device__ __forceinline__ float sigmoidf_(float x) { return __builtin_amdgcn_rcpf(1.0f + __expf(-x)); }
;     __device__ __forceinline__ void operator()(AccRef acc, const Unit& u, int wr, int wc, int fr, int fq) const {
;         const int row0 = u.pm * 256 + wr * 64 + fr, col0 = u.pn * 128 + wc * 32 + 8 * fq;
;         u32x4 rws[2][4];
; #pragma unroll
;         for (int ai = 0; ai < 2; ++ai)
; #pragma unroll
;             for (int m = 0; m < 4; ++m) rws[ai][m] = *(const u32x4*)(REC + (size_t)(row0 + ai * 128 + m * 16) * D + col0);
; #pragma unroll
;         for (int n = 0; n < 2; ++n) {
;             const f32x4 ba = *(const f32x4*)(b_a + col0 + 4 * n), bx = *(const f32x4*)(b_x + col0 + 4 * n), l = *(const f32x4*)(lam + col0 + 4 * n);
;             f32x4 k8;
; #pragma unroll
;             for (int j = 0; j < 4; ++j) k8[j] = -8.0f * __logf(1.0f + __expf(-l[j]));
; #pragma unroll
;             for (int ai = 0; ai < 2; ++ai)
; #pragma unroll
;                 for (int m = 0; m < 4; ++m) { const size_t off = (size_t)(row0 + ai * 128 + m * 16) * D + col0 + 4 * n;
;                     float lo[4], bo[4];
; #pragma unroll
;                     for (int j = 0; j < 4; ++j) { const unsigned w = rws[ai][m][2 * n + (j >> 1)]; const float rec = (j & 1) ? bfhi(w) : bflo(w);
;                         const float r = sigmoidf_(acc[ai][0][m][n][j] + ba[j]), ig = sigmoidf_(acc[ai][1][m][n][j] + bx[j]);
;                         const float la = k8[j] * r; const float mult = __builtin_sqrtf(1.0f - __expf(2.0f * la));
;                         lo[j] = la; bo[j] = mult * ig * rec; }
	global_load_dwordx4 v[212:215], v[184:185], off
	v_lshl_add_u64 v[186:187], s[26:27], 0, v[8:9]
	global_load_dwordx4 v[108:111], v[186:187], off
	v_lshl_add_u64 v[188:189], s[20:21], 0, v[8:9]
	global_load_dwordx4 v[104:107], v[188:189], off
	v_lshl_add_u32 v182, s12, 8, v204
	v_or_b32_e32 v202, 16, v182
	v_or_b32_e32 v200, 32, v182
	v_or_b32_e32 v198, 48, v182
	v_add_u32_e32 v196, 0x80, v182
	v_add_u32_e32 v194, 0x90, v182
	v_add_u32_e32 v192, 0xa0, v182
	v_add_u32_e32 v190, 0xb0, v182
	v_ashrrev_i32_e32 v183, 31, v182
	v_ashrrev_i32_e32 v203, 31, v202
	v_ashrrev_i32_e32 v201, 31, v200
	v_ashrrev_i32_e32 v199, 31, v198
	v_ashrrev_i32_e32 v197, 31, v196
	v_ashrrev_i32_e32 v195, 31, v194
	v_ashrrev_i32_e32 v193, 31, v192
	v_ashrrev_i32_e32 v191, 31, v190
	v_lshl_add_u64 v[10:11], v[180:181], 1, s[18:19]
	v_lshlrev_b64 v[20:21], 11, v[182:183]
	v_lshlrev_b64 v[22:23], 11, v[202:203]
	v_lshlrev_b64 v[32:33], 11, v[200:201]
	v_lshlrev_b64 v[34:35], 11, v[198:199]
	v_lshlrev_b64 v[44:45], 11, v[196:197]
	v_lshlrev_b64 v[46:47], 11, v[194:195]
	v_lshlrev_b64 v[56:57], 11, v[192:193]
	v_lshlrev_b64 v[58:59], 11, v[190:191]
	v_lshl_add_u64 v[20:21], v[10:11], 0, v[20:21]
	v_lshl_add_u64 v[8:9], v[10:11], 0, v[22:23]
	v_lshl_add_u64 v[22:23], v[10:11], 0, v[32:33]
	v_lshl_add_u64 v[32:33], v[10:11], 0, v[34:35]
	v_lshl_add_u64 v[34:35], v[10:11], 0, v[44:45]
	v_lshl_add_u64 v[216:217], v[10:11], 0, v[46:47]
	v_lshl_add_u64 v[220:221], v[10:11], 0, v[56:57]
	v_lshl_add_u64 v[10:11], v[10:11], 0, v[58:59]
	global_load_dwordx4 v[92:95], v[20:21], off
	global_load_dwordx4 v[80:83], v[8:9], off
	global_load_dwordx4 v[68:71], v[22:23], off
	global_load_dwordx4 v[56:59], v[32:33], off
	global_load_dwordx4 v[44:47], v[34:35], off
	s_nop 0
	global_load_dwordx4 v[32:35], v[216:217], off
	global_load_dwordx4 v[20:23], v[220:221], off
	s_nop 0
	global_load_dwordx4 v[8:11], v[10:11], off
	v_lshlrev_b64 v[182:183], 10, v[182:183]
	s_add_i32 s74, s74, s50
	s_waitcnt vmcnt(0)
	v_mul_f32_e32 v212, 0xbfb8aa3b, v212
	v_exp_f32_e32 v212, v212
	v_mul_f32_e32 v213, 0xbfb8aa3b, v213
	v_mul_f32_e32 v214, 0xbfb8aa3b, v214
	v_exp_f32_e32 v213, v213
	v_mul_f32_e32 v215, 0xbfb8aa3b, v215
	v_exp_f32_e32 v214, v214
	v_add_f32_e32 v212, 1.0, v212
	v_exp_f32_e32 v215, v215
	v_cmp_gt_f32_e32 vcc, s77, v212
	v_add_f32_e32 v213, 1.0, v213
	v_add_f32_e32 v214, 1.0, v214
	v_cndmask_b32_e64 v216, 0, 32, vcc
	v_ldexp_f32 v212, v212, v216
	v_cmp_gt_f32_e64 s[12:13], s77, v213
	v_log_f32_e32 v212, v212
	v_add_f32_e32 v215, 1.0, v215
	v_cndmask_b32_e64 v217, 0, 32, s[12:13]
	v_cmp_gt_f32_e64 s[14:15], s77, v214
	v_cmp_gt_f32_e64 s[16:17], s77, v215
	v_ldexp_f32 v213, v213, v217
	v_cndmask_b32_e64 v218, 0, 32, s[14:15]
	v_cndmask_b32_e64 v220, 0, 32, s[16:17]
	v_ldexp_f32 v214, v214, v218
	v_log_f32_e32 v213, v213
	v_ldexp_f32 v215, v215, v220
	v_log_f32_e32 v214, v214
	v_mul_f32_e32 v220, 0x3f317217, v212
	v_log_f32_e32 v215, v215
	v_fma_f32 v220, v212, s78, -v220
	v_fmac_f32_e32 v220, 0x3377d1cf, v212
	v_add_f32_e32 v160, v160, v108
	v_add_f32_e32 v161, v161, v109
	v_cndmask_b32_e32 v216, 0, v210, vcc
	v_mul_f32_e32 v221, 0x3f317217, v213
	v_fmac_f32_e32 v220, 0x3f317217, v212
	v_cmp_lt_f32_e64 vcc, |v212|, s79
	v_mul_f32_e32 v160, 0xbfb8aa3b, v160
	v_mul_f32_e32 v161, 0xbfb8aa3b, v161
	v_add_f32_e32 v162, v162, v110
	v_mul_f32_e32 v222, 0x3f317217, v214
	v_fma_f32 v221, v213, s78, -v221
	v_cndmask_b32_e32 v212, v212, v220, vcc
	v_exp_f32_e32 v160, v160
	v_exp_f32_e32 v161, v161
	v_mul_f32_e32 v162, 0xbfb8aa3b, v162
	v_add_f32_e32 v166, v166, v106
	v_fma_f32 v222, v214, s78, -v222
	v_fmac_f32_e32 v221, 0x3377d1cf, v213
	v_sub_f32_e32 v212, v212, v216
	v_mul_f32_e32 v216, 0x3f317217, v215
	v_exp_f32_e32 v162, v162
	v_mul_f32_e32 v166, 0xbfb8aa3b, v166
	v_add_f32_e32 v163, v163, v111
	v_fmac_f32_e32 v222, 0x3377d1cf, v214
	v_fmac_f32_e32 v221, 0x3f317217, v213
	v_cmp_lt_f32_e64 vcc, |v213|, s79
	v_fma_f32 v216, v215, s78, -v216
	v_exp_f32_e32 v166, v166
	v_mul_f32_e32 v163, 0xbfb8aa3b, v163
	v_fmac_f32_e32 v222, 0x3f317217, v214
	v_cndmask_b32_e32 v213, v213, v221, vcc
	v_cmp_lt_f32_e64 vcc, |v214|, s79
	v_fmac_f32_e32 v216, 0x3377d1cf, v215
	v_exp_f32_e32 v163, v163
	v_cndmask_b32_e32 v214, v214, v222, vcc
	v_fmac_f32_e32 v216, 0x3f317217, v215
	v_cmp_lt_f32_e64 vcc, |v215|, s79
	v_add_f32_e32 v160, 1.0, v160
	v_add_f32_e32 v161, 1.0, v161
	v_cndmask_b32_e32 v215, v215, v216, vcc
	v_cndmask_b32_e64 v216, 0, v210, s[16:17]
	v_rcp_f32_e32 v160, v160
	v_rcp_f32_e32 v161, v161
	v_add_f32_e32 v162, 1.0, v162
	v_cndmask_b32_e64 v217, 0, v210, s[12:13]
	v_sub_f32_e32 v215, v215, v216
	v_rcp_f32_e32 v216, v162
	v_add_f32_e32 v162, 1.0, v166
	v_sub_f32_e32 v213, v213, v217
	v_rcp_f32_e32 v166, v162
	v_add_f32_e32 v162, 1.0, v163
	v_rcp_f32_e32 v217, v162
	v_pk_mul_f32 v[162:163], v[212:213], s[34:35] op_sel_hi:[1,0]
	v_cndmask_b32_e64 v218, 0, v210, s[14:15]
	v_pk_mul_f32 v[212:213], v[160:161], v[162:163]
	v_add_f32_e32 v161, v167, v107
	v_add_f32_e32 v160, v212, v212
	v_mul_f32_e32 v160, 0x3fb8aa3b, v160
	v_exp_f32_e32 v160, v160
	v_mul_f32_e32 v161, 0xbfb8aa3b, v161
	v_exp_f32_e32 v161, v161
	v_sub_f32_e32 v214, v214, v218
	v_sub_f32_e32 v160, 1.0, v160
	v_add_f32_e32 v161, 1.0, v161
	v_add_f32_e32 v223, v213, v213
	v_sqrt_f32_e32 v218, v160
	v_rcp_f32_e32 v167, v161
	v_mul_f32_e32 v223, 0x3fb8aa3b, v223
	v_exp_f32_e32 v223, v223
	v_add_u32_e32 v161, -1, v218
	v_fma_f32 v222, -v161, v218, v160
	v_cmp_ge_f32_e64 s[12:13], 0, v222
	v_add_u32_e32 v222, 1, v218
	v_cvt_pk_bf16_f32 v212, v212, v213
	v_cndmask_b32_e64 v161, v218, v161, s[12:13]
	v_fma_f32 v218, -v222, v218, v160
; __device__ __forceinline__ float bflo(unsigned w) { return __uint_as_float(w << 16); }
; __device__ __forceinline__ float bfhi(unsigned w) { return __uint_as_float(w & 0xffff0000u); }
; __device__ __forceinline__ float sigmoidf_(float x) { return __builtin_amdgcn_rcpf(1.0f + __expf(-x)); }
;     __device__ __forceinline__ void operator()(AccRef acc, const Unit& u, int wr, int wc, int fr, int fq) const {
;     ...
;                 for (int m = 0; m < 4; ++m) { const size_t off = (size_t)(row0 + ai * 128 + m * 16) * D + col0 + 4 * n;
;                     float lo[4], bo[4];
; #pragma unroll
;                     for (int j = 0; j < 4; ++j) { const unsigned w = rws[ai][m][2 * n + (j >> 1)]; const float rec = (j & 1) ? bfhi(w) : bflo(w);
;                         const float r = sigmoidf_(acc[ai][0][m][n][j] + ba[j]), ig = sigmoidf_(acc[ai][1][m][n][j] + bx[j]);
;                         const float la = k8[j] * r; const float mult = __builtin_sqrtf(1.0f - __expf(2.0f * la));
;                         lo[j] = la; bo[j] = mult * ig * rec; }
;                     *(u32x2*)(LA + off) = (u32x2){cvt_pk_bf16(lo[0], lo[1]), cvt_pk_bf16(lo[2], lo[3])}; *(u32x2*)(BV + off) = (u32x2){cvt_pk_bf16(bo[0], bo[1]), cvt_pk_bf16(bo[2], bo[3])}; }
	v_cmp_lt_f32_e64 s[12:13], 0, v218
	v_add_f32_e32 v164, v164, v104
	v_add_f32_e32 v165, v165, v105
	v_cndmask_b32_e64 v161, v161, v222, s[12:13]
	v_sub_f32_e32 v222, 1.0, v223
	v_mov_b32_e32 v223, v222
	v_sqrt_f32_e32 v224, v223
	v_mul_f32_e32 v164, 0xbfb8aa3b, v164
	v_mul_f32_e32 v165, 0xbfb8aa3b, v165
	v_mov_b32_e32 v222, v161
	v_add_u32_e32 v160, -1, v224
	v_fma_f32 v161, -v160, v224, v223
	v_cmp_ge_f32_e32 vcc, 0, v161
	v_add_u32_e32 v225, 1, v224
	v_exp_f32_e32 v164, v164
	v_cndmask_b32_e32 v218, v224, v160, vcc
	v_pk_mul_f32 v[160:161], v[214:215], s[34:35] op_sel_hi:[1,0]
	v_fma_f32 v224, -v225, v224, v223
	v_pk_mul_f32 v[214:215], v[216:217], v[160:161]
	v_cmp_lt_f32_e32 vcc, 0, v224
	v_add_f32_e32 v216, v214, v214
	v_mul_f32_e32 v216, 0x3fb8aa3b, v216
	v_exp_f32_e32 v216, v216
	v_cndmask_b32_e32 v217, v218, v225, vcc
	v_sub_f32_e32 v216, 1.0, v216
	v_add_f32_e32 v224, v215, v215
	v_mul_f32_e32 v224, 0x3fb8aa3b, v224
	v_sqrt_f32_e32 v218, v216
	v_exp_f32_e32 v224, v224
	v_exp_f32_e32 v165, v165
	v_add_u32_e32 v213, -1, v218
	v_mov_b32_e32 v223, v217
	v_fma_f32 v217, -v213, v218, v216
	v_cmp_ge_f32_e64 s[12:13], 0, v217
	v_add_u32_e32 v217, 1, v218
	v_add_f32_e32 v164, 1.0, v164
	v_cndmask_b32_e64 v213, v218, v213, s[12:13]
	v_fma_f32 v218, -v217, v218, v216
	v_cmp_lt_f32_e64 s[12:13], 0, v218
	v_sub_f32_e32 v218, 1.0, v224
	s_nop 0
	v_cndmask_b32_e64 v213, v213, v217, s[12:13]
	v_sqrt_f32_e32 v224, v218
	v_add_f32_e32 v165, 1.0, v165
	v_rcp_f32_e32 v164, v164
	v_mov_b32_e32 v216, v213
	v_add_u32_e32 v213, -1, v224
	v_fma_f32 v217, -v213, v224, v218
	v_cmp_ge_f32_e32 vcc, 0, v217
	v_add_u32_e32 v217, 1, v224
	v_rcp_f32_e32 v165, v165
	v_cndmask_b32_e32 v213, v224, v213, vcc
	v_fma_f32 v224, -v217, v224, v218
	v_cmp_lt_f32_e32 vcc, 0, v224
	v_add_f32_e32 v152, v152, v108
	v_lshl_add_u64 v[220:221], v[182:183], 0, v[180:181]
	v_cndmask_b32_e32 v213, v213, v217, vcc
	v_mul_f32_e32 v152, 0xbfb8aa3b, v152
	v_exp_f32_e32 v152, v152
	v_mov_b32_e32 v217, v213
	v_cvt_pk_bf16_f32 v213, v214, v215
	v_lshlrev_b64 v[214:215], 1, v[220:221]
	v_lshl_add_u64 v[220:221], s[70:71], 0, v[214:215]
	v_mov_b32_e32 v211, v212
	v_mov_b32_e32 v218, v213
	v_lshlrev_b32_e32 v212, 16, v92
	v_and_b32_e32 v213, 0xffff0000, v92
	v_pk_mul_f32 v[164:165], v[164:165], v[222:223]
	v_pk_mul_f32 v[166:167], v[166:167], v[216:217]
	v_pk_mul_f32 v[164:165], v[164:165], v[212:213]
	v_add_f32_e32 v153, v153, v109
	v_cvt_pk_bf16_f32 v92, v164, v165
	v_lshlrev_b32_e32 v164, 16, v93
	v_and_b32_e32 v165, 0xffff0000, v93
	v_add_f32_e32 v93, 1.0, v152
	v_rcp_f32_e32 v152, v93
	v_pk_mul_f32 v[164:165], v[166:167], v[164:165]
	v_mul_f32_e32 v153, 0xbfb8aa3b, v153
	v_cvt_pk_bf16_f32 v93, v164, v165
	v_lshl_add_u64 v[164:165], s[68:69], 0, v[214:215]
	v_mul_f32_e32 v166, v152, v162
	v_mov_b32_e32 v224, v92
	v_mov_b32_e32 v225, v93
	v_add_f32_e32 v92, v166, v166
	v_mul_f32_e32 v92, 0x3fb8aa3b, v92
	v_exp_f32_e32 v92, v92
	v_add_f32_e32 v93, v156, v104
	v_mul_f32_e32 v93, 0xbfb8aa3b, v93
	v_exp_f32_e32 v152, v93
	v_sub_f32_e32 v92, 1.0, v92
	v_exp_f32_e32 v153, v153
	v_add_f32_e32 v154, v154, v110
	v_mov_b32_e32 v156, v92
	v_sqrt_f32_e32 v164, v156
	v_add_f32_e32 v153, 1.0, v153
	v_rcp_f32_e32 v153, v153
	v_add_f32_e32 v157, v157, v105
	v_add_u32_e32 v165, -1, v164
	v_fma_f32 v167, -v165, v164, v156
	v_cmp_ge_f32_e64 s[12:13], 0, v167
	v_add_u32_e32 v167, 1, v164
	v_mul_f32_e32 v154, 0xbfb8aa3b, v154
	v_cndmask_b32_e64 v165, v164, v165, s[12:13]
	v_fma_f32 v164, -v167, v164, v156
	v_cmp_lt_f32_e64 s[12:13], 0, v164
	v_mul_f32_e32 v157, 0xbfb8aa3b, v157
	v_exp_f32_e32 v154, v154
	v_cndmask_b32_e64 v164, v165, v167, s[12:13]
	v_mul_f32_e32 v167, v153, v163
	v_add_f32_e32 v153, v167, v167
	v_mul_f32_e32 v153, 0x3fb8aa3b, v153
	v_exp_f32_e32 v153, v153
	v_lshlrev_b64 v[92:93], 10, v[202:203]
	v_sub_f32_e32 v153, 1.0, v153
	v_exp_f32_e32 v157, v157
	v_add_f32_e32 v154, 1.0, v154
	v_mov_b32_e32 v165, v153
	v_sqrt_f32_e32 v202, v165
	v_add_f32_e32 v153, 1.0, v157
	v_rcp_f32_e32 v154, v154
	v_add_u32_e32 v157, -1, v202
	v_mov_b32_e32 v156, v164
	v_fma_f32 v164, -v157, v202, v165
	v_cmp_ge_f32_e64 s[12:13], 0, v164
	v_add_u32_e32 v164, 1, v202
	v_add_f32_e32 v155, v155, v111
	v_cndmask_b32_e64 v157, v202, v157, s[12:13]
	v_fma_f32 v202, -v164, v202, v165
	v_cmp_lt_f32_e64 s[12:13], 0, v202
	v_mul_f32_e32 v202, v154, v160
	v_add_f32_e32 v154, v202, v202
	v_mul_f32_e32 v154, 0x3fb8aa3b, v154
	v_exp_f32_e32 v154, v154
	v_cndmask_b32_e64 v157, v157, v164, s[12:13]
	v_sub_f32_e32 v154, 1.0, v154
	v_add_f32_e32 v158, v158, v106
	v_mul_f32_e32 v155, 0xbfb8aa3b, v155
	v_mul_f32_e32 v158, 0xbfb8aa3b, v158
	v_mov_b32_e32 v164, v154
	v_exp_f32_e32 v155, v155
	v_exp_f32_e32 v158, v158
	v_sqrt_f32_e32 v203, v164
	v_add_f32_e32 v155, 1.0, v155
	v_add_f32_e32 v154, 1.0, v158
	v_add_u32_e32 v158, -1, v203
	v_rcp_f32_e32 v155, v155
	v_fma_f32 v165, -v158, v203, v164
	v_cmp_ge_f32_e64 s[12:13], 0, v165
	v_add_u32_e32 v165, 1, v203
	v_add_f32_e32 v159, v159, v107
	v_cndmask_b32_e64 v158, v203, v158, s[12:13]
	v_fma_f32 v203, -v165, v203, v164
	v_cmp_lt_f32_e64 s[12:13], 0, v203
	v_mul_f32_e32 v203, v155, v161
	v_add_f32_e32 v155, v203, v203
	v_mul_f32_e32 v155, 0x3fb8aa3b, v155
	v_exp_f32_e32 v155, v155
	v_cndmask_b32_e64 v158, v158, v165, s[12:13]
	v_sub_f32_e32 v155, 1.0, v155
	v_mul_f32_e32 v159, 0xbfb8aa3b, v159
	v_exp_f32_e32 v159, v159
	v_mov_b32_e32 v165, v155
	v_sqrt_f32_e32 v212, v165
	v_add_f32_e32 v155, 1.0, v159
	v_add_f32_e32 v152, 1.0, v152
	v_add_u32_e32 v159, -1, v212
	v_fma_f32 v164, -v159, v212, v165
	v_cmp_ge_f32_e64 s[12:13], 0, v164
	v_add_u32_e32 v164, 1, v212
	v_rcp_f32_e32 v152, v152
; __device__ __forceinline__ float bflo(unsigned w) { return __uint_as_float(w << 16); }
; __device__ __forceinline__ float bfhi(unsigned w) { return __uint_as_float(w & 0xffff0000u); }
; __device__ __forceinline__ float sigmoidf_(float x) { return __builtin_amdgcn_rcpf(1.0f + __expf(-x)); }
;     __device__ __forceinline__ void operator()(AccRef acc, const Unit& u, int wr, int wc, int fr, int fq) const {
;     ...
;                 for (int m = 0; m < 4; ++m) { const size_t off = (size_t)(row0 + ai * 128 + m * 16) * D + col0 + 4 * n;
;                     float lo[4], bo[4];
; #pragma unroll
;                     for (int j = 0; j < 4; ++j) { const unsigned w = rws[ai][m][2 * n + (j >> 1)]; const float rec = (j & 1) ? bfhi(w) : bflo(w);
;                         const float r = sigmoidf_(acc[ai][0][m][n][j] + ba[j]), ig = sigmoidf_(acc[ai][1][m][n][j] + bx[j]);
;                         const float la = k8[j] * r; const float mult = __builtin_sqrtf(1.0f - __expf(2.0f * la));
;                         lo[j] = la; bo[j] = mult * ig * rec; }
;                     *(u32x2*)(LA + off) = (u32x2){cvt_pk_bf16(lo[0], lo[1]), cvt_pk_bf16(lo[2], lo[3])}; *(u32x2*)(BV + off) = (u32x2){cvt_pk_bf16(bo[0], bo[1]), cvt_pk_bf16(bo[2], bo[3])}; }
	v_cndmask_b32_e64 v159, v212, v159, s[12:13]
	v_fma_f32 v212, -v164, v212, v165
	v_cmp_lt_f32_e64 s[12:13], 0, v212
	v_rcp_f32_e32 v153, v153
	v_add_f32_e32 v144, v144, v108
	v_cndmask_b32_e64 v159, v159, v164, s[12:13]
	v_mul_f32_e32 v144, 0xbfb8aa3b, v144
	v_exp_f32_e32 v144, v144
	v_lshl_add_u64 v[164:165], v[92:93], 0, v[180:181]
	v_lshlrev_b64 v[164:165], 1, v[164:165]
	v_cvt_pk_bf16_f32 v166, v166, v167
	v_cvt_pk_bf16_f32 v167, v202, v203
	v_lshl_add_u64 v[202:203], s[70:71], 0, v[164:165]
	v_mov_b32_e32 v226, v166
	v_mov_b32_e32 v227, v167
	v_lshlrev_b32_e32 v166, 16, v80
	v_and_b32_e32 v167, 0xffff0000, v80
	v_pk_mul_f32 v[152:153], v[152:153], v[156:157]
	v_rcp_f32_e32 v154, v154
	v_rcp_f32_e32 v155, v155
	v_pk_mul_f32 v[152:153], v[152:153], v[166:167]
	v_add_f32_e32 v145, v145, v109
	v_cvt_pk_bf16_f32 v80, v152, v153
	v_lshlrev_b32_e32 v152, 16, v81
	v_and_b32_e32 v153, 0xffff0000, v81
	v_add_f32_e32 v81, 1.0, v144
	v_rcp_f32_e32 v144, v81
	v_pk_mul_f32 v[154:155], v[154:155], v[158:159]
	v_mul_f32_e32 v145, 0xbfb8aa3b, v145
	v_pk_mul_f32 v[152:153], v[154:155], v[152:153]
	v_mul_f32_e32 v154, v144, v162
	v_cvt_pk_bf16_f32 v81, v152, v153
	v_lshl_add_u64 v[152:153], s[68:69], 0, v[164:165]
	v_mov_b32_e32 v228, v80
	v_mov_b32_e32 v229, v81
	v_add_f32_e32 v80, v154, v154
	v_mul_f32_e32 v80, 0x3fb8aa3b, v80
	v_exp_f32_e32 v80, v80
	v_add_f32_e32 v81, v148, v104
	v_mul_f32_e32 v81, 0xbfb8aa3b, v81
	v_exp_f32_e32 v144, v81
	v_sub_f32_e32 v80, 1.0, v80
	v_exp_f32_e32 v145, v145
	v_add_f32_e32 v146, v146, v110
	v_mov_b32_e32 v148, v80
	v_sqrt_f32_e32 v152, v148
	v_add_f32_e32 v145, 1.0, v145
	v_rcp_f32_e32 v145, v145
	v_add_f32_e32 v149, v149, v105
	v_add_u32_e32 v153, -1, v152
	v_fma_f32 v155, -v153, v152, v148
	v_cmp_ge_f32_e64 s[12:13], 0, v155
	v_add_u32_e32 v155, 1, v152
	v_mul_f32_e32 v146, 0xbfb8aa3b, v146
	v_cndmask_b32_e64 v153, v152, v153, s[12:13]
	v_fma_f32 v152, -v155, v152, v148
	v_cmp_lt_f32_e64 s[12:13], 0, v152
	v_mul_f32_e32 v149, 0xbfb8aa3b, v149
	v_exp_f32_e32 v146, v146
	v_cndmask_b32_e64 v152, v153, v155, s[12:13]
	v_mul_f32_e32 v155, v145, v163
	v_add_f32_e32 v145, v155, v155
	v_mul_f32_e32 v145, 0x3fb8aa3b, v145
	v_exp_f32_e32 v145, v145
	v_exp_f32_e32 v149, v149
	v_sub_f32_e32 v145, 1.0, v145
	v_add_f32_e32 v146, 1.0, v146
	v_mov_b32_e32 v153, v145
	v_sqrt_f32_e32 v156, v153
	v_add_f32_e32 v145, 1.0, v149
	v_rcp_f32_e32 v146, v146
	v_mov_b32_e32 v148, v152
	v_add_u32_e32 v149, -1, v156
	v_fma_f32 v152, -v149, v156, v153
	v_cmp_ge_f32_e64 s[12:13], 0, v152
	v_add_u32_e32 v152, 1, v156
	v_add_f32_e32 v147, v147, v111
	v_cndmask_b32_e64 v149, v156, v149, s[12:13]
	v_fma_f32 v156, -v152, v156, v153
	v_cmp_lt_f32_e64 s[12:13], 0, v156
	v_mul_f32_e32 v156, v146, v160
	v_add_f32_e32 v146, v156, v156
	v_mul_f32_e32 v146, 0x3fb8aa3b, v146
	v_exp_f32_e32 v146, v146
	v_cndmask_b32_e64 v149, v149, v152, s[12:13]
	v_sub_f32_e32 v146, 1.0, v146
	v_add_f32_e32 v150, v150, v106
	v_mul_f32_e32 v147, 0xbfb8aa3b, v147
	v_mul_f32_e32 v150, 0xbfb8aa3b, v150
	v_mov_b32_e32 v152, v146
	v_exp_f32_e32 v147, v147
	v_exp_f32_e32 v150, v150
	v_sqrt_f32_e32 v157, v152
	v_add_f32_e32 v147, 1.0, v147
	v_add_f32_e32 v146, 1.0, v150
	v_add_u32_e32 v150, -1, v157
	v_rcp_f32_e32 v147, v147
	v_fma_f32 v153, -v150, v157, v152
	v_cmp_ge_f32_e64 s[12:13], 0, v153
	v_add_u32_e32 v153, 1, v157
	v_add_f32_e32 v151, v151, v107
	v_cndmask_b32_e64 v150, v157, v150, s[12:13]
	v_fma_f32 v157, -v153, v157, v152
	v_cmp_lt_f32_e64 s[12:13], 0, v157
	v_mul_f32_e32 v157, v147, v161
	v_add_f32_e32 v147, v157, v157
	v_mul_f32_e32 v147, 0x3fb8aa3b, v147
	v_exp_f32_e32 v147, v147
	v_cndmask_b32_e64 v150, v150, v153, s[12:13]
	v_sub_f32_e32 v147, 1.0, v147
	v_mul_f32_e32 v151, 0xbfb8aa3b, v151
	v_exp_f32_e32 v151, v151
	v_mov_b32_e32 v153, v147
	v_sqrt_f32_e32 v158, v153
	v_add_f32_e32 v147, 1.0, v151
	v_add_f32_e32 v144, 1.0, v144
	v_add_u32_e32 v151, -1, v158
	v_fma_f32 v152, -v151, v158, v153
	v_cmp_ge_f32_e64 s[12:13], 0, v152
	v_add_u32_e32 v152, 1, v158
	v_lshlrev_b64 v[80:81], 10, v[200:201]
	v_cndmask_b32_e64 v151, v158, v151, s[12:13]
	v_fma_f32 v158, -v152, v158, v153
	v_cmp_lt_f32_e64 s[12:13], 0, v158
	v_rcp_f32_e32 v144, v144
	v_rcp_f32_e32 v145, v145
	v_cndmask_b32_e64 v151, v151, v152, s[12:13]
	v_add_f32_e32 v136, v136, v108
	v_mul_f32_e32 v136, 0xbfb8aa3b, v136
	v_lshl_add_u64 v[152:153], v[80:81], 0, v[180:181]
	v_lshlrev_b64 v[152:153], 1, v[152:153]
	v_exp_f32_e32 v136, v136
	v_cvt_pk_bf16_f32 v154, v154, v155
	v_cvt_pk_bf16_f32 v155, v156, v157
	v_lshl_add_u64 v[156:157], s[70:71], 0, v[152:153]
	v_mov_b32_e32 v230, v154
	v_mov_b32_e32 v231, v155
	v_lshlrev_b32_e32 v154, 16, v68
	v_and_b32_e32 v155, 0xffff0000, v68
	v_pk_mul_f32 v[144:145], v[144:145], v[148:149]
	v_rcp_f32_e32 v146, v146
	v_rcp_f32_e32 v147, v147
	v_pk_mul_f32 v[144:145], v[144:145], v[154:155]
	v_add_f32_e32 v137, v137, v109
	v_cvt_pk_bf16_f32 v68, v144, v145
	v_lshlrev_b32_e32 v144, 16, v69
	v_and_b32_e32 v145, 0xffff0000, v69
	v_add_f32_e32 v69, 1.0, v136
	v_rcp_f32_e32 v136, v69
	v_pk_mul_f32 v[146:147], v[146:147], v[150:151]
	v_mul_f32_e32 v137, 0xbfb8aa3b, v137
	v_pk_mul_f32 v[144:145], v[146:147], v[144:145]
	v_mul_f32_e32 v146, v136, v162
	v_cvt_pk_bf16_f32 v69, v144, v145
	v_lshl_add_u64 v[144:145], s[68:69], 0, v[152:153]
	v_mov_b32_e32 v232, v68
	v_mov_b32_e32 v233, v69
	v_add_f32_e32 v68, v146, v146
	v_mul_f32_e32 v68, 0x3fb8aa3b, v68
	v_exp_f32_e32 v68, v68
	v_add_f32_e32 v69, v140, v104
	v_mul_f32_e32 v69, 0xbfb8aa3b, v69
	v_exp_f32_e32 v136, v69
	v_sub_f32_e32 v68, 1.0, v68
	v_exp_f32_e32 v137, v137
	v_add_f32_e32 v138, v138, v110
	v_mov_b32_e32 v140, v68
; __device__ __forceinline__ float bflo(unsigned w) { return __uint_as_float(w << 16); }
; __device__ __forceinline__ float bfhi(unsigned w) { return __uint_as_float(w & 0xffff0000u); }
; __device__ __forceinline__ float sigmoidf_(float x) { return __builtin_amdgcn_rcpf(1.0f + __expf(-x)); }
;     __device__ __forceinline__ void operator()(AccRef acc, const Unit& u, int wr, int wc, int fr, int fq) const {
;     ...
;                 for (int m = 0; m < 4; ++m) { const size_t off = (size_t)(row0 + ai * 128 + m * 16) * D + col0 + 4 * n;
;                     float lo[4], bo[4];
; #pragma unroll
;                     for (int j = 0; j < 4; ++j) { const unsigned w = rws[ai][m][2 * n + (j >> 1)]; const float rec = (j & 1) ? bfhi(w) : bflo(w);
;                         const float r = sigmoidf_(acc[ai][0][m][n][j] + ba[j]), ig = sigmoidf_(acc[ai][1][m][n][j] + bx[j]);
;                         const float la = k8[j] * r; const float mult = __builtin_sqrtf(1.0f - __expf(2.0f * la));
;                         lo[j] = la; bo[j] = mult * ig * rec; }
;                     *(u32x2*)(LA + off) = (u32x2){cvt_pk_bf16(lo[0], lo[1]), cvt_pk_bf16(lo[2], lo[3])}; *(u32x2*)(BV + off) = (u32x2){cvt_pk_bf16(bo[0], bo[1]), cvt_pk_bf16(bo[2], bo[3])}; }
	v_sqrt_f32_e32 v144, v140
	v_add_f32_e32 v137, 1.0, v137
	v_rcp_f32_e32 v137, v137
	v_add_f32_e32 v141, v141, v105
	v_add_u32_e32 v145, -1, v144
	v_fma_f32 v147, -v145, v144, v140
	v_cmp_ge_f32_e64 s[12:13], 0, v147
	v_add_u32_e32 v147, 1, v144
	v_mul_f32_e32 v138, 0xbfb8aa3b, v138
	v_cndmask_b32_e64 v145, v144, v145, s[12:13]
	v_fma_f32 v144, -v147, v144, v140
	v_cmp_lt_f32_e64 s[12:13], 0, v144
	v_mul_f32_e32 v141, 0xbfb8aa3b, v141
	v_exp_f32_e32 v138, v138
	v_cndmask_b32_e64 v144, v145, v147, s[12:13]
	v_mul_f32_e32 v147, v137, v163
	v_add_f32_e32 v137, v147, v147
	v_mul_f32_e32 v137, 0x3fb8aa3b, v137
	v_exp_f32_e32 v137, v137
	v_exp_f32_e32 v141, v141
	v_sub_f32_e32 v137, 1.0, v137
	v_add_f32_e32 v138, 1.0, v138
	v_mov_b32_e32 v145, v137
	v_sqrt_f32_e32 v148, v145
	v_add_f32_e32 v137, 1.0, v141
	v_rcp_f32_e32 v138, v138
	v_mov_b32_e32 v140, v144
	v_add_u32_e32 v141, -1, v148
	v_fma_f32 v144, -v141, v148, v145
	v_cmp_ge_f32_e64 s[12:13], 0, v144
	v_add_u32_e32 v144, 1, v148
	v_add_f32_e32 v139, v139, v111
	v_cndmask_b32_e64 v141, v148, v141, s[12:13]
	v_fma_f32 v148, -v144, v148, v145
	v_cmp_lt_f32_e64 s[12:13], 0, v148
	v_mul_f32_e32 v148, v138, v160
	v_add_f32_e32 v138, v148, v148
	v_mul_f32_e32 v138, 0x3fb8aa3b, v138
	v_exp_f32_e32 v138, v138
	v_cndmask_b32_e64 v141, v141, v144, s[12:13]
	v_sub_f32_e32 v138, 1.0, v138
	v_add_f32_e32 v142, v142, v106
	v_mul_f32_e32 v139, 0xbfb8aa3b, v139
	v_mul_f32_e32 v142, 0xbfb8aa3b, v142
	v_mov_b32_e32 v144, v138
	v_exp_f32_e32 v139, v139
	v_exp_f32_e32 v142, v142
	v_sqrt_f32_e32 v149, v144
	v_add_f32_e32 v139, 1.0, v139
	v_add_f32_e32 v138, 1.0, v142
	v_add_u32_e32 v142, -1, v149
	v_rcp_f32_e32 v139, v139
	v_fma_f32 v145, -v142, v149, v144
	v_cmp_ge_f32_e64 s[12:13], 0, v145
	v_add_u32_e32 v145, 1, v149
	v_add_f32_e32 v143, v143, v107
	v_cndmask_b32_e64 v142, v149, v142, s[12:13]
	v_fma_f32 v149, -v145, v149, v144
	v_cmp_lt_f32_e64 s[12:13], 0, v149
	v_mul_f32_e32 v149, v139, v161
	v_add_f32_e32 v139, v149, v149
	v_mul_f32_e32 v139, 0x3fb8aa3b, v139
	v_exp_f32_e32 v139, v139
	v_cndmask_b32_e64 v142, v142, v145, s[12:13]
	v_sub_f32_e32 v139, 1.0, v139
	v_mul_f32_e32 v143, 0xbfb8aa3b, v143
	v_exp_f32_e32 v143, v143
	v_mov_b32_e32 v145, v139
	v_sqrt_f32_e32 v150, v145
	v_add_f32_e32 v139, 1.0, v143
	v_add_f32_e32 v136, 1.0, v136
	v_add_u32_e32 v143, -1, v150
	v_fma_f32 v144, -v143, v150, v145
	v_cmp_ge_f32_e64 s[12:13], 0, v144
	v_add_u32_e32 v144, 1, v150
	v_lshlrev_b64 v[68:69], 10, v[198:199]
	v_cndmask_b32_e64 v143, v150, v143, s[12:13]
	v_fma_f32 v150, -v144, v150, v145
	v_cmp_lt_f32_e64 s[12:13], 0, v150
	v_rcp_f32_e32 v136, v136
	v_rcp_f32_e32 v137, v137
	v_cndmask_b32_e64 v143, v143, v144, s[12:13]
	v_add_f32_e32 v128, v128, v108
	v_mul_f32_e32 v128, 0xbfb8aa3b, v128
	v_lshl_add_u64 v[144:145], v[68:69], 0, v[180:181]
	v_lshlrev_b64 v[144:145], 1, v[144:145]
	v_exp_f32_e32 v128, v128
	v_cvt_pk_bf16_f32 v146, v146, v147
	v_cvt_pk_bf16_f32 v147, v148, v149
	v_lshl_add_u64 v[148:149], s[70:71], 0, v[144:145]
	v_mov_b32_e32 v235, v146
	v_mov_b32_e32 v236, v147
	v_lshlrev_b32_e32 v146, 16, v56
	v_and_b32_e32 v147, 0xffff0000, v56
	v_pk_mul_f32 v[136:137], v[136:137], v[140:141]
	v_rcp_f32_e32 v138, v138
	v_rcp_f32_e32 v139, v139
	v_pk_mul_f32 v[136:137], v[136:137], v[146:147]
	v_add_f32_e32 v129, v129, v109
	v_cvt_pk_bf16_f32 v56, v136, v137
	v_lshlrev_b32_e32 v136, 16, v57
	v_and_b32_e32 v137, 0xffff0000, v57
	v_add_f32_e32 v57, 1.0, v128
	v_rcp_f32_e32 v128, v57
	v_pk_mul_f32 v[138:139], v[138:139], v[142:143]
	v_mul_f32_e32 v129, 0xbfb8aa3b, v129
	v_pk_mul_f32 v[136:137], v[138:139], v[136:137]
	v_mul_f32_e32 v138, v128, v162
	v_cvt_pk_bf16_f32 v57, v136, v137
	v_lshl_add_u64 v[136:137], s[68:69], 0, v[144:145]
	v_mov_b32_e32 v237, v56
	v_mov_b32_e32 v238, v57
	v_add_f32_e32 v56, v138, v138
	v_mul_f32_e32 v56, 0x3fb8aa3b, v56
	v_exp_f32_e32 v56, v56
	v_add_f32_e32 v57, v132, v104
	v_mul_f32_e32 v57, 0xbfb8aa3b, v57
	v_exp_f32_e32 v128, v57
	v_sub_f32_e32 v56, 1.0, v56
	v_exp_f32_e32 v129, v129
	v_add_f32_e32 v130, v130, v110
	v_mov_b32_e32 v132, v56
	v_sqrt_f32_e32 v136, v132
	v_add_f32_e32 v129, 1.0, v129
	v_rcp_f32_e32 v129, v129
	v_add_f32_e32 v133, v133, v105
	v_add_u32_e32 v137, -1, v136
	v_fma_f32 v139, -v137, v136, v132
	v_cmp_ge_f32_e64 s[12:13], 0, v139
	v_add_u32_e32 v139, 1, v136
	v_mul_f32_e32 v130, 0xbfb8aa3b, v130
	v_cndmask_b32_e64 v137, v136, v137, s[12:13]
	v_fma_f32 v136, -v139, v136, v132
	v_cmp_lt_f32_e64 s[12:13], 0, v136
	v_mul_f32_e32 v133, 0xbfb8aa3b, v133
	v_exp_f32_e32 v130, v130
	v_cndmask_b32_e64 v136, v137, v139, s[12:13]
	v_mul_f32_e32 v139, v129, v163
	v_add_f32_e32 v129, v139, v139
	v_mul_f32_e32 v129, 0x3fb8aa3b, v129
	v_exp_f32_e32 v129, v129
	v_exp_f32_e32 v133, v133
	v_sub_f32_e32 v129, 1.0, v129
	v_add_f32_e32 v130, 1.0, v130
	v_mov_b32_e32 v137, v129
	v_sqrt_f32_e32 v140, v137
	v_add_f32_e32 v129, 1.0, v133
	v_rcp_f32_e32 v130, v130
	v_mov_b32_e32 v132, v136
	v_add_u32_e32 v133, -1, v140
	v_fma_f32 v136, -v133, v140, v137
	v_cmp_ge_f32_e64 s[12:13], 0, v136
	v_add_u32_e32 v136, 1, v140
	v_add_f32_e32 v131, v131, v111
	v_cndmask_b32_e64 v133, v140, v133, s[12:13]
	v_fma_f32 v140, -v136, v140, v137
	v_cmp_lt_f32_e64 s[12:13], 0, v140
	v_mul_f32_e32 v140, v130, v160
	v_add_f32_e32 v130, v140, v140
	v_mul_f32_e32 v130, 0x3fb8aa3b, v130
	v_exp_f32_e32 v130, v130
	v_cndmask_b32_e64 v133, v133, v136, s[12:13]
	v_sub_f32_e32 v130, 1.0, v130
	v_add_f32_e32 v134, v134, v106
	v_mul_f32_e32 v131, 0xbfb8aa3b, v131
	v_mul_f32_e32 v134, 0xbfb8aa3b, v134
	v_mov_b32_e32 v136, v130
	v_exp_f32_e32 v131, v131
	v_exp_f32_e32 v134, v134
	v_sqrt_f32_e32 v141, v136
; __device__ __forceinline__ float bflo(unsigned w) { return __uint_as_float(w << 16); }
; __device__ __forceinline__ float bfhi(unsigned w) { return __uint_as_float(w & 0xffff0000u); }
; __device__ __forceinline__ float sigmoidf_(float x) { return __builtin_amdgcn_rcpf(1.0f + __expf(-x)); }
;     __device__ __forceinline__ void operator()(AccRef acc, const Unit& u, int wr, int wc, int fr, int fq) const {
;     ...
;                 for (int m = 0; m < 4; ++m) { const size_t off = (size_t)(row0 + ai * 128 + m * 16) * D + col0 + 4 * n;
;                     float lo[4], bo[4];
; #pragma unroll
;                     for (int j = 0; j < 4; ++j) { const unsigned w = rws[ai][m][2 * n + (j >> 1)]; const float rec = (j & 1) ? bfhi(w) : bflo(w);
;                         const float r = sigmoidf_(acc[ai][0][m][n][j] + ba[j]), ig = sigmoidf_(acc[ai][1][m][n][j] + bx[j]);
;                         const float la = k8[j] * r; const float mult = __builtin_sqrtf(1.0f - __expf(2.0f * la));
;                         lo[j] = la; bo[j] = mult * ig * rec; }
;                     *(u32x2*)(LA + off) = (u32x2){cvt_pk_bf16(lo[0], lo[1]), cvt_pk_bf16(lo[2], lo[3])}; *(u32x2*)(BV + off) = (u32x2){cvt_pk_bf16(bo[0], bo[1]), cvt_pk_bf16(bo[2], bo[3])}; }
	v_add_f32_e32 v131, 1.0, v131
	v_add_f32_e32 v130, 1.0, v134
	v_add_u32_e32 v134, -1, v141
	v_rcp_f32_e32 v131, v131
	v_fma_f32 v137, -v134, v141, v136
	v_cmp_ge_f32_e64 s[12:13], 0, v137
	v_add_u32_e32 v137, 1, v141
	v_add_f32_e32 v135, v135, v107
	v_cndmask_b32_e64 v134, v141, v134, s[12:13]
	v_fma_f32 v141, -v137, v141, v136
	v_cmp_lt_f32_e64 s[12:13], 0, v141
	v_mul_f32_e32 v141, v131, v161
	v_add_f32_e32 v131, v141, v141
	v_mul_f32_e32 v131, 0x3fb8aa3b, v131
	v_exp_f32_e32 v131, v131
	v_cndmask_b32_e64 v134, v134, v137, s[12:13]
	v_sub_f32_e32 v131, 1.0, v131
	v_mul_f32_e32 v135, 0xbfb8aa3b, v135
	v_exp_f32_e32 v135, v135
	v_mov_b32_e32 v137, v131
	v_sqrt_f32_e32 v142, v137
	v_add_f32_e32 v131, 1.0, v135
	v_add_f32_e32 v128, 1.0, v128
	v_add_u32_e32 v135, -1, v142
	v_fma_f32 v136, -v135, v142, v137
	v_cmp_ge_f32_e64 s[12:13], 0, v136
	v_add_u32_e32 v136, 1, v142
	v_lshlrev_b64 v[56:57], 10, v[196:197]
	v_cndmask_b32_e64 v135, v142, v135, s[12:13]
	v_fma_f32 v142, -v136, v142, v137
	v_cmp_lt_f32_e64 s[12:13], 0, v142
	v_rcp_f32_e32 v128, v128
	v_rcp_f32_e32 v129, v129
	v_cndmask_b32_e64 v135, v135, v136, s[12:13]
	v_add_f32_e32 v120, v120, v108
	v_mul_f32_e32 v120, 0xbfb8aa3b, v120
	v_lshl_add_u64 v[136:137], v[56:57], 0, v[180:181]
	v_lshlrev_b64 v[136:137], 1, v[136:137]
	v_exp_f32_e32 v120, v120
	v_cvt_pk_bf16_f32 v138, v138, v139
	v_cvt_pk_bf16_f32 v139, v140, v141
	v_lshl_add_u64 v[140:141], s[70:71], 0, v[136:137]
	v_mov_b32_e32 v239, v138
	v_mov_b32_e32 v240, v139
	v_lshlrev_b32_e32 v138, 16, v44
	v_and_b32_e32 v139, 0xffff0000, v44
	v_pk_mul_f32 v[128:129], v[128:129], v[132:133]
	v_rcp_f32_e32 v130, v130
	v_rcp_f32_e32 v131, v131
	v_pk_mul_f32 v[128:129], v[128:129], v[138:139]
	v_add_f32_e32 v121, v121, v109
	v_cvt_pk_bf16_f32 v44, v128, v129
	v_lshlrev_b32_e32 v128, 16, v45
	v_and_b32_e32 v129, 0xffff0000, v45
	v_add_f32_e32 v45, 1.0, v120
	v_rcp_f32_e32 v120, v45
	v_pk_mul_f32 v[130:131], v[130:131], v[134:135]
	v_mul_f32_e32 v121, 0xbfb8aa3b, v121
	v_pk_mul_f32 v[128:129], v[130:131], v[128:129]
	v_mul_f32_e32 v130, v120, v162
	v_cvt_pk_bf16_f32 v45, v128, v129
	v_lshl_add_u64 v[128:129], s[68:69], 0, v[136:137]
	v_mov_b32_e32 v241, v44
	v_mov_b32_e32 v242, v45
	v_add_f32_e32 v44, v130, v130
	v_mul_f32_e32 v44, 0x3fb8aa3b, v44
	v_exp_f32_e32 v44, v44
	v_add_f32_e32 v45, v124, v104
	v_mul_f32_e32 v45, 0xbfb8aa3b, v45
	v_exp_f32_e32 v120, v45
	v_sub_f32_e32 v44, 1.0, v44
	v_exp_f32_e32 v121, v121
	v_add_f32_e32 v122, v122, v110
	v_mov_b32_e32 v124, v44
	v_sqrt_f32_e32 v128, v124
	v_add_f32_e32 v121, 1.0, v121
	v_rcp_f32_e32 v121, v121
	v_add_f32_e32 v125, v125, v105
	v_add_u32_e32 v129, -1, v128
	v_fma_f32 v131, -v129, v128, v124
	v_cmp_ge_f32_e64 s[12:13], 0, v131
	v_add_u32_e32 v131, 1, v128
	v_mul_f32_e32 v122, 0xbfb8aa3b, v122
	v_cndmask_b32_e64 v129, v128, v129, s[12:13]
	v_fma_f32 v128, -v131, v128, v124
	v_cmp_lt_f32_e64 s[12:13], 0, v128
	v_mul_f32_e32 v125, 0xbfb8aa3b, v125
	v_exp_f32_e32 v122, v122
	v_cndmask_b32_e64 v128, v129, v131, s[12:13]
	v_mul_f32_e32 v131, v121, v163
	v_add_f32_e32 v121, v131, v131
	v_mul_f32_e32 v121, 0x3fb8aa3b, v121
	v_exp_f32_e32 v121, v121
	v_exp_f32_e32 v125, v125
	v_sub_f32_e32 v121, 1.0, v121
	v_add_f32_e32 v122, 1.0, v122
	v_mov_b32_e32 v129, v121
	v_sqrt_f32_e32 v132, v129
	v_add_f32_e32 v121, 1.0, v125
	v_rcp_f32_e32 v122, v122
	v_mov_b32_e32 v124, v128
	v_add_u32_e32 v125, -1, v132
	v_fma_f32 v128, -v125, v132, v129
	v_cmp_ge_f32_e64 s[12:13], 0, v128
	v_add_u32_e32 v128, 1, v132
	v_add_f32_e32 v123, v123, v111
	v_cndmask_b32_e64 v125, v132, v125, s[12:13]
	v_fma_f32 v132, -v128, v132, v129
	v_cmp_lt_f32_e64 s[12:13], 0, v132
	v_mul_f32_e32 v132, v122, v160
	v_add_f32_e32 v122, v132, v132
	v_mul_f32_e32 v122, 0x3fb8aa3b, v122
	v_exp_f32_e32 v122, v122
	v_cndmask_b32_e64 v125, v125, v128, s[12:13]
	v_sub_f32_e32 v122, 1.0, v122
	v_add_f32_e32 v126, v126, v106
	v_mul_f32_e32 v123, 0xbfb8aa3b, v123
	v_mul_f32_e32 v126, 0xbfb8aa3b, v126
	v_mov_b32_e32 v128, v122
	v_exp_f32_e32 v123, v123
	v_exp_f32_e32 v126, v126
	v_sqrt_f32_e32 v133, v128
	v_add_f32_e32 v123, 1.0, v123
	v_add_f32_e32 v122, 1.0, v126
	v_add_u32_e32 v126, -1, v133
	v_rcp_f32_e32 v123, v123
	v_fma_f32 v129, -v126, v133, v128
	v_cmp_ge_f32_e64 s[12:13], 0, v129
	v_add_u32_e32 v129, 1, v133
	v_add_f32_e32 v127, v127, v107
	v_cndmask_b32_e64 v126, v133, v126, s[12:13]
	v_fma_f32 v133, -v129, v133, v128
	v_cmp_lt_f32_e64 s[12:13], 0, v133
	v_mul_f32_e32 v133, v123, v161
	v_add_f32_e32 v123, v133, v133
	v_mul_f32_e32 v123, 0x3fb8aa3b, v123
	v_exp_f32_e32 v123, v123
	v_cndmask_b32_e64 v126, v126, v129, s[12:13]
	v_sub_f32_e32 v123, 1.0, v123
	v_mul_f32_e32 v127, 0xbfb8aa3b, v127
	v_exp_f32_e32 v127, v127
	v_mov_b32_e32 v129, v123
	v_sqrt_f32_e32 v134, v129
	v_add_f32_e32 v123, 1.0, v127
	v_add_f32_e32 v120, 1.0, v120
	v_add_u32_e32 v127, -1, v134
	v_fma_f32 v128, -v127, v134, v129
	v_cmp_ge_f32_e64 s[12:13], 0, v128
	v_add_u32_e32 v128, 1, v134
	v_lshlrev_b64 v[44:45], 10, v[194:195]
	v_cndmask_b32_e64 v127, v134, v127, s[12:13]
	v_fma_f32 v134, -v128, v134, v129
	v_cmp_lt_f32_e64 s[12:13], 0, v134
	v_rcp_f32_e32 v120, v120
	v_rcp_f32_e32 v121, v121
	v_cndmask_b32_e64 v127, v127, v128, s[12:13]
	v_add_f32_e32 v112, v112, v108
	v_mul_f32_e32 v112, 0xbfb8aa3b, v112
	v_lshl_add_u64 v[128:129], v[44:45], 0, v[180:181]
	v_lshlrev_b64 v[128:129], 1, v[128:129]
	v_exp_f32_e32 v112, v112
	v_cvt_pk_bf16_f32 v130, v130, v131
	v_cvt_pk_bf16_f32 v131, v132, v133
	v_lshl_add_u64 v[132:133], s[70:71], 0, v[128:129]
	v_mov_b32_e32 v243, v130
	v_mov_b32_e32 v244, v131
	v_lshlrev_b32_e32 v130, 16, v32
	v_and_b32_e32 v131, 0xffff0000, v32
; __device__ __forceinline__ float bflo(unsigned w) { return __uint_as_float(w << 16); }
; __device__ __forceinline__ float bfhi(unsigned w) { return __uint_as_float(w & 0xffff0000u); }
; __device__ __forceinline__ float sigmoidf_(float x) { return __builtin_amdgcn_rcpf(1.0f + __expf(-x)); }
;     __device__ __forceinline__ void operator()(AccRef acc, const Unit& u, int wr, int wc, int fr, int fq) const {
;     ...
;                 for (int m = 0; m < 4; ++m) { const size_t off = (size_t)(row0 + ai * 128 + m * 16) * D + col0 + 4 * n;
;                     float lo[4], bo[4];
; #pragma unroll
;                     for (int j = 0; j < 4; ++j) { const unsigned w = rws[ai][m][2 * n + (j >> 1)]; const float rec = (j & 1) ? bfhi(w) : bflo(w);
;                         const float r = sigmoidf_(acc[ai][0][m][n][j] + ba[j]), ig = sigmoidf_(acc[ai][1][m][n][j] + bx[j]);
;                         const float la = k8[j] * r; const float mult = __builtin_sqrtf(1.0f - __expf(2.0f * la));
;                         lo[j] = la; bo[j] = mult * ig * rec; }
;                     *(u32x2*)(LA + off) = (u32x2){cvt_pk_bf16(lo[0], lo[1]), cvt_pk_bf16(lo[2], lo[3])}; *(u32x2*)(BV + off) = (u32x2){cvt_pk_bf16(bo[0], bo[1]), cvt_pk_bf16(bo[2], bo[3])}; }
	v_pk_mul_f32 v[120:121], v[120:121], v[124:125]
	v_rcp_f32_e32 v122, v122
	v_rcp_f32_e32 v123, v123
	v_pk_mul_f32 v[120:121], v[120:121], v[130:131]
	v_add_f32_e32 v113, v113, v109
	v_cvt_pk_bf16_f32 v32, v120, v121
	v_lshlrev_b32_e32 v120, 16, v33
	v_and_b32_e32 v121, 0xffff0000, v33
	v_add_f32_e32 v33, 1.0, v112
	v_rcp_f32_e32 v112, v33
	v_pk_mul_f32 v[122:123], v[122:123], v[126:127]
	v_mul_f32_e32 v113, 0xbfb8aa3b, v113
	v_pk_mul_f32 v[120:121], v[122:123], v[120:121]
	v_mul_f32_e32 v122, v112, v162
	v_cvt_pk_bf16_f32 v33, v120, v121
	v_lshl_add_u64 v[120:121], s[68:69], 0, v[128:129]
	v_mov_b32_e32 v245, v32
	v_mov_b32_e32 v246, v33
	v_add_f32_e32 v32, v122, v122
	v_mul_f32_e32 v32, 0x3fb8aa3b, v32
	v_exp_f32_e32 v32, v32
	v_add_f32_e32 v33, v116, v104
	v_mul_f32_e32 v33, 0xbfb8aa3b, v33
	v_exp_f32_e32 v112, v33
	v_sub_f32_e32 v32, 1.0, v32
	v_exp_f32_e32 v113, v113
	v_add_f32_e32 v114, v114, v110
	v_mov_b32_e32 v116, v32
	v_sqrt_f32_e32 v120, v116
	v_add_f32_e32 v113, 1.0, v113
	v_rcp_f32_e32 v113, v113
	v_add_f32_e32 v117, v117, v105
	v_add_u32_e32 v121, -1, v120
	v_fma_f32 v123, -v121, v120, v116
	v_cmp_ge_f32_e64 s[12:13], 0, v123
	v_add_u32_e32 v123, 1, v120
	v_mul_f32_e32 v114, 0xbfb8aa3b, v114
	v_cndmask_b32_e64 v121, v120, v121, s[12:13]
	v_fma_f32 v120, -v123, v120, v116
	v_cmp_lt_f32_e64 s[12:13], 0, v120
	v_mul_f32_e32 v117, 0xbfb8aa3b, v117
	v_exp_f32_e32 v114, v114
	v_cndmask_b32_e64 v120, v121, v123, s[12:13]
	v_mul_f32_e32 v123, v113, v163
	v_add_f32_e32 v113, v123, v123
	v_mul_f32_e32 v113, 0x3fb8aa3b, v113
	v_exp_f32_e32 v113, v113
	v_exp_f32_e32 v117, v117
	v_sub_f32_e32 v113, 1.0, v113
	v_add_f32_e32 v114, 1.0, v114
	v_mov_b32_e32 v121, v113
	v_sqrt_f32_e32 v124, v121
	v_add_f32_e32 v113, 1.0, v117
	v_rcp_f32_e32 v114, v114
	v_mov_b32_e32 v116, v120
	v_add_u32_e32 v117, -1, v124
	v_fma_f32 v120, -v117, v124, v121
	v_cmp_ge_f32_e64 s[12:13], 0, v120
	v_add_u32_e32 v120, 1, v124
	v_add_f32_e32 v115, v115, v111
	v_cndmask_b32_e64 v117, v124, v117, s[12:13]
	v_fma_f32 v124, -v120, v124, v121
	v_cmp_lt_f32_e64 s[12:13], 0, v124
	v_mul_f32_e32 v124, v114, v160
	v_add_f32_e32 v114, v124, v124
	v_mul_f32_e32 v114, 0x3fb8aa3b, v114
	v_exp_f32_e32 v114, v114
	v_cndmask_b32_e64 v117, v117, v120, s[12:13]
	v_sub_f32_e32 v114, 1.0, v114
	v_add_f32_e32 v118, v118, v106
	v_mul_f32_e32 v115, 0xbfb8aa3b, v115
	v_mul_f32_e32 v118, 0xbfb8aa3b, v118
	v_mov_b32_e32 v120, v114
	v_exp_f32_e32 v115, v115
	v_exp_f32_e32 v118, v118
	v_sqrt_f32_e32 v125, v120
	v_add_f32_e32 v115, 1.0, v115
	v_add_f32_e32 v114, 1.0, v118
	v_add_u32_e32 v118, -1, v125
	v_rcp_f32_e32 v115, v115
	v_fma_f32 v121, -v118, v125, v120
	v_cmp_ge_f32_e64 s[12:13], 0, v121
	v_add_u32_e32 v121, 1, v125
	v_add_f32_e32 v119, v119, v107
	v_cndmask_b32_e64 v118, v125, v118, s[12:13]
	v_fma_f32 v125, -v121, v125, v120
	v_cmp_lt_f32_e64 s[12:13], 0, v125
	v_mul_f32_e32 v125, v115, v161
	v_add_f32_e32 v115, v125, v125
	v_mul_f32_e32 v115, 0x3fb8aa3b, v115
	v_exp_f32_e32 v115, v115
	v_cndmask_b32_e64 v118, v118, v121, s[12:13]
	v_sub_f32_e32 v115, 1.0, v115
	v_mul_f32_e32 v119, 0xbfb8aa3b, v119
	v_exp_f32_e32 v119, v119
	v_mov_b32_e32 v121, v115
	v_sqrt_f32_e32 v126, v121
	v_add_f32_e32 v115, 1.0, v119
	v_add_f32_e32 v112, 1.0, v112
	v_add_u32_e32 v119, -1, v126
	v_fma_f32 v120, -v119, v126, v121
	v_cmp_ge_f32_e64 s[12:13], 0, v120
	v_add_u32_e32 v120, 1, v126
	v_lshlrev_b64 v[32:33], 10, v[192:193]
	v_cndmask_b32_e64 v119, v126, v119, s[12:13]
	v_fma_f32 v126, -v120, v126, v121
	v_cmp_lt_f32_e64 s[12:13], 0, v126
	v_rcp_f32_e32 v112, v112
	v_rcp_f32_e32 v113, v113
	v_cndmask_b32_e64 v119, v119, v120, s[12:13]
	v_add_f32_e32 v96, v96, v108
	v_mul_f32_e32 v96, 0xbfb8aa3b, v96
	v_lshl_add_u64 v[120:121], v[32:33], 0, v[180:181]
	v_lshlrev_b64 v[120:121], 1, v[120:121]
	v_exp_f32_e32 v96, v96
	v_cvt_pk_bf16_f32 v122, v122, v123
	v_cvt_pk_bf16_f32 v123, v124, v125
	v_lshl_add_u64 v[124:125], s[70:71], 0, v[120:121]
	v_mov_b32_e32 v247, v122
	v_mov_b32_e32 v248, v123
	v_lshlrev_b32_e32 v122, 16, v20
	v_and_b32_e32 v123, 0xffff0000, v20
	v_pk_mul_f32 v[112:113], v[112:113], v[116:117]
	v_rcp_f32_e32 v114, v114
	v_rcp_f32_e32 v115, v115
	v_pk_mul_f32 v[112:113], v[112:113], v[122:123]
	v_add_f32_e32 v97, v97, v109
	v_cvt_pk_bf16_f32 v20, v112, v113
	v_lshlrev_b32_e32 v112, 16, v21
	v_and_b32_e32 v113, 0xffff0000, v21
	v_add_f32_e32 v21, 1.0, v96
	v_rcp_f32_e32 v96, v21
	v_pk_mul_f32 v[114:115], v[114:115], v[118:119]
	v_mul_f32_e32 v97, 0xbfb8aa3b, v97
	v_pk_mul_f32 v[112:113], v[114:115], v[112:113]
	v_mul_f32_e32 v108, v96, v162
	v_cvt_pk_bf16_f32 v21, v112, v113
	v_lshl_add_u64 v[112:113], s[68:69], 0, v[120:121]
	v_mov_b32_e32 v249, v20
	v_mov_b32_e32 v250, v21
	v_add_f32_e32 v20, v108, v108
	v_mul_f32_e32 v20, 0x3fb8aa3b, v20
	v_exp_f32_e32 v20, v20
	v_add_f32_e32 v21, v100, v104
	v_mul_f32_e32 v21, 0xbfb8aa3b, v21
	v_exp_f32_e32 v96, v21
	v_sub_f32_e32 v20, 1.0, v20
	v_exp_f32_e32 v97, v97
	v_add_f32_e32 v98, v98, v110
	v_mov_b32_e32 v100, v20
	v_sqrt_f32_e32 v104, v100
	v_add_f32_e32 v97, 1.0, v97
	v_rcp_f32_e32 v97, v97
	v_add_f32_e32 v101, v101, v105
	v_add_u32_e32 v112, -1, v104
	v_fma_f32 v113, -v112, v104, v100
	v_cmp_ge_f32_e64 s[12:13], 0, v113
	v_mul_f32_e32 v98, 0xbfb8aa3b, v98
	v_mul_f32_e32 v101, 0xbfb8aa3b, v101
	v_cndmask_b32_e64 v109, v104, v112, s[12:13]
	v_add_u32_e32 v112, 1, v104
	v_fma_f32 v104, -v112, v104, v100
	v_cmp_lt_f32_e64 s[12:13], 0, v104
	v_exp_f32_e32 v98, v98
	v_exp_f32_e32 v101, v101
	v_cndmask_b32_e64 v104, v109, v112, s[12:13]
	v_mul_f32_e32 v109, v97, v163
	v_add_f32_e32 v97, v109, v109
	v_mul_f32_e32 v97, 0x3fb8aa3b, v97
	v_exp_f32_e32 v97, v97
; __device__ __forceinline__ float bflo(unsigned w) { return __uint_as_float(w << 16); }
; __device__ __forceinline__ float bfhi(unsigned w) { return __uint_as_float(w & 0xffff0000u); }
; __device__ __forceinline__ float sigmoidf_(float x) { return __builtin_amdgcn_rcpf(1.0f + __expf(-x)); }
;     __device__ __forceinline__ void operator()(AccRef acc, const Unit& u, int wr, int wc, int fr, int fq) const {
;     ...
;             const f32x4 ba = *(const f32x4*)(b_a + col0 + 4 * n), bx = *(const f32x4*)(b_x + col0 + 4 * n), l = *(const f32x4*)(lam + col0 + 4 * n);
;     ...
;                 for (int m = 0; m < 4; ++m) { const size_t off = (size_t)(row0 + ai * 128 + m * 16) * D + col0 + 4 * n;
;                     float lo[4], bo[4];
; #pragma unroll
;                     for (int j = 0; j < 4; ++j) { const unsigned w = rws[ai][m][2 * n + (j >> 1)]; const float rec = (j & 1) ? bfhi(w) : bflo(w);
;                         const float r = sigmoidf_(acc[ai][0][m][n][j] + ba[j]), ig = sigmoidf_(acc[ai][1][m][n][j] + bx[j]);
;                         const float la = k8[j] * r; const float mult = __builtin_sqrtf(1.0f - __expf(2.0f * la));
;                         lo[j] = la; bo[j] = mult * ig * rec; }
;                     *(u32x2*)(LA + off) = (u32x2){cvt_pk_bf16(lo[0], lo[1]), cvt_pk_bf16(lo[2], lo[3])}; *(u32x2*)(BV + off) = (u32x2){cvt_pk_bf16(bo[0], bo[1]), cvt_pk_bf16(bo[2], bo[3])}; }
	v_add_f32_e32 v98, 1.0, v98
	v_rcp_f32_e32 v98, v98
	v_sub_f32_e32 v97, 1.0, v97
	v_mov_b32_e32 v100, v104
	v_add_f32_e32 v99, v99, v111
	v_mov_b32_e32 v105, v97
	v_sqrt_f32_e32 v112, v105
	v_add_f32_e32 v97, 1.0, v101
	v_mul_f32_e32 v99, 0xbfb8aa3b, v99
	v_exp_f32_e32 v99, v99
	v_add_u32_e32 v101, -1, v112
	v_fma_f32 v104, -v101, v112, v105
	v_cmp_ge_f32_e64 s[12:13], 0, v104
	v_add_u32_e32 v104, 1, v112
	v_fma_f32 v110, -v104, v112, v105
	v_cndmask_b32_e64 v101, v112, v101, s[12:13]
	v_cmp_lt_f32_e64 s[12:13], 0, v110
	v_mul_f32_e32 v110, v98, v160
	v_add_f32_e32 v98, v110, v110
	v_mul_f32_e32 v98, 0x3fb8aa3b, v98
	v_exp_f32_e32 v98, v98
	v_cndmask_b32_e64 v101, v101, v104, s[12:13]
	v_sub_f32_e32 v98, 1.0, v98
	v_add_f32_e32 v102, v102, v106
	v_add_f32_e32 v99, 1.0, v99
	v_mul_f32_e32 v102, 0xbfb8aa3b, v102
	v_mov_b32_e32 v104, v98
	v_rcp_f32_e32 v99, v99
	v_exp_f32_e32 v102, v102
	v_sqrt_f32_e32 v106, v104
	v_mul_f32_e32 v111, v99, v161
	v_add_f32_e32 v98, 1.0, v102
	v_add_u32_e32 v102, -1, v106
	v_add_f32_e32 v99, v111, v111
	v_fma_f32 v105, -v102, v106, v104
	v_mul_f32_e32 v99, 0x3fb8aa3b, v99
	v_cmp_ge_f32_e64 s[12:13], 0, v105
	v_add_u32_e32 v105, 1, v106
	v_exp_f32_e32 v99, v99
	v_cndmask_b32_e64 v102, v106, v102, s[12:13]
	v_fma_f32 v106, -v105, v106, v104
	v_cmp_lt_f32_e64 s[12:13], 0, v106
	v_sub_f32_e32 v99, 1.0, v99
	v_add_f32_e32 v103, v103, v107
	v_cndmask_b32_e64 v102, v102, v105, s[12:13]
	v_mul_f32_e32 v103, 0xbfb8aa3b, v103
	v_exp_f32_e32 v103, v103
	v_mov_b32_e32 v105, v99
	v_sqrt_f32_e32 v106, v105
	v_add_f32_e32 v99, 1.0, v103
	v_add_f32_e32 v96, 1.0, v96
	v_add_u32_e32 v103, -1, v106
	v_fma_f32 v104, -v103, v106, v105
	v_cmp_ge_f32_e64 s[12:13], 0, v104
	v_add_u32_e32 v104, 1, v106
	v_lshlrev_b64 v[20:21], 10, v[190:191]
	v_cndmask_b32_e64 v103, v106, v103, s[12:13]
	v_fma_f32 v106, -v104, v106, v105
	v_cmp_lt_f32_e64 s[12:13], 0, v106
	v_rcp_f32_e32 v96, v96
	v_rcp_f32_e32 v97, v97
	v_cndmask_b32_e64 v103, v103, v104, s[12:13]
	v_rcp_f32_e32 v98, v98
	v_rcp_f32_e32 v99, v99
	v_lshl_add_u64 v[104:105], v[20:21], 0, v[180:181]
	v_lshlrev_b64 v[104:105], 1, v[104:105]
	v_cvt_pk_bf16_f32 v106, v108, v109
	v_cvt_pk_bf16_f32 v107, v110, v111
	v_lshl_add_u64 v[108:109], s[70:71], 0, v[104:105]
	v_mov_b32_e32 v251, v106
	v_mov_b32_e32 v253, v107
	v_lshlrev_b32_e32 v106, 16, v8
	v_and_b32_e32 v107, 0xffff0000, v8
	v_pk_mul_f32 v[96:97], v[96:97], v[100:101]
	v_pk_mul_f32 v[98:99], v[98:99], v[102:103]
	v_pk_mul_f32 v[96:97], v[96:97], v[106:107]
	v_or_b32_e32 v180, 4, v180
	v_cvt_pk_bf16_f32 v8, v96, v97
	v_lshlrev_b32_e32 v96, 16, v9
	v_and_b32_e32 v97, 0xffff0000, v9
	v_pk_mul_f32 v[96:97], v[98:99], v[96:97]
	v_lshl_add_u64 v[108:109], v[182:183], 0, v[180:181]
	v_cvt_pk_bf16_f32 v9, v96, v97
	v_lshl_add_u64 v[96:97], s[68:69], 0, v[104:105]
	v_mov_b32_e32 v254, v8
	v_mov_b32_e32 v255, v9
	global_load_dwordx4 v[104:107], v[184:185], off offset:16
	global_load_dwordx4 v[100:103], v[186:187], off offset:16
	s_nop 0
	global_load_dwordx4 v[96:99], v[188:189], off offset:16
	s_mov_b64 s[16:17], s[44:45]
	s_waitcnt vmcnt(0)
	v_mul_f32_e32 v8, 0xbfb8aa3b, v104
	v_exp_f32_e32 v8, v8
	v_mul_f32_e32 v104, 0xbfb8aa3b, v105
	v_exp_f32_e32 v104, v104
	v_add_f32_e32 v84, v84, v100
	v_add_f32_e32 v8, 1.0, v8
	v_cmp_gt_f32_e32 vcc, s77, v8
	v_add_f32_e32 v104, 1.0, v104
	v_cmp_gt_f32_e64 s[12:13], s77, v104
	v_cndmask_b32_e64 v9, 0, 32, vcc
	v_ldexp_f32 v8, v8, v9
	v_log_f32_e32 v8, v8
	v_cndmask_b32_e64 v105, 0, 32, s[12:13]
	v_ldexp_f32 v104, v104, v105
	v_mul_f32_e32 v105, 0xbfb8aa3b, v106
	v_exp_f32_e32 v105, v105
	v_mul_f32_e32 v9, 0x3f317217, v8
	v_fma_f32 v9, v8, s78, -v9
	v_fmac_f32_e32 v9, 0x3377d1cf, v8
	v_fmac_f32_e32 v9, 0x3f317217, v8
	v_cmp_lt_f32_e64 s[14:15], |v8|, s79
	v_add_f32_e32 v105, 1.0, v105
	v_log_f32_e32 v104, v104
	v_cndmask_b32_e64 v8, v8, v9, s[14:15]
	v_cndmask_b32_e32 v9, 0, v210, vcc
	v_cmp_gt_f32_e32 vcc, s77, v105
	v_sub_f32_e32 v8, v8, v9
	v_mul_f32_e32 v9, 0x3f317217, v104
	v_cndmask_b32_e64 v106, 0, 32, vcc
	v_ldexp_f32 v105, v105, v106
	v_mul_f32_e32 v106, 0xbfb8aa3b, v107
	v_exp_f32_e32 v106, v106
	v_fma_f32 v9, v104, s78, -v9
	v_fmac_f32_e32 v9, 0x3377d1cf, v104
	v_log_f32_e32 v105, v105
	v_fmac_f32_e32 v9, 0x3f317217, v104
	v_cmp_lt_f32_e64 s[14:15], |v104|, s79
	v_add_f32_e32 v106, 1.0, v106
	v_mul_f32_e32 v84, 0xbfb8aa3b, v84
	v_cndmask_b32_e64 v9, v104, v9, s[14:15]
	v_cndmask_b32_e64 v104, 0, v210, s[12:13]
	v_cmp_gt_f32_e64 s[12:13], s77, v106
	v_sub_f32_e32 v9, v9, v104
	v_mul_f32_e32 v104, 0x3f317217, v105
	v_cndmask_b32_e64 v107, 0, 32, s[12:13]
	v_ldexp_f32 v106, v106, v107
	v_fma_f32 v104, v105, s78, -v104
	v_log_f32_e32 v106, v106
	v_fmac_f32_e32 v104, 0x3377d1cf, v105
	v_fmac_f32_e32 v104, 0x3f317217, v105
	v_cmp_lt_f32_e64 s[14:15], |v105|, s79
	v_add_f32_e32 v88, v88, v96
	v_exp_f32_e32 v84, v84
	v_cndmask_b32_e64 v104, v105, v104, s[14:15]
	v_cndmask_b32_e32 v105, 0, v210, vcc
	v_sub_f32_e32 v104, v104, v105
	v_mul_f32_e32 v105, 0x3f317217, v106
	v_fma_f32 v105, v106, s78, -v105
	v_fmac_f32_e32 v105, 0x3377d1cf, v106
	v_fmac_f32_e32 v105, 0x3f317217, v106
	v_cmp_lt_f32_e64 vcc, |v106|, s79
	v_mul_f32_e32 v88, 0xbfb8aa3b, v88
	v_add_f32_e32 v85, v85, v101
	v_cndmask_b32_e32 v105, v106, v105, vcc
	v_cndmask_b32_e64 v106, 0, v210, s[12:13]
	v_sub_f32_e32 v105, v105, v106
	v_exp_f32_e32 v106, v88
	v_mul_f32_e32 v85, 0xbfb8aa3b, v85
	v_exp_f32_e32 v85, v85
	v_add_f32_e32 v84, 1.0, v84
	v_rcp_f32_e32 v88, v84
	v_add_f32_e32 v84, 1.0, v106
	v_rcp_f32_e32 v106, v84
	v_add_f32_e32 v84, 1.0, v85
	v_add_f32_e32 v85, v89, v97
	v_mul_f32_e32 v85, 0xbfb8aa3b, v85
	v_add_f32_e32 v86, v86, v102
; __device__ __forceinline__ float bflo(unsigned w) { return __uint_as_float(w << 16); }
; __device__ __forceinline__ float bfhi(unsigned w) { return __uint_as_float(w & 0xffff0000u); }
; __device__ __forceinline__ float sigmoidf_(float x) { return __builtin_amdgcn_rcpf(1.0f + __expf(-x)); }
;     __device__ __forceinline__ void operator()(AccRef acc, const Unit& u, int wr, int wc, int fr, int fq) const {
;     ...
;                 for (int m = 0; m < 4; ++m) { const size_t off = (size_t)(row0 + ai * 128 + m * 16) * D + col0 + 4 * n;
;                     float lo[4], bo[4];
; #pragma unroll
;                     for (int j = 0; j < 4; ++j) { const unsigned w = rws[ai][m][2 * n + (j >> 1)]; const float rec = (j & 1) ? bfhi(w) : bflo(w);
;                         const float r = sigmoidf_(acc[ai][0][m][n][j] + ba[j]), ig = sigmoidf_(acc[ai][1][m][n][j] + bx[j]);
;                         const float la = k8[j] * r; const float mult = __builtin_sqrtf(1.0f - __expf(2.0f * la));
;                         lo[j] = la; bo[j] = mult * ig * rec; }
;                     *(u32x2*)(LA + off) = (u32x2){cvt_pk_bf16(lo[0], lo[1]), cvt_pk_bf16(lo[2], lo[3])}; *(u32x2*)(BV + off) = (u32x2){cvt_pk_bf16(bo[0], bo[1]), cvt_pk_bf16(bo[2], bo[3])}; }
	v_exp_f32_e32 v85, v85
	v_mul_f32_e32 v86, 0xbfb8aa3b, v86
	v_exp_f32_e32 v86, v86
	v_rcp_f32_e32 v89, v84
	v_add_f32_e32 v84, 1.0, v85
	v_add_f32_e32 v85, v90, v98
	v_rcp_f32_e32 v107, v84
	v_add_f32_e32 v84, 1.0, v86
	v_mul_f32_e32 v85, 0xbfb8aa3b, v85
	v_add_f32_e32 v86, v87, v103
	v_exp_f32_e32 v85, v85
	v_mul_f32_e32 v86, 0xbfb8aa3b, v86
	v_exp_f32_e32 v87, v86
	v_rcp_f32_e32 v86, v84
	v_add_f32_e32 v84, 1.0, v85
	v_rcp_f32_e32 v90, v84
	v_add_f32_e32 v84, 1.0, v87
	v_rcp_f32_e32 v87, v84
	v_pk_mul_f32 v[84:85], v[8:9], s[34:35] op_sel_hi:[1,0]
	v_add_f32_e32 v9, v91, v99
	v_pk_mul_f32 v[88:89], v[88:89], v[84:85]
	v_mul_f32_e32 v9, 0xbfb8aa3b, v9
	v_add_f32_e32 v8, v88, v88
	v_mul_f32_e32 v8, 0x3fb8aa3b, v8
	v_exp_f32_e32 v8, v8
	v_exp_f32_e32 v9, v9
	v_add_f32_e32 v112, v89, v89
	v_mul_f32_e32 v112, 0x3fb8aa3b, v112
	v_sub_f32_e32 v8, 1.0, v8
	v_add_f32_e32 v9, 1.0, v9
	v_exp_f32_e32 v112, v112
	v_sqrt_f32_e32 v110, v8
	v_rcp_f32_e32 v91, v9
	v_cvt_pk_bf16_f32 v88, v88, v89
	v_add_f32_e32 v72, v72, v100
	v_add_u32_e32 v9, -1, v110
	v_fma_f32 v111, -v9, v110, v8
	v_cmp_ge_f32_e64 s[12:13], 0, v111
	v_add_u32_e32 v111, 1, v110
	v_mul_f32_e32 v72, 0xbfb8aa3b, v72
	v_cndmask_b32_e64 v9, v110, v9, s[12:13]
	v_fma_f32 v110, -v111, v110, v8
	v_cmp_lt_f32_e64 s[12:13], 0, v110
	v_exp_f32_e32 v72, v72
	v_add_f32_e32 v73, v73, v101
	v_cndmask_b32_e64 v9, v9, v111, s[12:13]
	v_sub_f32_e32 v111, 1.0, v112
	v_sqrt_f32_e32 v112, v111
	v_add_f32_e32 v72, 1.0, v72
	v_rcp_f32_e32 v72, v72
	v_mov_b32_e32 v110, v9
	v_add_u32_e32 v8, -1, v112
	v_fma_f32 v9, -v8, v112, v111
	v_cmp_ge_f32_e32 vcc, 0, v9
	v_add_u32_e32 v114, 1, v112
	v_mul_f32_e32 v73, 0xbfb8aa3b, v73
	v_cndmask_b32_e32 v113, v112, v8, vcc
	v_pk_mul_f32 v[8:9], v[104:105], s[34:35] op_sel_hi:[1,0]
	v_fma_f32 v112, -v114, v112, v111
	v_pk_mul_f32 v[86:87], v[86:87], v[8:9]
	v_cmp_lt_f32_e32 vcc, 0, v112
	v_add_f32_e32 v104, v86, v86
	v_mul_f32_e32 v104, 0x3fb8aa3b, v104
	v_exp_f32_e32 v104, v104
	v_cndmask_b32_e32 v105, v113, v114, vcc
	v_sub_f32_e32 v104, 1.0, v104
	v_add_f32_e32 v113, v87, v87
	v_mul_f32_e32 v113, 0x3fb8aa3b, v113
	v_sqrt_f32_e32 v112, v104
	v_exp_f32_e32 v113, v113
	v_exp_f32_e32 v73, v73
	v_add_u32_e32 v89, -1, v112
	v_mov_b32_e32 v111, v105
	v_fma_f32 v105, -v89, v112, v104
	v_cmp_ge_f32_e64 s[12:13], 0, v105
	v_add_u32_e32 v105, 1, v112
	v_pk_mul_f32 v[106:107], v[106:107], v[110:111]
	v_cndmask_b32_e64 v89, v112, v89, s[12:13]
	v_fma_f32 v112, -v105, v112, v104
	v_cmp_lt_f32_e64 s[12:13], 0, v112
	v_sub_f32_e32 v112, 1.0, v113
	s_nop 0
	v_cndmask_b32_e64 v89, v89, v105, s[12:13]
	v_sqrt_f32_e32 v113, v112
	v_add_f32_e32 v76, v76, v96
	v_add_f32_e32 v73, 1.0, v73
	v_mov_b32_e32 v104, v89
	v_add_u32_e32 v89, -1, v113
	v_fma_f32 v105, -v89, v113, v112
	v_cmp_ge_f32_e32 vcc, 0, v105
	v_add_u32_e32 v105, 1, v113
	v_mul_f32_e32 v76, 0xbfb8aa3b, v76
	v_cndmask_b32_e32 v89, v113, v89, vcc
	v_fma_f32 v113, -v105, v113, v112
	v_cmp_lt_f32_e32 vcc, 0, v113
	v_rcp_f32_e32 v73, v73
	v_exp_f32_e32 v76, v76
	v_cndmask_b32_e32 v89, v89, v105, vcc
	v_add_f32_e32 v77, v77, v97
	v_add_f32_e32 v74, v74, v102
	v_mov_b32_e32 v105, v89
	v_cvt_pk_bf16_f32 v89, v86, v87
	v_lshlrev_b64 v[86:87], 1, v[108:109]
	v_lshl_add_u64 v[108:109], s[70:71], 0, v[86:87]
	v_mov_b32_e32 v116, v211
	v_mov_b32_e32 v117, v218
	v_mov_b32_e32 v118, v88
	v_mov_b32_e32 v119, v89
	global_store_dwordx4 v[108:109], v[116:119], off offset:-8
	v_lshlrev_b32_e32 v88, 16, v94
	v_and_b32_e32 v89, 0xffff0000, v94
	v_lshlrev_b32_e32 v94, 16, v95
	v_and_b32_e32 v95, 0xffff0000, v95
	v_pk_mul_f32 v[90:91], v[90:91], v[104:105]
	v_pk_mul_f32 v[88:89], v[106:107], v[88:89]
	v_pk_mul_f32 v[90:91], v[90:91], v[94:95]
	v_cvt_pk_bf16_f32 v88, v88, v89
	v_cvt_pk_bf16_f32 v89, v90, v91
	v_mul_f32_e32 v90, v72, v84
	v_add_f32_e32 v72, v90, v90
	v_mul_f32_e32 v72, 0x3fb8aa3b, v72
	v_exp_f32_e32 v72, v72
	v_lshl_add_u64 v[86:87], s[68:69], 0, v[86:87]
	v_mov_b32_e32 v120, v224
	v_mov_b32_e32 v121, v225
	v_mov_b32_e32 v122, v88
	v_mov_b32_e32 v123, v89
	global_store_dwordx4 v[86:87], v[120:123], off offset:-8
	v_mul_f32_e32 v88, v73, v85
	v_sub_f32_e32 v72, 1.0, v72
	v_add_f32_e32 v73, v88, v88
	v_mul_f32_e32 v73, 0x3fb8aa3b, v73
	v_mov_b32_e32 v91, v72
	v_sqrt_f32_e32 v94, v91
	v_add_f32_e32 v72, 1.0, v76
	v_exp_f32_e32 v73, v73
	v_mul_f32_e32 v77, 0xbfb8aa3b, v77
	v_add_u32_e32 v76, -1, v94
	v_fma_f32 v86, -v76, v94, v91
	v_cmp_ge_f32_e64 s[12:13], 0, v86
	v_add_u32_e32 v86, 1, v94
	v_fma_f32 v87, -v86, v94, v91
	v_cndmask_b32_e64 v76, v94, v76, s[12:13]
	v_cmp_lt_f32_e64 s[12:13], 0, v87
	v_sub_f32_e32 v73, 1.0, v73
	v_mul_f32_e32 v74, 0xbfb8aa3b, v74
	v_cndmask_b32_e64 v76, v76, v86, s[12:13]
	v_exp_f32_e32 v77, v77
	v_exp_f32_e32 v74, v74
	v_mov_b32_e32 v86, v73
	v_sqrt_f32_e32 v87, v86
	v_add_f32_e32 v73, 1.0, v77
	v_add_f32_e32 v74, 1.0, v74
	v_add_u32_e32 v77, -1, v87
	v_fma_f32 v89, -v77, v87, v86
	v_rcp_f32_e32 v74, v74
	v_cmp_ge_f32_e64 s[12:13], 0, v89
	v_add_u32_e32 v89, 1, v87
	v_add_f32_e32 v75, v75, v103
	v_cndmask_b32_e64 v77, v87, v77, s[12:13]
	v_fma_f32 v87, -v89, v87, v86
	v_cmp_lt_f32_e64 s[12:13], 0, v87
	v_add_f32_e32 v78, v78, v98
	v_mul_f32_e32 v75, 0xbfb8aa3b, v75
	v_cndmask_b32_e64 v77, v77, v89, s[12:13]
	v_mul_f32_e32 v89, v74, v8
	v_add_f32_e32 v74, v89, v89
	v_mul_f32_e32 v74, 0x3fb8aa3b, v74
	v_exp_f32_e32 v74, v74
	v_mul_f32_e32 v78, 0xbfb8aa3b, v78
	v_sub_f32_e32 v74, 1.0, v74
	v_exp_f32_e32 v75, v75
	v_exp_f32_e32 v78, v78
	v_mov_b32_e32 v87, v74
	v_sqrt_f32_e32 v91, v87
	v_add_f32_e32 v75, 1.0, v75
	v_add_f32_e32 v74, 1.0, v78
	v_add_u32_e32 v78, -1, v91
	v_rcp_f32_e32 v75, v75
; __device__ __forceinline__ float bflo(unsigned w) { return __uint_as_float(w << 16); }
; __device__ __forceinline__ float bfhi(unsigned w) { return __uint_as_float(w & 0xffff0000u); }
; __device__ __forceinline__ float sigmoidf_(float x) { return __builtin_amdgcn_rcpf(1.0f + __expf(-x)); }
;     __device__ __forceinline__ void operator()(AccRef acc, const Unit& u, int wr, int wc, int fr, int fq) const {
;     ...
;                 for (int m = 0; m < 4; ++m) { const size_t off = (size_t)(row0 + ai * 128 + m * 16) * D + col0 + 4 * n;
;                     float lo[4], bo[4];
; #pragma unroll
;                     for (int j = 0; j < 4; ++j) { const unsigned w = rws[ai][m][2 * n + (j >> 1)]; const float rec = (j & 1) ? bfhi(w) : bflo(w);
;                         const float r = sigmoidf_(acc[ai][0][m][n][j] + ba[j]), ig = sigmoidf_(acc[ai][1][m][n][j] + bx[j]);
;                         const float la = k8[j] * r; const float mult = __builtin_sqrtf(1.0f - __expf(2.0f * la));
;                         lo[j] = la; bo[j] = mult * ig * rec; }
;                     *(u32x2*)(LA + off) = (u32x2){cvt_pk_bf16(lo[0], lo[1]), cvt_pk_bf16(lo[2], lo[3])}; *(u32x2*)(BV + off) = (u32x2){cvt_pk_bf16(bo[0], bo[1]), cvt_pk_bf16(bo[2], bo[3])}; }
	v_fma_f32 v86, -v78, v91, v87
	v_cmp_ge_f32_e64 s[12:13], 0, v86
	v_add_u32_e32 v86, 1, v91
	v_add_f32_e32 v79, v79, v99
	v_cndmask_b32_e64 v78, v91, v78, s[12:13]
	v_fma_f32 v91, -v86, v91, v87
	v_cmp_lt_f32_e64 s[12:13], 0, v91
	v_mul_f32_e32 v91, v75, v9
	v_add_f32_e32 v75, v91, v91
	v_mul_f32_e32 v75, 0x3fb8aa3b, v75
	v_exp_f32_e32 v75, v75
	v_cndmask_b32_e64 v78, v78, v86, s[12:13]
	v_sub_f32_e32 v75, 1.0, v75
	v_mul_f32_e32 v79, 0xbfb8aa3b, v79
	v_exp_f32_e32 v79, v79
	v_mov_b32_e32 v86, v75
	v_sqrt_f32_e32 v94, v86
	v_add_f32_e32 v60, v60, v100
	v_add_f32_e32 v75, 1.0, v79
	v_add_u32_e32 v79, -1, v94
	v_mul_f32_e32 v60, 0xbfb8aa3b, v60
	v_fma_f32 v87, -v79, v94, v86
	v_exp_f32_e32 v60, v60
	v_cmp_ge_f32_e64 s[12:13], 0, v87
	v_add_u32_e32 v87, 1, v94
	v_rcp_f32_e32 v72, v72
	v_cndmask_b32_e64 v79, v94, v79, s[12:13]
	v_fma_f32 v94, -v87, v94, v86
	v_cmp_lt_f32_e64 s[12:13], 0, v94
	v_rcp_f32_e32 v73, v73
	v_rcp_f32_e32 v74, v74
	v_rcp_f32_e32 v75, v75
	v_cndmask_b32_e64 v79, v79, v87, s[12:13]
	v_add_f32_e32 v60, 1.0, v60
	v_rcp_f32_e32 v60, v60
	v_pk_mul_f32 v[72:73], v[72:73], v[76:77]
	v_lshlrev_b32_e32 v76, 16, v83
	v_and_b32_e32 v77, 0xffff0000, v83
	v_pk_mul_f32 v[74:75], v[74:75], v[78:79]
	v_add_f32_e32 v61, v61, v101
	v_pk_mul_f32 v[74:75], v[74:75], v[76:77]
	v_mul_f32_e32 v76, v60, v84
	v_add_f32_e32 v60, v76, v76
	v_mul_f32_e32 v60, 0x3fb8aa3b, v60
	v_exp_f32_e32 v60, v60
	v_mul_f32_e32 v61, 0xbfb8aa3b, v61
	v_exp_f32_e32 v61, v61
	v_lshl_add_u64 v[86:87], v[92:93], 0, v[180:181]
	v_sub_f32_e32 v60, 1.0, v60
	v_lshlrev_b64 v[86:87], 1, v[86:87]
	v_add_f32_e32 v64, v64, v96
	v_add_f32_e32 v61, 1.0, v61
	v_cvt_pk_bf16_f32 v88, v90, v88
	v_cvt_pk_bf16_f32 v89, v89, v91
	v_lshl_add_u64 v[90:91], s[70:71], 0, v[86:87]
	v_mul_f32_e32 v64, 0xbfb8aa3b, v64
	v_mov_b32_e32 v77, v60
	v_rcp_f32_e32 v61, v61
	v_mov_b32_e32 v124, v226
	v_mov_b32_e32 v125, v227
	v_mov_b32_e32 v126, v88
	v_mov_b32_e32 v127, v89
	global_store_dwordx4 v[90:91], v[124:127], off offset:-8
	v_lshlrev_b32_e32 v88, 16, v82
	v_and_b32_e32 v89, 0xffff0000, v82
	v_exp_f32_e32 v64, v64
	v_sqrt_f32_e32 v78, v77
	v_pk_mul_f32 v[72:73], v[72:73], v[88:89]
	v_add_f32_e32 v65, v65, v97
	v_cvt_pk_bf16_f32 v72, v72, v73
	v_cvt_pk_bf16_f32 v73, v74, v75
	v_lshl_add_u64 v[74:75], s[68:69], 0, v[86:87]
	v_mov_b32_e32 v128, v228
	v_mov_b32_e32 v129, v229
	v_mov_b32_e32 v130, v72
	v_mov_b32_e32 v131, v73
	global_store_dwordx4 v[74:75], v[128:131], off offset:-8
	v_mul_f32_e32 v74, v61, v85
	v_add_f32_e32 v60, 1.0, v64
	v_add_u32_e32 v64, -1, v78
	v_add_f32_e32 v61, v74, v74
	v_fma_f32 v72, -v64, v78, v77
	v_mul_f32_e32 v61, 0x3fb8aa3b, v61
	v_cmp_ge_f32_e64 s[12:13], 0, v72
	v_add_u32_e32 v72, 1, v78
	v_exp_f32_e32 v61, v61
	v_fma_f32 v73, -v72, v78, v77
	v_cndmask_b32_e64 v64, v78, v64, s[12:13]
	v_cmp_lt_f32_e64 s[12:13], 0, v73
	v_sub_f32_e32 v61, 1.0, v61
	v_add_f32_e32 v62, v62, v102
	v_cndmask_b32_e64 v64, v64, v72, s[12:13]
	v_mul_f32_e32 v65, 0xbfb8aa3b, v65
	v_mul_f32_e32 v62, 0xbfb8aa3b, v62
	v_mov_b32_e32 v72, v61
	v_exp_f32_e32 v65, v65
	v_sqrt_f32_e32 v73, v72
	v_exp_f32_e32 v62, v62
	v_add_f32_e32 v61, 1.0, v65
	v_add_u32_e32 v65, -1, v73
	v_add_f32_e32 v62, 1.0, v62
	v_fma_f32 v75, -v65, v73, v72
	v_rcp_f32_e32 v62, v62
	v_cmp_ge_f32_e64 s[12:13], 0, v75
	v_add_u32_e32 v75, 1, v73
	v_add_f32_e32 v63, v63, v103
	v_cndmask_b32_e64 v65, v73, v65, s[12:13]
	v_fma_f32 v73, -v75, v73, v72
	v_cmp_lt_f32_e64 s[12:13], 0, v73
	v_add_f32_e32 v66, v66, v98
	v_mul_f32_e32 v63, 0xbfb8aa3b, v63
	v_cndmask_b32_e64 v65, v65, v75, s[12:13]
	v_mul_f32_e32 v75, v62, v8
	v_add_f32_e32 v62, v75, v75
	v_mul_f32_e32 v62, 0x3fb8aa3b, v62
	v_exp_f32_e32 v62, v62
	v_mul_f32_e32 v66, 0xbfb8aa3b, v66
	v_sub_f32_e32 v62, 1.0, v62
	v_exp_f32_e32 v63, v63
	v_exp_f32_e32 v66, v66
	v_mov_b32_e32 v73, v62
	v_sqrt_f32_e32 v77, v73
	v_add_f32_e32 v63, 1.0, v63
	v_add_f32_e32 v62, 1.0, v66
	v_add_u32_e32 v66, -1, v77
	v_rcp_f32_e32 v63, v63
	v_fma_f32 v72, -v66, v77, v73
	v_cmp_ge_f32_e64 s[12:13], 0, v72
	v_add_u32_e32 v72, 1, v77
	v_add_f32_e32 v67, v67, v99
	v_cndmask_b32_e64 v66, v77, v66, s[12:13]
	v_fma_f32 v77, -v72, v77, v73
	v_cmp_lt_f32_e64 s[12:13], 0, v77
	v_mul_f32_e32 v77, v63, v9
	v_add_f32_e32 v63, v77, v77
	v_mul_f32_e32 v63, 0x3fb8aa3b, v63
	v_exp_f32_e32 v63, v63
	v_cndmask_b32_e64 v66, v66, v72, s[12:13]
	v_sub_f32_e32 v63, 1.0, v63
	v_mul_f32_e32 v67, 0xbfb8aa3b, v67
	v_exp_f32_e32 v67, v67
	v_mov_b32_e32 v72, v63
	v_sqrt_f32_e32 v78, v72
	v_add_f32_e32 v48, v48, v100
	v_add_f32_e32 v63, 1.0, v67
	v_add_u32_e32 v67, -1, v78
	v_mul_f32_e32 v48, 0xbfb8aa3b, v48
	v_fma_f32 v73, -v67, v78, v72
	v_exp_f32_e32 v48, v48
	v_cmp_ge_f32_e64 s[12:13], 0, v73
	v_add_u32_e32 v73, 1, v78
	v_rcp_f32_e32 v60, v60
	v_cndmask_b32_e64 v67, v78, v67, s[12:13]
	v_fma_f32 v78, -v73, v78, v72
	v_cmp_lt_f32_e64 s[12:13], 0, v78
	v_rcp_f32_e32 v61, v61
	v_rcp_f32_e32 v62, v62
	v_rcp_f32_e32 v63, v63
	v_cndmask_b32_e64 v67, v67, v73, s[12:13]
	v_add_f32_e32 v48, 1.0, v48
	v_rcp_f32_e32 v48, v48
	v_pk_mul_f32 v[60:61], v[60:61], v[64:65]
	v_lshlrev_b32_e32 v64, 16, v71
	v_and_b32_e32 v65, 0xffff0000, v71
	v_pk_mul_f32 v[62:63], v[62:63], v[66:67]
	v_add_f32_e32 v49, v49, v101
	v_pk_mul_f32 v[62:63], v[62:63], v[64:65]
	v_mul_f32_e32 v64, v48, v84
	v_add_f32_e32 v48, v64, v64
	v_mul_f32_e32 v48, 0x3fb8aa3b, v48
	v_exp_f32_e32 v48, v48
	v_mul_f32_e32 v49, 0xbfb8aa3b, v49
	v_exp_f32_e32 v49, v49
	v_lshl_add_u64 v[72:73], v[80:81], 0, v[180:181]
	v_sub_f32_e32 v48, 1.0, v48
	v_lshlrev_b64 v[72:73], 1, v[72:73]
	v_add_f32_e32 v52, v52, v96
	v_add_f32_e32 v49, 1.0, v49
	v_cvt_pk_bf16_f32 v74, v76, v74
; __device__ __forceinline__ float bflo(unsigned w) { return __uint_as_float(w << 16); }
; __device__ __forceinline__ float bfhi(unsigned w) { return __uint_as_float(w & 0xffff0000u); }
; __device__ __forceinline__ float sigmoidf_(float x) { return __builtin_amdgcn_rcpf(1.0f + __expf(-x)); }
;     __device__ __forceinline__ void operator()(AccRef acc, const Unit& u, int wr, int wc, int fr, int fq) const {
;     ...
;                 for (int m = 0; m < 4; ++m) { const size_t off = (size_t)(row0 + ai * 128 + m * 16) * D + col0 + 4 * n;
;                     float lo[4], bo[4];
; #pragma unroll
;                     for (int j = 0; j < 4; ++j) { const unsigned w = rws[ai][m][2 * n + (j >> 1)]; const float rec = (j & 1) ? bfhi(w) : bflo(w);
;                         const float r = sigmoidf_(acc[ai][0][m][n][j] + ba[j]), ig = sigmoidf_(acc[ai][1][m][n][j] + bx[j]);
;                         const float la = k8[j] * r; const float mult = __builtin_sqrtf(1.0f - __expf(2.0f * la));
;                         lo[j] = la; bo[j] = mult * ig * rec; }
;                     *(u32x2*)(LA + off) = (u32x2){cvt_pk_bf16(lo[0], lo[1]), cvt_pk_bf16(lo[2], lo[3])}; *(u32x2*)(BV + off) = (u32x2){cvt_pk_bf16(bo[0], bo[1]), cvt_pk_bf16(bo[2], bo[3])}; }
	v_cvt_pk_bf16_f32 v75, v75, v77
	v_lshl_add_u64 v[76:77], s[70:71], 0, v[72:73]
	v_mul_f32_e32 v52, 0xbfb8aa3b, v52
	v_mov_b32_e32 v65, v48
	v_rcp_f32_e32 v49, v49
	v_mov_b32_e32 v132, v230
	v_mov_b32_e32 v133, v231
	v_mov_b32_e32 v134, v74
	v_mov_b32_e32 v135, v75
	global_store_dwordx4 v[76:77], v[132:135], off offset:-8
	v_lshlrev_b32_e32 v74, 16, v70
	v_and_b32_e32 v75, 0xffff0000, v70
	v_exp_f32_e32 v52, v52
	v_sqrt_f32_e32 v66, v65
	v_pk_mul_f32 v[60:61], v[60:61], v[74:75]
	v_add_f32_e32 v53, v53, v97
	v_cvt_pk_bf16_f32 v60, v60, v61
	v_cvt_pk_bf16_f32 v61, v62, v63
	v_lshl_add_u64 v[62:63], s[68:69], 0, v[72:73]
	v_mov_b32_e32 v136, v232
	v_mov_b32_e32 v137, v233
	v_mov_b32_e32 v138, v60
	v_mov_b32_e32 v139, v61
	global_store_dwordx4 v[62:63], v[136:139], off offset:-8
	v_mul_f32_e32 v62, v49, v85
	v_add_f32_e32 v48, 1.0, v52
	v_add_u32_e32 v52, -1, v66
	v_add_f32_e32 v49, v62, v62
	v_fma_f32 v60, -v52, v66, v65
	v_mul_f32_e32 v49, 0x3fb8aa3b, v49
	v_cmp_ge_f32_e64 s[12:13], 0, v60
	v_add_u32_e32 v60, 1, v66
	v_exp_f32_e32 v49, v49
	v_fma_f32 v61, -v60, v66, v65
	v_cndmask_b32_e64 v52, v66, v52, s[12:13]
	v_cmp_lt_f32_e64 s[12:13], 0, v61
	v_sub_f32_e32 v49, 1.0, v49
	v_add_f32_e32 v50, v50, v102
	v_cndmask_b32_e64 v52, v52, v60, s[12:13]
	v_mul_f32_e32 v53, 0xbfb8aa3b, v53
	v_mul_f32_e32 v50, 0xbfb8aa3b, v50
	v_mov_b32_e32 v60, v49
	v_exp_f32_e32 v53, v53
	v_sqrt_f32_e32 v61, v60
	v_exp_f32_e32 v50, v50
	v_add_f32_e32 v49, 1.0, v53
	v_add_u32_e32 v53, -1, v61
	v_add_f32_e32 v50, 1.0, v50
	v_fma_f32 v63, -v53, v61, v60
	v_rcp_f32_e32 v50, v50
	v_cmp_ge_f32_e64 s[12:13], 0, v63
	v_add_u32_e32 v63, 1, v61
	v_add_f32_e32 v51, v51, v103
	v_cndmask_b32_e64 v53, v61, v53, s[12:13]
	v_fma_f32 v61, -v63, v61, v60
	v_cmp_lt_f32_e64 s[12:13], 0, v61
	v_add_f32_e32 v54, v54, v98
	v_mul_f32_e32 v51, 0xbfb8aa3b, v51
	v_cndmask_b32_e64 v53, v53, v63, s[12:13]
	v_mul_f32_e32 v63, v50, v8
	v_add_f32_e32 v50, v63, v63
	v_mul_f32_e32 v50, 0x3fb8aa3b, v50
	v_exp_f32_e32 v50, v50
	v_mul_f32_e32 v54, 0xbfb8aa3b, v54
	v_sub_f32_e32 v50, 1.0, v50
	v_exp_f32_e32 v51, v51
	v_exp_f32_e32 v54, v54
	v_mov_b32_e32 v61, v50
	v_sqrt_f32_e32 v65, v61
	v_add_f32_e32 v51, 1.0, v51
	v_add_f32_e32 v50, 1.0, v54
	v_add_u32_e32 v54, -1, v65
	v_rcp_f32_e32 v51, v51
	v_fma_f32 v60, -v54, v65, v61
	v_cmp_ge_f32_e64 s[12:13], 0, v60
	v_add_u32_e32 v60, 1, v65
	v_add_f32_e32 v55, v55, v99
	v_cndmask_b32_e64 v54, v65, v54, s[12:13]
	v_fma_f32 v65, -v60, v65, v61
	v_cmp_lt_f32_e64 s[12:13], 0, v65
	v_mul_f32_e32 v65, v51, v9
	v_add_f32_e32 v51, v65, v65
	v_mul_f32_e32 v51, 0x3fb8aa3b, v51
	v_exp_f32_e32 v51, v51
	v_cndmask_b32_e64 v54, v54, v60, s[12:13]
	v_sub_f32_e32 v51, 1.0, v51
	v_mul_f32_e32 v55, 0xbfb8aa3b, v55
	v_exp_f32_e32 v55, v55
	v_mov_b32_e32 v60, v51
	v_sqrt_f32_e32 v66, v60
	v_add_f32_e32 v36, v36, v100
	v_add_f32_e32 v51, 1.0, v55
	v_add_u32_e32 v55, -1, v66
	v_mul_f32_e32 v36, 0xbfb8aa3b, v36
	v_fma_f32 v61, -v55, v66, v60
	v_exp_f32_e32 v36, v36
	v_cmp_ge_f32_e64 s[12:13], 0, v61
	v_add_u32_e32 v61, 1, v66
	v_rcp_f32_e32 v48, v48
	v_cndmask_b32_e64 v55, v66, v55, s[12:13]
	v_fma_f32 v66, -v61, v66, v60
	v_cmp_lt_f32_e64 s[12:13], 0, v66
	v_rcp_f32_e32 v49, v49
	v_rcp_f32_e32 v50, v50
	v_rcp_f32_e32 v51, v51
	v_cndmask_b32_e64 v55, v55, v61, s[12:13]
	v_add_f32_e32 v36, 1.0, v36
	v_rcp_f32_e32 v36, v36
	v_pk_mul_f32 v[48:49], v[48:49], v[52:53]
	v_lshlrev_b32_e32 v52, 16, v59
	v_and_b32_e32 v53, 0xffff0000, v59
	v_pk_mul_f32 v[50:51], v[50:51], v[54:55]
	v_add_f32_e32 v37, v37, v101
	v_pk_mul_f32 v[50:51], v[50:51], v[52:53]
	v_mul_f32_e32 v52, v36, v84
	v_add_f32_e32 v36, v52, v52
	v_mul_f32_e32 v36, 0x3fb8aa3b, v36
	v_exp_f32_e32 v36, v36
	v_mul_f32_e32 v37, 0xbfb8aa3b, v37
	v_exp_f32_e32 v37, v37
	v_lshl_add_u64 v[60:61], v[68:69], 0, v[180:181]
	v_sub_f32_e32 v36, 1.0, v36
	v_lshlrev_b64 v[60:61], 1, v[60:61]
	v_add_f32_e32 v40, v40, v96
	v_add_f32_e32 v37, 1.0, v37
	v_cvt_pk_bf16_f32 v62, v64, v62
	v_cvt_pk_bf16_f32 v63, v63, v65
	v_lshl_add_u64 v[64:65], s[70:71], 0, v[60:61]
	v_mul_f32_e32 v40, 0xbfb8aa3b, v40
	v_mov_b32_e32 v53, v36
	v_rcp_f32_e32 v37, v37
	v_mov_b32_e32 v140, v235
	v_mov_b32_e32 v141, v236
	v_mov_b32_e32 v142, v62
	v_mov_b32_e32 v143, v63
	global_store_dwordx4 v[64:65], v[140:143], off offset:-8
	v_lshlrev_b32_e32 v62, 16, v58
	v_and_b32_e32 v63, 0xffff0000, v58
	v_exp_f32_e32 v40, v40
	v_sqrt_f32_e32 v54, v53
	v_pk_mul_f32 v[48:49], v[48:49], v[62:63]
	v_add_f32_e32 v41, v41, v97
	v_cvt_pk_bf16_f32 v48, v48, v49
	v_cvt_pk_bf16_f32 v49, v50, v51
	v_lshl_add_u64 v[50:51], s[68:69], 0, v[60:61]
	v_mov_b32_e32 v144, v237
	v_mov_b32_e32 v145, v238
	v_mov_b32_e32 v146, v48
	v_mov_b32_e32 v147, v49
	global_store_dwordx4 v[50:51], v[144:147], off offset:-8
	v_mul_f32_e32 v50, v37, v85
	v_add_f32_e32 v36, 1.0, v40
	v_add_u32_e32 v40, -1, v54
	v_add_f32_e32 v37, v50, v50
	v_fma_f32 v48, -v40, v54, v53
	v_mul_f32_e32 v37, 0x3fb8aa3b, v37
	v_cmp_ge_f32_e64 s[12:13], 0, v48
	v_add_u32_e32 v48, 1, v54
	v_exp_f32_e32 v37, v37
	v_fma_f32 v49, -v48, v54, v53
	v_cndmask_b32_e64 v40, v54, v40, s[12:13]
	v_cmp_lt_f32_e64 s[12:13], 0, v49
	v_sub_f32_e32 v37, 1.0, v37
	v_add_f32_e32 v38, v38, v102
	v_cndmask_b32_e64 v40, v40, v48, s[12:13]
	v_mul_f32_e32 v41, 0xbfb8aa3b, v41
	v_mul_f32_e32 v38, 0xbfb8aa3b, v38
	v_mov_b32_e32 v48, v37
	v_exp_f32_e32 v41, v41
	v_sqrt_f32_e32 v49, v48
	v_exp_f32_e32 v38, v38
	v_add_f32_e32 v37, 1.0, v41
	v_add_u32_e32 v41, -1, v49
	v_add_f32_e32 v38, 1.0, v38
	v_fma_f32 v51, -v41, v49, v48
	v_rcp_f32_e32 v38, v38
	v_cmp_ge_f32_e64 s[12:13], 0, v51
	v_add_u32_e32 v51, 1, v49
	v_add_f32_e32 v39, v39, v103
; __device__ __forceinline__ float bflo(unsigned w) { return __uint_as_float(w << 16); }
; __device__ __forceinline__ float bfhi(unsigned w) { return __uint_as_float(w & 0xffff0000u); }
; __device__ __forceinline__ float sigmoidf_(float x) { return __builtin_amdgcn_rcpf(1.0f + __expf(-x)); }
;     __device__ __forceinline__ void operator()(AccRef acc, const Unit& u, int wr, int wc, int fr, int fq) const {
;     ...
;                 for (int m = 0; m < 4; ++m) { const size_t off = (size_t)(row0 + ai * 128 + m * 16) * D + col0 + 4 * n;
;                     float lo[4], bo[4];
; #pragma unroll
;                     for (int j = 0; j < 4; ++j) { const unsigned w = rws[ai][m][2 * n + (j >> 1)]; const float rec = (j & 1) ? bfhi(w) : bflo(w);
;                         const float r = sigmoidf_(acc[ai][0][m][n][j] + ba[j]), ig = sigmoidf_(acc[ai][1][m][n][j] + bx[j]);
;                         const float la = k8[j] * r; const float mult = __builtin_sqrtf(1.0f - __expf(2.0f * la));
;                         lo[j] = la; bo[j] = mult * ig * rec; }
;                     *(u32x2*)(LA + off) = (u32x2){cvt_pk_bf16(lo[0], lo[1]), cvt_pk_bf16(lo[2], lo[3])}; *(u32x2*)(BV + off) = (u32x2){cvt_pk_bf16(bo[0], bo[1]), cvt_pk_bf16(bo[2], bo[3])}; }
	v_cndmask_b32_e64 v41, v49, v41, s[12:13]
	v_fma_f32 v49, -v51, v49, v48
	v_cmp_lt_f32_e64 s[12:13], 0, v49
	v_add_f32_e32 v42, v42, v98
	v_mul_f32_e32 v39, 0xbfb8aa3b, v39
	v_cndmask_b32_e64 v41, v41, v51, s[12:13]
	v_mul_f32_e32 v51, v38, v8
	v_add_f32_e32 v38, v51, v51
	v_mul_f32_e32 v38, 0x3fb8aa3b, v38
	v_exp_f32_e32 v38, v38
	v_mul_f32_e32 v42, 0xbfb8aa3b, v42
	v_sub_f32_e32 v38, 1.0, v38
	v_exp_f32_e32 v39, v39
	v_exp_f32_e32 v42, v42
	v_mov_b32_e32 v49, v38
	v_sqrt_f32_e32 v53, v49
	v_add_f32_e32 v39, 1.0, v39
	v_add_f32_e32 v38, 1.0, v42
	v_add_u32_e32 v42, -1, v53
	v_rcp_f32_e32 v39, v39
	v_fma_f32 v48, -v42, v53, v49
	v_cmp_ge_f32_e64 s[12:13], 0, v48
	v_add_u32_e32 v48, 1, v53
	v_add_f32_e32 v43, v43, v99
	v_cndmask_b32_e64 v42, v53, v42, s[12:13]
	v_fma_f32 v53, -v48, v53, v49
	v_cmp_lt_f32_e64 s[12:13], 0, v53
	v_mul_f32_e32 v53, v39, v9
	v_add_f32_e32 v39, v53, v53
	v_mul_f32_e32 v39, 0x3fb8aa3b, v39
	v_exp_f32_e32 v39, v39
	v_cndmask_b32_e64 v42, v42, v48, s[12:13]
	v_sub_f32_e32 v39, 1.0, v39
	v_mul_f32_e32 v43, 0xbfb8aa3b, v43
	v_exp_f32_e32 v43, v43
	v_mov_b32_e32 v48, v39
	v_sqrt_f32_e32 v54, v48
	v_add_f32_e32 v24, v24, v100
	v_add_f32_e32 v39, 1.0, v43
	v_add_u32_e32 v43, -1, v54
	v_mul_f32_e32 v24, 0xbfb8aa3b, v24
	v_fma_f32 v49, -v43, v54, v48
	v_exp_f32_e32 v24, v24
	v_cmp_ge_f32_e64 s[12:13], 0, v49
	v_add_u32_e32 v49, 1, v54
	v_rcp_f32_e32 v36, v36
	v_cndmask_b32_e64 v43, v54, v43, s[12:13]
	v_fma_f32 v54, -v49, v54, v48
	v_cmp_lt_f32_e64 s[12:13], 0, v54
	v_rcp_f32_e32 v37, v37
	v_rcp_f32_e32 v38, v38
	v_rcp_f32_e32 v39, v39
	v_cndmask_b32_e64 v43, v43, v49, s[12:13]
	v_add_f32_e32 v24, 1.0, v24
	v_rcp_f32_e32 v24, v24
	v_pk_mul_f32 v[36:37], v[36:37], v[40:41]
	v_lshlrev_b32_e32 v40, 16, v47
	v_and_b32_e32 v41, 0xffff0000, v47
	v_pk_mul_f32 v[38:39], v[38:39], v[42:43]
	v_add_f32_e32 v25, v25, v101
	v_pk_mul_f32 v[38:39], v[38:39], v[40:41]
	v_mul_f32_e32 v40, v24, v84
	v_add_f32_e32 v24, v40, v40
	v_mul_f32_e32 v24, 0x3fb8aa3b, v24
	v_exp_f32_e32 v24, v24
	v_mul_f32_e32 v25, 0xbfb8aa3b, v25
	v_exp_f32_e32 v25, v25
	v_lshl_add_u64 v[48:49], v[56:57], 0, v[180:181]
	v_sub_f32_e32 v24, 1.0, v24
	v_lshlrev_b64 v[48:49], 1, v[48:49]
	v_add_f32_e32 v28, v28, v96
	v_add_f32_e32 v25, 1.0, v25
	v_cvt_pk_bf16_f32 v50, v52, v50
	v_cvt_pk_bf16_f32 v51, v51, v53
	v_lshl_add_u64 v[52:53], s[70:71], 0, v[48:49]
	v_mul_f32_e32 v28, 0xbfb8aa3b, v28
	v_mov_b32_e32 v41, v24
	v_rcp_f32_e32 v25, v25
	v_mov_b32_e32 v148, v239
	v_mov_b32_e32 v149, v240
	v_mov_b32_e32 v150, v50
	v_mov_b32_e32 v151, v51
	global_store_dwordx4 v[52:53], v[148:151], off offset:-8
	v_lshlrev_b32_e32 v50, 16, v46
	v_and_b32_e32 v51, 0xffff0000, v46
	v_exp_f32_e32 v28, v28
	v_sqrt_f32_e32 v42, v41
	v_pk_mul_f32 v[36:37], v[36:37], v[50:51]
	v_add_f32_e32 v29, v29, v97
	v_cvt_pk_bf16_f32 v36, v36, v37
	v_cvt_pk_bf16_f32 v37, v38, v39
	v_lshl_add_u64 v[38:39], s[68:69], 0, v[48:49]
	v_mov_b32_e32 v152, v241
	v_mov_b32_e32 v153, v242
	v_mov_b32_e32 v154, v36
	v_mov_b32_e32 v155, v37
	global_store_dwordx4 v[38:39], v[152:155], off offset:-8
	v_mul_f32_e32 v38, v25, v85
	v_add_f32_e32 v24, 1.0, v28
	v_add_u32_e32 v28, -1, v42
	v_add_f32_e32 v25, v38, v38
	v_fma_f32 v36, -v28, v42, v41
	v_mul_f32_e32 v25, 0x3fb8aa3b, v25
	v_cmp_ge_f32_e64 s[12:13], 0, v36
	v_add_u32_e32 v36, 1, v42
	v_exp_f32_e32 v25, v25
	v_fma_f32 v37, -v36, v42, v41
	v_cndmask_b32_e64 v28, v42, v28, s[12:13]
	v_cmp_lt_f32_e64 s[12:13], 0, v37
	v_sub_f32_e32 v25, 1.0, v25
	v_add_f32_e32 v26, v26, v102
	v_cndmask_b32_e64 v28, v28, v36, s[12:13]
	v_mul_f32_e32 v29, 0xbfb8aa3b, v29
	v_mul_f32_e32 v26, 0xbfb8aa3b, v26
	v_mov_b32_e32 v36, v25
	v_exp_f32_e32 v29, v29
	v_sqrt_f32_e32 v37, v36
	v_exp_f32_e32 v26, v26
	v_add_f32_e32 v25, 1.0, v29
	v_add_u32_e32 v29, -1, v37
	v_add_f32_e32 v26, 1.0, v26
	v_fma_f32 v39, -v29, v37, v36
	v_rcp_f32_e32 v26, v26
	v_cmp_ge_f32_e64 s[12:13], 0, v39
	v_add_u32_e32 v39, 1, v37
	v_add_f32_e32 v27, v27, v103
	v_cndmask_b32_e64 v29, v37, v29, s[12:13]
	v_fma_f32 v37, -v39, v37, v36
	v_cmp_lt_f32_e64 s[12:13], 0, v37
	v_add_f32_e32 v30, v30, v98
	v_mul_f32_e32 v27, 0xbfb8aa3b, v27
	v_cndmask_b32_e64 v29, v29, v39, s[12:13]
	v_mul_f32_e32 v39, v26, v8
	v_add_f32_e32 v26, v39, v39
	v_mul_f32_e32 v26, 0x3fb8aa3b, v26
	v_exp_f32_e32 v26, v26
	v_mul_f32_e32 v30, 0xbfb8aa3b, v30
	v_sub_f32_e32 v26, 1.0, v26
	v_exp_f32_e32 v27, v27
	v_exp_f32_e32 v30, v30
	v_mov_b32_e32 v37, v26
	v_sqrt_f32_e32 v41, v37
	v_add_f32_e32 v27, 1.0, v27
	v_add_f32_e32 v26, 1.0, v30
	v_add_u32_e32 v30, -1, v41
	v_rcp_f32_e32 v27, v27
	v_fma_f32 v36, -v30, v41, v37
	v_cmp_ge_f32_e64 s[12:13], 0, v36
	v_add_u32_e32 v36, 1, v41
	v_add_f32_e32 v31, v31, v99
	v_cndmask_b32_e64 v30, v41, v30, s[12:13]
	v_fma_f32 v41, -v36, v41, v37
	v_cmp_lt_f32_e64 s[12:13], 0, v41
	v_mul_f32_e32 v41, v27, v9
	v_add_f32_e32 v27, v41, v41
	v_mul_f32_e32 v27, 0x3fb8aa3b, v27
	v_exp_f32_e32 v27, v27
	v_cndmask_b32_e64 v30, v30, v36, s[12:13]
	v_sub_f32_e32 v27, 1.0, v27
	v_mul_f32_e32 v31, 0xbfb8aa3b, v31
	v_exp_f32_e32 v31, v31
	v_mov_b32_e32 v36, v27
	v_sqrt_f32_e32 v42, v36
	v_add_f32_e32 v12, v12, v100
	v_add_f32_e32 v27, 1.0, v31
	v_add_u32_e32 v31, -1, v42
	v_mul_f32_e32 v12, 0xbfb8aa3b, v12
	v_fma_f32 v37, -v31, v42, v36
	v_exp_f32_e32 v12, v12
	v_cmp_ge_f32_e64 s[12:13], 0, v37
	v_add_u32_e32 v37, 1, v42
	v_rcp_f32_e32 v24, v24
	v_cndmask_b32_e64 v31, v42, v31, s[12:13]
	v_fma_f32 v42, -v37, v42, v36
	v_cmp_lt_f32_e64 s[12:13], 0, v42
	v_rcp_f32_e32 v25, v25
	v_rcp_f32_e32 v26, v26
	v_rcp_f32_e32 v27, v27
	v_cndmask_b32_e64 v31, v31, v37, s[12:13]
	v_add_f32_e32 v12, 1.0, v12
	v_rcp_f32_e32 v12, v12
; __device__ __forceinline__ float bflo(unsigned w) { return __uint_as_float(w << 16); }
; __device__ __forceinline__ float bfhi(unsigned w) { return __uint_as_float(w & 0xffff0000u); }
; __device__ __forceinline__ float sigmoidf_(float x) { return __builtin_amdgcn_rcpf(1.0f + __expf(-x)); }
;     __device__ __forceinline__ void operator()(AccRef acc, const Unit& u, int wr, int wc, int fr, int fq) const {
;     ...
;                 for (int m = 0; m < 4; ++m) { const size_t off = (size_t)(row0 + ai * 128 + m * 16) * D + col0 + 4 * n;
;                     float lo[4], bo[4];
; #pragma unroll
;                     for (int j = 0; j < 4; ++j) { const unsigned w = rws[ai][m][2 * n + (j >> 1)]; const float rec = (j & 1) ? bfhi(w) : bflo(w);
;                         const float r = sigmoidf_(acc[ai][0][m][n][j] + ba[j]), ig = sigmoidf_(acc[ai][1][m][n][j] + bx[j]);
;                         const float la = k8[j] * r; const float mult = __builtin_sqrtf(1.0f - __expf(2.0f * la));
;                         lo[j] = la; bo[j] = mult * ig * rec; }
;                     *(u32x2*)(LA + off) = (u32x2){cvt_pk_bf16(lo[0], lo[1]), cvt_pk_bf16(lo[2], lo[3])}; *(u32x2*)(BV + off) = (u32x2){cvt_pk_bf16(bo[0], bo[1]), cvt_pk_bf16(bo[2], bo[3])}; }
	v_pk_mul_f32 v[24:25], v[24:25], v[28:29]
	v_lshlrev_b32_e32 v28, 16, v35
	v_and_b32_e32 v29, 0xffff0000, v35
	v_pk_mul_f32 v[26:27], v[26:27], v[30:31]
	v_add_f32_e32 v13, v13, v101
	v_pk_mul_f32 v[26:27], v[26:27], v[28:29]
	v_mul_f32_e32 v28, v12, v84
	v_add_f32_e32 v12, v28, v28
	v_mul_f32_e32 v12, 0x3fb8aa3b, v12
	v_exp_f32_e32 v12, v12
	v_mul_f32_e32 v13, 0xbfb8aa3b, v13
	v_exp_f32_e32 v13, v13
	v_lshl_add_u64 v[36:37], v[44:45], 0, v[180:181]
	v_sub_f32_e32 v12, 1.0, v12
	v_lshlrev_b64 v[36:37], 1, v[36:37]
	v_add_f32_e32 v16, v16, v96
	v_add_f32_e32 v13, 1.0, v13
	v_cvt_pk_bf16_f32 v38, v40, v38
	v_cvt_pk_bf16_f32 v39, v39, v41
	v_lshl_add_u64 v[40:41], s[70:71], 0, v[36:37]
	v_mul_f32_e32 v16, 0xbfb8aa3b, v16
	v_mov_b32_e32 v29, v12
	v_rcp_f32_e32 v13, v13
	v_mov_b32_e32 v156, v243
	v_mov_b32_e32 v157, v244
	v_mov_b32_e32 v158, v38
	v_mov_b32_e32 v159, v39
	global_store_dwordx4 v[40:41], v[156:159], off offset:-8
	v_lshlrev_b32_e32 v38, 16, v34
	v_and_b32_e32 v39, 0xffff0000, v34
	v_exp_f32_e32 v16, v16
	v_sqrt_f32_e32 v30, v29
	v_pk_mul_f32 v[24:25], v[24:25], v[38:39]
	v_add_f32_e32 v17, v17, v97
	v_cvt_pk_bf16_f32 v24, v24, v25
	v_cvt_pk_bf16_f32 v25, v26, v27
	v_lshl_add_u64 v[26:27], s[68:69], 0, v[36:37]
	v_mov_b32_e32 v160, v245
	v_mov_b32_e32 v161, v246
	v_mov_b32_e32 v162, v24
	v_mov_b32_e32 v163, v25
	global_store_dwordx4 v[26:27], v[160:163], off offset:-8
	v_mul_f32_e32 v26, v13, v85
	v_add_f32_e32 v12, 1.0, v16
	v_add_u32_e32 v16, -1, v30
	v_add_f32_e32 v13, v26, v26
	v_fma_f32 v24, -v16, v30, v29
	v_mul_f32_e32 v13, 0x3fb8aa3b, v13
	v_cmp_ge_f32_e64 s[12:13], 0, v24
	v_add_u32_e32 v24, 1, v30
	v_exp_f32_e32 v13, v13
	v_fma_f32 v25, -v24, v30, v29
	v_cndmask_b32_e64 v16, v30, v16, s[12:13]
	v_cmp_lt_f32_e64 s[12:13], 0, v25
	v_sub_f32_e32 v13, 1.0, v13
	v_add_f32_e32 v14, v14, v102
	v_cndmask_b32_e64 v16, v16, v24, s[12:13]
	v_mul_f32_e32 v17, 0xbfb8aa3b, v17
	v_mul_f32_e32 v14, 0xbfb8aa3b, v14
	v_mov_b32_e32 v24, v13
	v_exp_f32_e32 v17, v17
	v_sqrt_f32_e32 v25, v24
	v_exp_f32_e32 v14, v14
	v_add_f32_e32 v13, 1.0, v17
	v_add_u32_e32 v17, -1, v25
	v_add_f32_e32 v14, 1.0, v14
	v_fma_f32 v27, -v17, v25, v24
	v_rcp_f32_e32 v14, v14
	v_cmp_ge_f32_e64 s[12:13], 0, v27
	v_add_u32_e32 v27, 1, v25
	v_add_f32_e32 v15, v15, v103
	v_cndmask_b32_e64 v17, v25, v17, s[12:13]
	v_fma_f32 v25, -v27, v25, v24
	v_cmp_lt_f32_e64 s[12:13], 0, v25
	v_add_f32_e32 v18, v18, v98
	v_mul_f32_e32 v15, 0xbfb8aa3b, v15
	v_cndmask_b32_e64 v17, v17, v27, s[12:13]
	v_mul_f32_e32 v27, v14, v8
	v_add_f32_e32 v14, v27, v27
	v_mul_f32_e32 v14, 0x3fb8aa3b, v14
	v_exp_f32_e32 v14, v14
	v_mul_f32_e32 v18, 0xbfb8aa3b, v18
	v_sub_f32_e32 v14, 1.0, v14
	v_exp_f32_e32 v15, v15
	v_exp_f32_e32 v18, v18
	v_mov_b32_e32 v25, v14
	v_sqrt_f32_e32 v29, v25
	v_add_f32_e32 v15, 1.0, v15
	v_add_f32_e32 v14, 1.0, v18
	v_add_u32_e32 v18, -1, v29
	v_rcp_f32_e32 v15, v15
	v_fma_f32 v24, -v18, v29, v25
	v_cmp_ge_f32_e64 s[12:13], 0, v24
	v_add_u32_e32 v24, 1, v29
	v_add_f32_e32 v19, v19, v99
	v_cndmask_b32_e64 v18, v29, v18, s[12:13]
	v_fma_f32 v29, -v24, v29, v25
	v_cmp_lt_f32_e64 s[12:13], 0, v29
	v_mul_f32_e32 v29, v15, v9
	v_add_f32_e32 v15, v29, v29
	v_mul_f32_e32 v15, 0x3fb8aa3b, v15
	v_exp_f32_e32 v15, v15
	v_cndmask_b32_e64 v18, v18, v24, s[12:13]
	v_sub_f32_e32 v15, 1.0, v15
	v_mul_f32_e32 v19, 0xbfb8aa3b, v19
	v_exp_f32_e32 v19, v19
	v_mov_b32_e32 v24, v15
	v_sqrt_f32_e32 v30, v24
	v_add_f32_e32 v0, v0, v100
	v_add_f32_e32 v15, 1.0, v19
	v_add_u32_e32 v19, -1, v30
	v_mul_f32_e32 v0, 0xbfb8aa3b, v0
	v_fma_f32 v25, -v19, v30, v24
	v_exp_f32_e32 v0, v0
	v_cmp_ge_f32_e64 s[12:13], 0, v25
	v_add_u32_e32 v25, 1, v30
	v_rcp_f32_e32 v12, v12
	v_cndmask_b32_e64 v19, v30, v19, s[12:13]
	v_fma_f32 v30, -v25, v30, v24
	v_cmp_lt_f32_e64 s[12:13], 0, v30
	v_rcp_f32_e32 v13, v13
	v_rcp_f32_e32 v14, v14
	v_rcp_f32_e32 v15, v15
	v_cndmask_b32_e64 v19, v19, v25, s[12:13]
	v_add_f32_e32 v0, 1.0, v0
	v_rcp_f32_e32 v0, v0
	v_pk_mul_f32 v[12:13], v[12:13], v[16:17]
	v_lshlrev_b32_e32 v16, 16, v23
	v_and_b32_e32 v17, 0xffff0000, v23
	v_pk_mul_f32 v[14:15], v[14:15], v[18:19]
	v_add_f32_e32 v4, v4, v96
	v_pk_mul_f32 v[14:15], v[14:15], v[16:17]
	v_mul_f32_e32 v16, v0, v84
	v_add_f32_e32 v0, v16, v16
	v_mul_f32_e32 v0, 0x3fb8aa3b, v0
	v_exp_f32_e32 v0, v0
	v_lshl_add_u64 v[24:25], v[32:33], 0, v[180:181]
; __device__ __forceinline__ float bflo(unsigned w) { return __uint_as_float(w << 16); }
; __device__ __forceinline__ float bfhi(unsigned w) { return __uint_as_float(w & 0xffff0000u); }
; __device__ __forceinline__ float sigmoidf_(float x) { return __builtin_amdgcn_rcpf(1.0f + __expf(-x)); }
;     __device__ __forceinline__ void operator()(AccRef acc, const Unit& u, int wr, int wc, int fr, int fq) const {
;     ...
;                 for (int m = 0; m < 4; ++m) { const size_t off = (size_t)(row0 + ai * 128 + m * 16) * D + col0 + 4 * n;
;                     float lo[4], bo[4];
; #pragma unroll
;                     for (int j = 0; j < 4; ++j) { const unsigned w = rws[ai][m][2 * n + (j >> 1)]; const float rec = (j & 1) ? bfhi(w) : bflo(w);
;                         const float r = sigmoidf_(acc[ai][0][m][n][j] + ba[j]), ig = sigmoidf_(acc[ai][1][m][n][j] + bx[j]);
;                         const float la = k8[j] * r; const float mult = __builtin_sqrtf(1.0f - __expf(2.0f * la));
;                         lo[j] = la; bo[j] = mult * ig * rec; }
;                     *(u32x2*)(LA + off) = (u32x2){cvt_pk_bf16(lo[0], lo[1]), cvt_pk_bf16(lo[2], lo[3])}; *(u32x2*)(BV + off) = (u32x2){cvt_pk_bf16(bo[0], bo[1]), cvt_pk_bf16(bo[2], bo[3])}; }
	v_mul_f32_e32 v4, 0xbfb8aa3b, v4
	v_lshlrev_b64 v[24:25], 1, v[24:25]
	v_sub_f32_e32 v0, 1.0, v0
	v_exp_f32_e32 v4, v4
	v_add_f32_e32 v1, v1, v101
	v_mov_b32_e32 v17, v0
	v_sqrt_f32_e32 v18, v17
	v_cvt_pk_bf16_f32 v26, v28, v26
	v_cvt_pk_bf16_f32 v27, v27, v29
	v_lshl_add_u64 v[28:29], s[70:71], 0, v[24:25]
	v_mul_f32_e32 v1, 0xbfb8aa3b, v1
	v_mov_b32_e32 v164, v247
	v_mov_b32_e32 v165, v248
	v_mov_b32_e32 v166, v26
	v_mov_b32_e32 v167, v27
	global_store_dwordx4 v[28:29], v[164:167], off offset:-8
	v_lshlrev_b32_e32 v26, 16, v22
	v_and_b32_e32 v27, 0xffff0000, v22
	v_exp_f32_e32 v1, v1
	v_pk_mul_f32 v[12:13], v[12:13], v[26:27]
	v_add_f32_e32 v0, 1.0, v4
	v_cvt_pk_bf16_f32 v12, v12, v13
	v_cvt_pk_bf16_f32 v13, v14, v15
	v_lshl_add_u64 v[14:15], s[68:69], 0, v[24:25]
	v_add_u32_e32 v4, -1, v18
	v_mov_b32_e32 v190, v249
	v_mov_b32_e32 v191, v250
	v_mov_b32_e32 v192, v12
	v_mov_b32_e32 v193, v13
	global_store_dwordx4 v[14:15], v[190:193], off offset:-8
	v_fma_f32 v12, -v4, v18, v17
	v_cmp_ge_f32_e64 s[12:13], 0, v12
	v_add_u32_e32 v12, 1, v18
	v_add_f32_e32 v1, 1.0, v1
	v_fma_f32 v13, -v12, v18, v17
	v_rcp_f32_e32 v1, v1
	v_cndmask_b32_e64 v4, v18, v4, s[12:13]
	v_cmp_lt_f32_e64 s[12:13], 0, v13
	v_add_f32_e32 v5, v5, v97
	v_mul_f32_e32 v5, 0xbfb8aa3b, v5
	v_cndmask_b32_e64 v4, v4, v12, s[12:13]
	v_mul_f32_e32 v12, v1, v85
	v_add_f32_e32 v1, v12, v12
	v_mul_f32_e32 v1, 0x3fb8aa3b, v1
	v_exp_f32_e32 v1, v1
	v_exp_f32_e32 v5, v5
	v_add_f32_e32 v2, v2, v102
	v_mul_f32_e32 v2, 0xbfb8aa3b, v2
	v_sub_f32_e32 v1, 1.0, v1
	v_exp_f32_e32 v2, v2
	v_mov_b32_e32 v13, v1
	v_sqrt_f32_e32 v14, v13
	v_add_f32_e32 v1, 1.0, v5
	v_add_f32_e32 v2, 1.0, v2
	v_add_u32_e32 v5, -1, v14
	v_fma_f32 v15, -v5, v14, v13
	v_cmp_ge_f32_e64 s[12:13], 0, v15
	v_add_u32_e32 v15, 1, v14
	v_rcp_f32_e32 v2, v2
	v_cndmask_b32_e64 v5, v14, v5, s[12:13]
	v_fma_f32 v14, -v15, v14, v13
	v_cmp_lt_f32_e64 s[12:13], 0, v14
	v_add_f32_e32 v6, v6, v98
	v_mul_f32_e32 v6, 0xbfb8aa3b, v6
	v_cndmask_b32_e64 v5, v5, v15, s[12:13]
	v_mul_f32_e32 v14, v2, v8
	v_add_f32_e32 v2, v14, v14
	v_mul_f32_e32 v2, 0x3fb8aa3b, v2
	v_exp_f32_e32 v2, v2
	v_exp_f32_e32 v6, v6
	v_add_f32_e32 v3, v3, v103
	v_mul_f32_e32 v3, 0xbfb8aa3b, v3
	v_sub_f32_e32 v2, 1.0, v2
	v_exp_f32_e32 v3, v3
	v_mov_b32_e32 v8, v2
	v_sqrt_f32_e32 v15, v8
	v_add_f32_e32 v2, 1.0, v6
	v_add_f32_e32 v3, 1.0, v3
	v_add_u32_e32 v6, -1, v15
	v_fma_f32 v13, -v6, v15, v8
	v_cmp_ge_f32_e64 s[12:13], 0, v13
	v_add_u32_e32 v13, 1, v15
	v_rcp_f32_e32 v3, v3
	v_cndmask_b32_e64 v6, v15, v6, s[12:13]
	v_fma_f32 v15, -v13, v15, v8
	v_cmp_lt_f32_e64 s[12:13], 0, v15
	v_add_f32_e32 v7, v7, v99
	v_mul_f32_e32 v7, 0xbfb8aa3b, v7
	v_cndmask_b32_e64 v6, v6, v13, s[12:13]
	v_mul_f32_e32 v13, v3, v9
	v_add_f32_e32 v3, v13, v13
	v_mul_f32_e32 v3, 0x3fb8aa3b, v3
	v_exp_f32_e32 v3, v3
	v_exp_f32_e32 v7, v7
	v_rcp_f32_e32 v0, v0
	v_sub_f32_e32 v3, 1.0, v3
	v_rcp_f32_e32 v1, v1
	v_mov_b32_e32 v9, v3
	v_sqrt_f32_e32 v15, v9
	v_add_f32_e32 v3, 1.0, v7
	v_rcp_f32_e32 v2, v2
	v_rcp_f32_e32 v3, v3
	v_add_u32_e32 v7, -1, v15
	v_fma_f32 v8, -v7, v15, v9
	v_cmp_ge_f32_e64 s[12:13], 0, v8
	v_add_u32_e32 v8, 1, v15
	v_cvt_pk_bf16_f32 v12, v16, v12
	v_cndmask_b32_e64 v7, v15, v7, s[12:13]
	v_fma_f32 v15, -v8, v15, v9
	v_cmp_lt_f32_e64 s[12:13], 0, v15
	v_cvt_pk_bf16_f32 v13, v14, v13
	v_pk_mul_f32 v[0:1], v[0:1], v[4:5]
	v_cndmask_b32_e64 v7, v7, v8, s[12:13]
	v_lshlrev_b32_e32 v4, 16, v11
	v_and_b32_e32 v5, 0xffff0000, v11
	v_lshl_add_u64 v[8:9], v[20:21], 0, v[180:181]
	v_lshlrev_b64 v[8:9], 1, v[8:9]
	v_lshl_add_u64 v[14:15], s[70:71], 0, v[8:9]
	v_mov_b32_e32 v194, v251
	v_mov_b32_e32 v195, v253
	v_mov_b32_e32 v196, v12
	v_mov_b32_e32 v197, v13
	global_store_dwordx4 v[14:15], v[194:197], off offset:-8
	v_lshlrev_b32_e32 v12, 16, v10
	v_and_b32_e32 v13, 0xffff0000, v10
	v_pk_mul_f32 v[2:3], v[2:3], v[6:7]
	v_pk_mul_f32 v[0:1], v[0:1], v[12:13]
	v_pk_mul_f32 v[2:3], v[2:3], v[4:5]
	v_cvt_pk_bf16_f32 v0, v0, v1
	v_cvt_pk_bf16_f32 v1, v2, v3
	v_lshl_add_u64 v[2:3], s[68:69], 0, v[8:9]
	s_andn2_b64 vcc, exec, s[10:11]
	s_mov_b32 s13, s38
	s_mov_b32 s12, s40
	s_mov_b64 s[14:15], s[42:43]
	v_mov_b32_e32 v198, v254
	v_mov_b32_e32 v199, v255
	v_mov_b32_e32 v200, v0
	v_mov_b32_e32 v201, v1
	global_store_dwordx4 v[2:3], v[198:201], off offset:-8
	s_cbranch_vccz .LBB0_1100
